# pipelined gla scan loads, gla_decay LDS prefetch in gla_step3, hoisted serialized loads in EpiXF and mem_attn epilogues
# speedup vs baseline: 1.0118x; 1.0118x over previous
; #define LAS __attribute__((address_space(3)))
; #define MFMA16(a, b, c) __builtin_amdgcn_mfma_f32_16x16x32_bf16((a), (b), (c), 0, 0, 0)
; __device__ __forceinline__ void mem_attn(const Params& P, int l, LAS unsigned char* lds, int item, int tid) {
;     ...
;         const int q0 = (qblk2 + trip) * 256 + w * 32; const size_t tt0 = (size_t)(b * SEQ + q0 + i), tt1 = tt0 + 16;
;         bf16x8 qf0[4], qf1[4];
; #pragma unroll
;         for (int ks = 0; ks < 4; ++ks) { qf0[ks] = *(const bf16x8*)(z + tt0 * ZP + ZC_MQ + h * 128 + ks * 32 + quad * 8); qf1[ks] = *(const bf16x8*)(z + tt1 * ZP + ZC_MQ + h * 128 + ks * 32 + quad * 8); }
;         f32x4 sa[16], sb[16];
; #pragma unroll
;         for (int kt = 0; kt < 16; ++kt) { sa[kt] = (f32x4){0.f, 0.f, 0.f, 0.f}; sb[kt] = (f32x4){0.f, 0.f, 0.f, 0.f};
; #pragma unroll
;             for (int ks = 0; ks < 4; ++ks) { const bf16x8 ka = *(const LAS bf16x8*)(KS + (kt * 16 + i) * 272 + (ks * 32 + quad * 8) * 2); sa[kt] = MFMA16(ka, qf0[ks], sa[kt]); sb[kt] = MFMA16(ka, qf1[ks], sb[kt]); }
;             if (kt & 1) __builtin_amdgcn_sched_barrier(0); }
.LBB0_415:
	v_add_u32_e32 v174, s7, v191
	v_mov_b64_e32 v[2:3], s[92:93]
	v_mad_i64_i32 v[2:3], s[8:9], v174, s80, v[2:3]
	v_lshl_add_u64 v[176:177], v[2:3], 0, s[76:77]
	v_lshl_add_u64 v[2:3], v[176:177], 0, v[0:1]
	v_add_co_u32_e32 v8, vcc, 0x2000, v2
	s_mov_b64 s[8:9], 0x2800
	s_nop 0
	v_addc_co_u32_e32 v9, vcc, 0, v3, vcc
	global_load_dwordx4 v[164:167], v[8:9], off offset:2048
	v_lshl_add_u64 v[4:5], v[2:3], 0, s[8:9]
	s_mov_b64 s[8:9], 0x62800
	v_lshl_add_u64 v[6:7], v[2:3], 0, s[8:9]
	v_add_co_u32_e32 v2, vcc, 0x62000, v2
	v_ashrrev_i32_e32 v175, 31, v174
	s_nop 0
	v_addc_co_u32_e32 v3, vcc, 0, v3, vcc
	global_load_dwordx4 v[168:171], v[2:3], off offset:2048
	global_load_dwordx4 v[156:159], v[4:5], off offset:64
	global_load_dwordx4 v[160:163], v[6:7], off offset:64
	global_load_dwordx4 v[78:81], v[4:5], off offset:128
	global_load_dwordx4 v[152:155], v[6:7], off offset:128
	global_load_dwordx4 v[74:77], v[4:5], off offset:192
	global_load_dwordx4 v[148:151], v[6:7], off offset:192
	ds_read_b128 v[2:5], v181
	ds_read_b128 v[10:13], v181 offset:64
	s_waitcnt vmcnt(7) lgkmcnt(1)
	v_mfma_f32_16x16x32_bf16 v[6:9], v[2:5], v[164:167], 0
	ds_read_b128 v[18:21], v181 offset:4416
	s_waitcnt vmcnt(6)
	v_mfma_f32_16x16x32_bf16 v[2:5], v[2:5], v[168:171], 0
	s_waitcnt vmcnt(5) lgkmcnt(1)
	v_mfma_f32_16x16x32_bf16 v[6:9], v[10:13], v[156:159], v[6:9]
	s_waitcnt vmcnt(4)
	v_mfma_f32_16x16x32_bf16 v[2:5], v[10:13], v[160:163], v[2:5]
	ds_read_b128 v[10:13], v181 offset:128
	s_waitcnt vmcnt(3) lgkmcnt(0)
	v_mfma_f32_16x16x32_bf16 v[6:9], v[10:13], v[78:81], v[6:9]
	s_waitcnt vmcnt(2)
	v_mfma_f32_16x16x32_bf16 v[2:5], v[10:13], v[152:155], v[2:5]
	ds_read_b128 v[10:13], v181 offset:192
	s_waitcnt vmcnt(1) lgkmcnt(0)
	v_mfma_f32_16x16x32_bf16 v[6:9], v[10:13], v[74:77], v[6:9]
	s_waitcnt vmcnt(0)
	v_mfma_f32_16x16x32_bf16 v[2:5], v[10:13], v[148:151], v[2:5]
	ds_read_b128 v[10:13], v181 offset:4352
	s_waitcnt lgkmcnt(0)
	v_mfma_f32_16x16x32_bf16 v[14:17], v[10:13], v[164:167], 0
	v_mfma_f32_16x16x32_bf16 v[10:13], v[10:13], v[168:171], 0
	v_mfma_f32_16x16x32_bf16 v[14:17], v[18:21], v[156:159], v[14:17]
	v_mfma_f32_16x16x32_bf16 v[10:13], v[18:21], v[160:163], v[10:13]
	ds_read_b128 v[18:21], v181 offset:4480
	s_waitcnt lgkmcnt(0)
	v_mfma_f32_16x16x32_bf16 v[14:17], v[18:21], v[78:81], v[14:17]
	v_mfma_f32_16x16x32_bf16 v[10:13], v[18:21], v[152:155], v[10:13]
	ds_read_b128 v[18:21], v181 offset:4544
	s_waitcnt lgkmcnt(0)
	v_mfma_f32_16x16x32_bf16 v[58:61], v[18:21], v[74:77], v[14:17]
	v_mfma_f32_16x16x32_bf16 v[62:65], v[18:21], v[148:151], v[10:13]
	s_nop 3
	ds_read_b128 v[10:13], v181 offset:8704
	ds_read_b128 v[18:21], v181 offset:8768
	s_waitcnt lgkmcnt(1)
	v_mfma_f32_16x16x32_bf16 v[14:17], v[10:13], v[164:167], 0
	v_mfma_f32_16x16x32_bf16 v[10:13], v[10:13], v[168:171], 0
	s_waitcnt lgkmcnt(0)
	v_mfma_f32_16x16x32_bf16 v[14:17], v[18:21], v[156:159], v[14:17]
	v_mfma_f32_16x16x32_bf16 v[10:13], v[18:21], v[160:163], v[10:13]
	ds_read_b128 v[18:21], v181 offset:8832
	s_waitcnt lgkmcnt(0)
	v_mfma_f32_16x16x32_bf16 v[14:17], v[18:21], v[78:81], v[14:17]
	v_mfma_f32_16x16x32_bf16 v[10:13], v[18:21], v[152:155], v[10:13]
	ds_read_b128 v[18:21], v181 offset:8896
	s_waitcnt lgkmcnt(0)
	v_mfma_f32_16x16x32_bf16 v[50:53], v[18:21], v[148:151], v[10:13]
	s_nop 4
	ds_read_b128 v[10:13], v181 offset:13056
	v_mfma_f32_16x16x32_bf16 v[54:57], v[18:21], v[74:77], v[14:17]
	ds_read_b128 v[18:21], v181 offset:13120
	s_waitcnt lgkmcnt(1)
	v_mfma_f32_16x16x32_bf16 v[14:17], v[10:13], v[164:167], 0
	v_mfma_f32_16x16x32_bf16 v[10:13], v[10:13], v[168:171], 0
	s_waitcnt lgkmcnt(0)
	v_mfma_f32_16x16x32_bf16 v[14:17], v[18:21], v[156:159], v[14:17]
	v_mfma_f32_16x16x32_bf16 v[10:13], v[18:21], v[160:163], v[10:13]
	ds_read_b128 v[18:21], v181 offset:13184
	s_waitcnt lgkmcnt(0)
	v_mfma_f32_16x16x32_bf16 v[14:17], v[18:21], v[78:81], v[14:17]
	v_mfma_f32_16x16x32_bf16 v[10:13], v[18:21], v[152:155], v[10:13]
	ds_read_b128 v[18:21], v181 offset:13248
	s_waitcnt lgkmcnt(0)
	v_mfma_f32_16x16x32_bf16 v[144:147], v[18:21], v[74:77], v[14:17]
	v_mfma_f32_16x16x32_bf16 v[122:125], v[18:21], v[148:151], v[10:13]
	s_nop 3
	ds_read_b128 v[10:13], v181 offset:17408
	ds_read_b128 v[18:21], v181 offset:17472
	s_waitcnt lgkmcnt(1)
	v_mfma_f32_16x16x32_bf16 v[14:17], v[10:13], v[164:167], 0
	v_mfma_f32_16x16x32_bf16 v[10:13], v[10:13], v[168:171], 0
	s_waitcnt lgkmcnt(0)
	v_mfma_f32_16x16x32_bf16 v[14:17], v[18:21], v[156:159], v[14:17]
	v_mfma_f32_16x16x32_bf16 v[10:13], v[18:21], v[160:163], v[10:13]
	ds_read_b128 v[18:21], v181 offset:17536
	s_waitcnt lgkmcnt(0)
	v_mfma_f32_16x16x32_bf16 v[14:17], v[18:21], v[78:81], v[14:17]
	v_mfma_f32_16x16x32_bf16 v[10:13], v[18:21], v[152:155], v[10:13]
	ds_read_b128 v[18:21], v181 offset:17600
	s_waitcnt lgkmcnt(0)
	v_mfma_f32_16x16x32_bf16 v[42:45], v[18:21], v[148:151], v[10:13]
	s_nop 4
	ds_read_b128 v[10:13], v181 offset:21760
	v_mfma_f32_16x16x32_bf16 v[46:49], v[18:21], v[74:77], v[14:17]
	ds_read_b128 v[18:21], v181 offset:21824
	s_waitcnt lgkmcnt(1)
	v_mfma_f32_16x16x32_bf16 v[14:17], v[10:13], v[164:167], 0
	v_mfma_f32_16x16x32_bf16 v[10:13], v[10:13], v[168:171], 0
	s_waitcnt lgkmcnt(0)
	v_mfma_f32_16x16x32_bf16 v[14:17], v[18:21], v[156:159], v[14:17]
	v_mfma_f32_16x16x32_bf16 v[10:13], v[18:21], v[160:163], v[10:13]
	ds_read_b128 v[18:21], v181 offset:21888
	s_waitcnt lgkmcnt(0)
	v_mfma_f32_16x16x32_bf16 v[14:17], v[18:21], v[78:81], v[14:17]
	v_mfma_f32_16x16x32_bf16 v[10:13], v[18:21], v[152:155], v[10:13]
	ds_read_b128 v[18:21], v181 offset:21952
	s_waitcnt lgkmcnt(0)
; #define LAS __attribute__((address_space(3)))
; #define MFMA16(a, b, c) __builtin_amdgcn_mfma_f32_16x16x32_bf16((a), (b), (c), 0, 0, 0)
; __device__ __forceinline__ void mem_attn(const Params& P, int l, LAS unsigned char* lds, int item, int tid) {
;     ...
;         for (int kt = 0; kt < 16; ++kt) { sa[kt] = (f32x4){0.f, 0.f, 0.f, 0.f}; sb[kt] = (f32x4){0.f, 0.f, 0.f, 0.f};
; #pragma unroll
;             for (int ks = 0; ks < 4; ++ks) { const bf16x8 ka = *(const LAS bf16x8*)(KS + (kt * 16 + i) * 272 + (ks * 32 + quad * 8) * 2); sa[kt] = MFMA16(ka, qf0[ks], sa[kt]); sb[kt] = MFMA16(ka, qf1[ks], sb[kt]); }
;             if (kt & 1) __builtin_amdgcn_sched_barrier(0); }
	v_mfma_f32_16x16x32_bf16 v[118:121], v[18:21], v[74:77], v[14:17]
	v_mfma_f32_16x16x32_bf16 v[114:117], v[18:21], v[148:151], v[10:13]
	s_nop 3
	ds_read_b128 v[10:13], v181 offset:26112
	ds_read_b128 v[18:21], v181 offset:26176
	s_waitcnt lgkmcnt(1)
	v_mfma_f32_16x16x32_bf16 v[14:17], v[10:13], v[164:167], 0
	v_mfma_f32_16x16x32_bf16 v[10:13], v[10:13], v[168:171], 0
	s_waitcnt lgkmcnt(0)
	v_mfma_f32_16x16x32_bf16 v[14:17], v[18:21], v[156:159], v[14:17]
	v_mfma_f32_16x16x32_bf16 v[10:13], v[18:21], v[160:163], v[10:13]
	ds_read_b128 v[18:21], v181 offset:26240
	s_waitcnt lgkmcnt(0)
	v_mfma_f32_16x16x32_bf16 v[14:17], v[18:21], v[78:81], v[14:17]
	v_mfma_f32_16x16x32_bf16 v[10:13], v[18:21], v[152:155], v[10:13]
	ds_read_b128 v[18:21], v181 offset:26304
	s_waitcnt lgkmcnt(0)
	v_mfma_f32_16x16x32_bf16 v[34:37], v[18:21], v[148:151], v[10:13]
	s_nop 4
	ds_read_b128 v[10:13], v181 offset:30464
	v_mfma_f32_16x16x32_bf16 v[38:41], v[18:21], v[74:77], v[14:17]
	ds_read_b128 v[18:21], v181 offset:30528
	s_waitcnt lgkmcnt(1)
	v_mfma_f32_16x16x32_bf16 v[14:17], v[10:13], v[164:167], 0
	v_mfma_f32_16x16x32_bf16 v[10:13], v[10:13], v[168:171], 0
	s_waitcnt lgkmcnt(0)
	v_mfma_f32_16x16x32_bf16 v[14:17], v[18:21], v[156:159], v[14:17]
	v_mfma_f32_16x16x32_bf16 v[10:13], v[18:21], v[160:163], v[10:13]
	ds_read_b128 v[18:21], v181 offset:30592
	s_waitcnt lgkmcnt(0)
	v_mfma_f32_16x16x32_bf16 v[14:17], v[18:21], v[78:81], v[14:17]
	v_mfma_f32_16x16x32_bf16 v[10:13], v[18:21], v[152:155], v[10:13]
	ds_read_b128 v[18:21], v181 offset:30656
	s_waitcnt lgkmcnt(0)
	v_mfma_f32_16x16x32_bf16 v[110:113], v[18:21], v[74:77], v[14:17]
	v_mfma_f32_16x16x32_bf16 v[106:109], v[18:21], v[148:151], v[10:13]
	s_nop 3
	ds_read_b128 v[10:13], v181 offset:34816
	ds_read_b128 v[18:21], v181 offset:34880
	s_waitcnt lgkmcnt(1)
	v_mfma_f32_16x16x32_bf16 v[14:17], v[10:13], v[164:167], 0
	v_mfma_f32_16x16x32_bf16 v[10:13], v[10:13], v[168:171], 0
	s_waitcnt lgkmcnt(0)
	v_mfma_f32_16x16x32_bf16 v[14:17], v[18:21], v[156:159], v[14:17]
	v_mfma_f32_16x16x32_bf16 v[10:13], v[18:21], v[160:163], v[10:13]
	ds_read_b128 v[18:21], v181 offset:34944
	s_waitcnt lgkmcnt(0)
	v_mfma_f32_16x16x32_bf16 v[14:17], v[18:21], v[78:81], v[14:17]
	v_mfma_f32_16x16x32_bf16 v[10:13], v[18:21], v[152:155], v[10:13]
	ds_read_b128 v[18:21], v181 offset:35008
	s_waitcnt lgkmcnt(0)
	v_mfma_f32_16x16x32_bf16 v[26:29], v[18:21], v[148:151], v[10:13]
	s_nop 4
	ds_read_b128 v[10:13], v181 offset:39168
	v_mfma_f32_16x16x32_bf16 v[30:33], v[18:21], v[74:77], v[14:17]
	ds_read_b128 v[18:21], v181 offset:39232
	s_waitcnt lgkmcnt(1)
	v_mfma_f32_16x16x32_bf16 v[14:17], v[10:13], v[164:167], 0
	v_mfma_f32_16x16x32_bf16 v[10:13], v[10:13], v[168:171], 0
	s_waitcnt lgkmcnt(0)
	v_mfma_f32_16x16x32_bf16 v[14:17], v[18:21], v[156:159], v[14:17]
	v_mfma_f32_16x16x32_bf16 v[10:13], v[18:21], v[160:163], v[10:13]
	ds_read_b128 v[18:21], v181 offset:39296
	s_waitcnt lgkmcnt(0)
	v_mfma_f32_16x16x32_bf16 v[14:17], v[18:21], v[78:81], v[14:17]
	v_mfma_f32_16x16x32_bf16 v[10:13], v[18:21], v[152:155], v[10:13]
	ds_read_b128 v[18:21], v181 offset:39360
	s_waitcnt lgkmcnt(0)
	v_mfma_f32_16x16x32_bf16 v[102:105], v[18:21], v[74:77], v[14:17]
	v_mfma_f32_16x16x32_bf16 v[98:101], v[18:21], v[148:151], v[10:13]
	s_nop 3
	ds_read_b128 v[10:13], v181 offset:43520
	ds_read_b128 v[18:21], v181 offset:43584
	s_waitcnt lgkmcnt(1)
	v_mfma_f32_16x16x32_bf16 v[14:17], v[10:13], v[164:167], 0
	ds_read_b128 v[66:69], v181 offset:47936
	v_mfma_f32_16x16x32_bf16 v[10:13], v[10:13], v[168:171], 0
	s_waitcnt lgkmcnt(1)
	v_mfma_f32_16x16x32_bf16 v[14:17], v[18:21], v[156:159], v[14:17]
	v_mfma_f32_16x16x32_bf16 v[10:13], v[18:21], v[160:163], v[10:13]
	ds_read_b128 v[18:21], v181 offset:43648
	s_waitcnt lgkmcnt(0)
	v_mfma_f32_16x16x32_bf16 v[14:17], v[18:21], v[78:81], v[14:17]
	v_mfma_f32_16x16x32_bf16 v[10:13], v[18:21], v[152:155], v[10:13]
	ds_read_b128 v[18:21], v181 offset:43712
	s_waitcnt lgkmcnt(0)
	v_mfma_f32_16x16x32_bf16 v[22:25], v[18:21], v[74:77], v[14:17]
	v_mfma_f32_16x16x32_bf16 v[18:21], v[18:21], v[148:151], v[10:13]
	s_nop 3
	ds_read_b128 v[10:13], v181 offset:47872
	s_waitcnt lgkmcnt(0)
	v_mfma_f32_16x16x32_bf16 v[14:17], v[10:13], v[164:167], 0
	v_mfma_f32_16x16x32_bf16 v[10:13], v[10:13], v[168:171], 0
	v_mfma_f32_16x16x32_bf16 v[14:17], v[66:69], v[156:159], v[14:17]
	v_mfma_f32_16x16x32_bf16 v[10:13], v[66:69], v[160:163], v[10:13]
	ds_read_b128 v[66:69], v181 offset:48000
	s_waitcnt lgkmcnt(0)
	v_mfma_f32_16x16x32_bf16 v[14:17], v[66:69], v[78:81], v[14:17]
	v_mfma_f32_16x16x32_bf16 v[10:13], v[66:69], v[152:155], v[10:13]
	ds_read_b128 v[66:69], v181 offset:48064
	s_waitcnt lgkmcnt(0)
	v_mfma_f32_16x16x32_bf16 v[94:97], v[66:69], v[74:77], v[14:17]
	v_mfma_f32_16x16x32_bf16 v[90:93], v[66:69], v[148:151], v[10:13]
	s_nop 3
	ds_read_b128 v[10:13], v181 offset:52224
	ds_read_b128 v[66:69], v181 offset:52288
	s_waitcnt lgkmcnt(1)
	v_mfma_f32_16x16x32_bf16 v[14:17], v[10:13], v[164:167], 0
	ds_read_b128 v[82:85], v181 offset:56640
	v_mfma_f32_16x16x32_bf16 v[10:13], v[10:13], v[168:171], 0
	s_waitcnt lgkmcnt(1)
	v_mfma_f32_16x16x32_bf16 v[14:17], v[66:69], v[156:159], v[14:17]
	v_mfma_f32_16x16x32_bf16 v[10:13], v[66:69], v[160:163], v[10:13]
	ds_read_b128 v[66:69], v181 offset:52352
	s_waitcnt lgkmcnt(0)
	v_mfma_f32_16x16x32_bf16 v[14:17], v[66:69], v[78:81], v[14:17]
	v_mfma_f32_16x16x32_bf16 v[10:13], v[66:69], v[152:155], v[10:13]
	ds_read_b128 v[66:69], v181 offset:52416
	s_waitcnt lgkmcnt(0)
	v_mfma_f32_16x16x32_bf16 v[14:17], v[66:69], v[74:77], v[14:17]
	v_mfma_f32_16x16x32_bf16 v[10:13], v[66:69], v[148:151], v[10:13]
	ds_read_b128 v[66:69], v181 offset:56576
	s_waitcnt lgkmcnt(0)
; #define LAS __attribute__((address_space(3)))
; #define MFMA16(a, b, c) __builtin_amdgcn_mfma_f32_16x16x32_bf16((a), (b), (c), 0, 0, 0)
; __device__ __forceinline__ void mem_attn(const Params& P, int l, LAS unsigned char* lds, int item, int tid) {
;     ...
;         for (int kt = 0; kt < 16; ++kt) { sa[kt] = (f32x4){0.f, 0.f, 0.f, 0.f}; sb[kt] = (f32x4){0.f, 0.f, 0.f, 0.f};
; #pragma unroll
;             for (int ks = 0; ks < 4; ++ks) { const bf16x8 ka = *(const LAS bf16x8*)(KS + (kt * 16 + i) * 272 + (ks * 32 + quad * 8) * 2); sa[kt] = MFMA16(ka, qf0[ks], sa[kt]); sb[kt] = MFMA16(ka, qf1[ks], sb[kt]); }
;             if (kt & 1) __builtin_amdgcn_sched_barrier(0); }
;         float mxa = -INFINITY, mxb = -INFINITY;
; #pragma unroll
;         for (int kt = 0; kt < 16; ++kt) { mxa = fmaxf(fmaxf(fmaxf(sa[kt][0], sa[kt][1]), fmaxf(sa[kt][2], sa[kt][3])), mxa); mxb = fmaxf(fmaxf(fmaxf(sb[kt][0], sb[kt][1]), fmaxf(sb[kt][2], sb[kt][3])), mxb); }
;         mxa = fmaxf(mxa, __shfl_xor(mxa, 16)); mxa = fmaxf(mxa, __shfl_xor(mxa, 32)); mxb = fmaxf(mxb, __shfl_xor(mxb, 16)); mxb = fmaxf(mxb, __shfl_xor(mxb, 32));
	v_mfma_f32_16x16x32_bf16 v[70:73], v[66:69], v[164:167], 0
	v_mfma_f32_16x16x32_bf16 v[66:69], v[66:69], v[168:171], 0
	v_mfma_f32_16x16x32_bf16 v[70:73], v[82:85], v[156:159], v[70:73]
	v_mfma_f32_16x16x32_bf16 v[66:69], v[82:85], v[160:163], v[66:69]
	ds_read_b128 v[82:85], v181 offset:56704
	s_waitcnt lgkmcnt(0)
	v_mfma_f32_16x16x32_bf16 v[70:73], v[82:85], v[78:81], v[70:73]
	v_mfma_f32_16x16x32_bf16 v[66:69], v[82:85], v[152:155], v[66:69]
	ds_read_b128 v[82:85], v181 offset:56768
	s_waitcnt lgkmcnt(0)
	v_mfma_f32_16x16x32_bf16 v[86:89], v[82:85], v[74:77], v[70:73]
	v_mfma_f32_16x16x32_bf16 v[82:85], v[82:85], v[148:151], v[66:69]
	s_nop 3
	ds_read_b128 v[66:69], v181 offset:60928
	ds_read_b128 v[192:195], v181 offset:60992
	s_waitcnt lgkmcnt(1)
	v_mfma_f32_16x16x32_bf16 v[70:73], v[66:69], v[164:167], 0
	v_mfma_f32_16x16x32_bf16 v[66:69], v[66:69], v[168:171], 0
	s_waitcnt lgkmcnt(0)
	v_mfma_f32_16x16x32_bf16 v[70:73], v[192:195], v[156:159], v[70:73]
	v_mfma_f32_16x16x32_bf16 v[66:69], v[192:195], v[160:163], v[66:69]
	ds_read_b128 v[192:195], v181 offset:61056
	s_waitcnt lgkmcnt(0)
	v_mfma_f32_16x16x32_bf16 v[70:73], v[192:195], v[78:81], v[70:73]
	v_mfma_f32_16x16x32_bf16 v[66:69], v[192:195], v[152:155], v[66:69]
	ds_read_b128 v[192:195], v181 offset:61120
	s_waitcnt lgkmcnt(0)
	v_mfma_f32_16x16x32_bf16 v[70:73], v[192:195], v[74:77], v[70:73]
	v_mfma_f32_16x16x32_bf16 v[66:69], v[192:195], v[148:151], v[66:69]
	ds_read_b128 v[192:195], v181 offset:65280
	s_waitcnt lgkmcnt(0)
	v_mfma_f32_16x16x32_bf16 v[164:167], v[192:195], v[164:167], 0
	v_mfma_f32_16x16x32_bf16 v[168:171], v[192:195], v[168:171], 0
	ds_read_b128 v[192:195], v181 offset:65344
	s_waitcnt lgkmcnt(0)
	v_mfma_f32_16x16x32_bf16 v[156:159], v[192:195], v[156:159], v[164:167]
	s_nop 3
	ds_read_b128 v[164:167], v181 offset:65408
	s_waitcnt lgkmcnt(0)
	v_mfma_f32_16x16x32_bf16 v[78:81], v[164:167], v[78:81], v[156:159]
	s_nop 2
	ds_read_b128 v[156:159], v181 offset:65472
	v_mfma_f32_16x16x32_bf16 v[160:163], v[192:195], v[160:163], v[168:171]
	v_mfma_f32_16x16x32_bf16 v[152:155], v[164:167], v[152:155], v[160:163]
	s_waitcnt lgkmcnt(0)
	v_mfma_f32_16x16x32_bf16 v[78:81], v[156:159], v[74:77], v[78:81]
	v_mfma_f32_16x16x32_bf16 v[74:77], v[156:159], v[148:151], v[152:155]
	v_max_f32_e32 v148, v7, v7
	v_max_f32_e32 v149, v6, v6
	v_max_f32_e32 v148, v149, v148
	v_max_f32_e32 v149, v9, v9
	v_max_f32_e32 v150, v8, v8
	v_max_f32_e32 v149, v150, v149
	v_max3_f32 v148, v148, v149, s12
	v_max_f32_e32 v149, v3, v3
	v_max_f32_e32 v150, v2, v2
	v_max_f32_e32 v149, v150, v149
	v_max_f32_e32 v150, v5, v5
	v_max_f32_e32 v151, v4, v4
	v_max_f32_e32 v150, v151, v150
	v_max3_f32 v149, v149, v150, s12
	v_max_f32_e32 v150, v59, v59
	v_max_f32_e32 v151, v58, v58
	v_max_f32_e32 v150, v151, v150
	v_max_f32_e32 v151, v61, v61
	v_max_f32_e32 v152, v60, v60
	v_max_f32_e32 v151, v152, v151
	v_max3_f32 v148, v150, v151, v148
	v_max_f32_e32 v150, v63, v63
	v_max_f32_e32 v151, v62, v62
	v_max_f32_e32 v150, v151, v150
	v_max_f32_e32 v151, v65, v65
	v_max_f32_e32 v152, v64, v64
	v_max_f32_e32 v151, v152, v151
	v_max3_f32 v149, v150, v151, v149
	v_max_f32_e32 v150, v55, v55
	v_max_f32_e32 v151, v54, v54
	v_max_f32_e32 v150, v151, v150
	v_max_f32_e32 v151, v57, v57
	v_max_f32_e32 v152, v56, v56
	v_max_f32_e32 v151, v152, v151
	v_max3_f32 v148, v150, v151, v148
	v_max_f32_e32 v150, v51, v51
	v_max_f32_e32 v151, v50, v50
	v_max_f32_e32 v150, v151, v150
	v_max_f32_e32 v151, v53, v53
	v_max_f32_e32 v152, v52, v52
	v_max_f32_e32 v151, v152, v151
	v_max3_f32 v149, v150, v151, v149
	v_max_f32_e32 v150, v145, v145
	v_max_f32_e32 v151, v144, v144
	v_max_f32_e32 v150, v151, v150
	v_max_f32_e32 v151, v147, v147
	v_max_f32_e32 v152, v146, v146
	v_max_f32_e32 v151, v152, v151
	v_max3_f32 v148, v150, v151, v148
	v_max_f32_e32 v150, v123, v123
	v_max_f32_e32 v151, v122, v122
	v_max_f32_e32 v150, v151, v150
	v_max_f32_e32 v151, v125, v125
	v_max_f32_e32 v152, v124, v124
	v_max_f32_e32 v151, v152, v151
	v_max3_f32 v149, v150, v151, v149
	v_max_f32_e32 v150, v47, v47
	v_max_f32_e32 v151, v46, v46
	v_max_f32_e32 v150, v151, v150
	v_max_f32_e32 v151, v49, v49
	v_max_f32_e32 v152, v48, v48
	v_max_f32_e32 v151, v152, v151
	v_max3_f32 v148, v150, v151, v148
	v_max_f32_e32 v150, v43, v43
	v_max_f32_e32 v151, v42, v42
	v_max_f32_e32 v150, v151, v150
	v_max_f32_e32 v151, v45, v45
	v_max_f32_e32 v152, v44, v44
	v_max_f32_e32 v151, v152, v151
	v_max3_f32 v149, v150, v151, v149
	v_max_f32_e32 v150, v119, v119
	v_max_f32_e32 v151, v118, v118
	v_max_f32_e32 v150, v151, v150
	v_max_f32_e32 v151, v121, v121
	v_max_f32_e32 v152, v120, v120
	v_max_f32_e32 v151, v152, v151
	v_max3_f32 v148, v150, v151, v148
	v_max_f32_e32 v150, v115, v115
	v_max_f32_e32 v151, v114, v114
	v_max_f32_e32 v150, v151, v150
	v_max_f32_e32 v151, v117, v117
	v_max_f32_e32 v152, v116, v116
	v_max_f32_e32 v151, v152, v151
	v_max3_f32 v149, v150, v151, v149
	v_max_f32_e32 v150, v39, v39
	v_max_f32_e32 v151, v38, v38
	v_max_f32_e32 v150, v151, v150
	v_max_f32_e32 v151, v41, v41
	v_max_f32_e32 v152, v40, v40
	v_max_f32_e32 v151, v152, v151
	v_max3_f32 v148, v150, v151, v148
	v_max_f32_e32 v150, v35, v35
	v_max_f32_e32 v151, v34, v34
	v_max_f32_e32 v150, v151, v150
	v_max_f32_e32 v151, v37, v37
	v_max_f32_e32 v152, v36, v36
	v_max_f32_e32 v151, v152, v151
	v_max3_f32 v149, v150, v151, v149
	v_max_f32_e32 v150, v111, v111
	v_max_f32_e32 v151, v110, v110
	v_max_f32_e32 v150, v151, v150
	v_max_f32_e32 v151, v113, v113
	v_max_f32_e32 v152, v112, v112
	v_max_f32_e32 v151, v152, v151
	v_max3_f32 v148, v150, v151, v148
	v_max_f32_e32 v150, v107, v107
	v_max_f32_e32 v151, v106, v106
; __device__ __forceinline__ void mem_attn(const Params& P, int l, LAS unsigned char* lds, int item, int tid) {
;     ...
;         for (int kt = 0; kt < 16; ++kt) { mxa = fmaxf(fmaxf(fmaxf(sa[kt][0], sa[kt][1]), fmaxf(sa[kt][2], sa[kt][3])), mxa); mxb = fmaxf(fmaxf(fmaxf(sb[kt][0], sb[kt][1]), fmaxf(sb[kt][2], sb[kt][3])), mxb); }
;         mxa = fmaxf(mxa, __shfl_xor(mxa, 16)); mxa = fmaxf(mxa, __shfl_xor(mxa, 32)); mxb = fmaxf(mxb, __shfl_xor(mxb, 16)); mxb = fmaxf(mxb, __shfl_xor(mxb, 32));
;         const float sc = 0.08838834764831845f * 1.4426950408889634f; float lsa = 0.f, lsb = 0.f;
;         bf16x8 pa[8], pbb[8];
; #pragma unroll
;         for (int s = 0; s < 8; ++s) { float p[8], r[8];
; #pragma unroll
;             for (int j = 0; j < 4; ++j) { p[j] = __builtin_amdgcn_exp2f((sa[2 * s][j] - mxa) * sc); p[4 + j] = __builtin_amdgcn_exp2f((sa[2 * s + 1][j] - mxa) * sc); r[j] = __builtin_amdgcn_exp2f((sb[2 * s][j] - mxb) * sc); r[4 + j] = __builtin_amdgcn_exp2f((sb[2 * s + 1][j] - mxb) * sc); }
	v_max_f32_e32 v150, v151, v150
	v_max_f32_e32 v151, v109, v109
	v_max_f32_e32 v152, v108, v108
	v_max_f32_e32 v151, v152, v151
	v_max3_f32 v149, v150, v151, v149
	v_max_f32_e32 v150, v31, v31
	v_max_f32_e32 v151, v30, v30
	v_max_f32_e32 v150, v151, v150
	v_max_f32_e32 v151, v33, v33
	v_max_f32_e32 v152, v32, v32
	v_max_f32_e32 v151, v152, v151
	v_max3_f32 v148, v150, v151, v148
	v_max_f32_e32 v150, v27, v27
	v_max_f32_e32 v151, v26, v26
	v_max_f32_e32 v150, v151, v150
	v_max_f32_e32 v151, v29, v29
	v_max_f32_e32 v152, v28, v28
	v_max_f32_e32 v151, v152, v151
	v_max3_f32 v149, v150, v151, v149
	v_max_f32_e32 v150, v103, v103
	v_max_f32_e32 v151, v102, v102
	v_max_f32_e32 v150, v151, v150
	v_max_f32_e32 v151, v105, v105
	v_max_f32_e32 v152, v104, v104
	v_max_f32_e32 v151, v152, v151
	v_max3_f32 v148, v150, v151, v148
	v_max_f32_e32 v150, v99, v99
	v_max_f32_e32 v151, v98, v98
	v_max_f32_e32 v150, v151, v150
	v_max_f32_e32 v151, v101, v101
	v_max_f32_e32 v152, v100, v100
	v_max_f32_e32 v151, v152, v151
	v_max3_f32 v149, v150, v151, v149
	v_max_f32_e32 v150, v23, v23
	v_max_f32_e32 v151, v22, v22
	v_max_f32_e32 v150, v151, v150
	v_max_f32_e32 v151, v25, v25
	v_max_f32_e32 v152, v24, v24
	v_max_f32_e32 v151, v152, v151
	v_max3_f32 v148, v150, v151, v148
	v_max_f32_e32 v150, v19, v19
	v_max_f32_e32 v151, v18, v18
	v_max_f32_e32 v150, v151, v150
	v_max_f32_e32 v151, v21, v21
	v_max_f32_e32 v152, v20, v20
	v_max_f32_e32 v151, v152, v151
	v_max3_f32 v149, v150, v151, v149
	v_max_f32_e32 v150, v95, v95
	v_max_f32_e32 v151, v94, v94
	v_max_f32_e32 v150, v151, v150
	v_max_f32_e32 v151, v97, v97
	v_max_f32_e32 v152, v96, v96
	v_max_f32_e32 v151, v152, v151
	v_max3_f32 v148, v150, v151, v148
	v_max_f32_e32 v150, v91, v91
	v_max_f32_e32 v151, v90, v90
	v_max_f32_e32 v150, v151, v150
	v_max_f32_e32 v151, v93, v93
	v_max_f32_e32 v152, v92, v92
	v_max_f32_e32 v151, v152, v151
	v_max3_f32 v149, v150, v151, v149
	v_max_f32_e32 v150, v15, v15
	v_max_f32_e32 v151, v14, v14
	v_max_f32_e32 v150, v151, v150
	v_max_f32_e32 v151, v17, v17
	v_max_f32_e32 v152, v16, v16
	v_max_f32_e32 v151, v152, v151
	v_max3_f32 v148, v150, v151, v148
	v_max_f32_e32 v150, v11, v11
	v_max_f32_e32 v151, v10, v10
	v_max_f32_e32 v150, v151, v150
	v_max_f32_e32 v151, v13, v13
	v_max_f32_e32 v152, v12, v12
	v_max_f32_e32 v151, v152, v151
	v_max3_f32 v149, v150, v151, v149
	v_max_f32_e32 v150, v87, v87
	v_max_f32_e32 v151, v86, v86
	v_max_f32_e32 v150, v151, v150
	v_max_f32_e32 v151, v89, v89
	v_max_f32_e32 v152, v88, v88
	v_max_f32_e32 v151, v152, v151
	v_max3_f32 v148, v150, v151, v148
	v_max_f32_e32 v150, v83, v83
	v_max_f32_e32 v151, v82, v82
	v_max_f32_e32 v150, v151, v150
	v_max_f32_e32 v151, v85, v85
	v_max_f32_e32 v152, v84, v84
	v_max_f32_e32 v151, v152, v151
	v_max3_f32 v149, v150, v151, v149
	v_max_f32_e32 v150, v71, v71
	v_max_f32_e32 v151, v70, v70
	v_max_f32_e32 v150, v151, v150
	v_max_f32_e32 v151, v73, v73
	v_max_f32_e32 v152, v72, v72
	v_max_f32_e32 v151, v152, v151
	v_max3_f32 v148, v150, v151, v148
	v_max_f32_e32 v150, v67, v67
	v_max_f32_e32 v151, v66, v66
	v_max_f32_e32 v150, v151, v150
	v_max_f32_e32 v151, v69, v69
	v_max_f32_e32 v152, v68, v68
	v_max_f32_e32 v151, v152, v151
	v_max3_f32 v149, v150, v151, v149
	v_max_f32_e32 v150, v79, v79
	v_max_f32_e32 v151, v78, v78
	v_max_f32_e32 v150, v151, v150
	v_max_f32_e32 v151, v81, v81
	v_max_f32_e32 v152, v80, v80
	v_max_f32_e32 v151, v152, v151
	v_max3_f32 v148, v150, v151, v148
	v_max_f32_e32 v150, v75, v75
	v_max_f32_e32 v151, v74, v74
	v_max_f32_e32 v150, v151, v150
	v_max_f32_e32 v151, v77, v77
	v_max_f32_e32 v152, v76, v76
	v_max_f32_e32 v151, v152, v151
	v_max3_f32 v149, v150, v151, v149
	ds_bpermute_b32 v150, v179, v148
	s_waitcnt lgkmcnt(0)
	v_max_f32_e32 v150, v150, v150
	v_max_f32_e32 v148, v148, v150
	ds_bpermute_b32 v150, v180, v148
	s_waitcnt lgkmcnt(0)
	v_max_f32_e32 v150, v150, v150
	v_max_f32_e32 v148, v148, v150
	ds_bpermute_b32 v150, v179, v149
	v_sub_f32_e32 v6, v6, v148
	v_mul_f32_e32 v6, 0x3e0293ee, v6
	v_sub_f32_e32 v7, v7, v148
	v_exp_f32_e32 v6, v6
	s_waitcnt lgkmcnt(0)
	v_max_f32_e32 v150, v150, v150
	v_max_f32_e32 v149, v149, v150
	ds_bpermute_b32 v150, v180, v149
	v_mul_f32_e32 v7, 0x3e0293ee, v7
	v_sub_f32_e32 v8, v8, v148
	v_exp_f32_e32 v7, v7
	v_mul_f32_e32 v8, 0x3e0293ee, v8
	s_waitcnt lgkmcnt(0)
; __device__ __forceinline__ unsigned pk2(float lo, float hi) { const f32x2c_t v = {lo, hi}; return __builtin_bit_cast(unsigned, __builtin_convertvector(v, bf16x2c_t)); }
; __device__ __forceinline__ void mem_attn(const Params& P, int l, LAS unsigned char* lds, int item, int tid) {
;     ...
;         for (int s = 0; s < 8; ++s) { float p[8], r[8];
; #pragma unroll
;             for (int j = 0; j < 4; ++j) { p[j] = __builtin_amdgcn_exp2f((sa[2 * s][j] - mxa) * sc); p[4 + j] = __builtin_amdgcn_exp2f((sa[2 * s + 1][j] - mxa) * sc); r[j] = __builtin_amdgcn_exp2f((sb[2 * s][j] - mxb) * sc); r[4 + j] = __builtin_amdgcn_exp2f((sb[2 * s + 1][j] - mxb) * sc); }
; #pragma unroll
;             for (int j = 0; j < 8; ++j) { lsa += p[j]; lsb += r[j]; }
;             v4u pw; pw.x = pk2(p[0], p[1]); pw.y = pk2(p[2], p[3]); pw.z = pk2(p[4], p[5]); pw.w = pk2(p[6], p[7]); pa[s] = __builtin_bit_cast(bf16x8, pw);
;             v4u rw; rw.x = pk2(r[0], r[1]); rw.y = pk2(r[2], r[3]); rw.z = pk2(r[4], r[5]); rw.w = pk2(r[6], r[7]); pbb[s] = __builtin_bit_cast(bf16x8, rw); }
	v_max_f32_e32 v150, v150, v150
	v_max_f32_e32 v149, v149, v150
	v_sub_f32_e32 v62, v62, v149
	v_mul_f32_e32 v62, 0x3e0293ee, v62
	v_sub_f32_e32 v2, v2, v149
	v_exp_f32_e32 v150, v62
	v_sub_f32_e32 v62, v63, v149
	v_mul_f32_e32 v2, 0x3e0293ee, v2
	v_sub_f32_e32 v3, v3, v149
	v_mul_f32_e32 v62, 0x3e0293ee, v62
	v_exp_f32_e32 v2, v2
	v_mul_f32_e32 v3, 0x3e0293ee, v3
	v_exp_f32_e32 v151, v62
	v_sub_f32_e32 v4, v4, v149
	v_sub_f32_e32 v62, v64, v149
	v_exp_f32_e32 v3, v3
	v_mul_f32_e32 v4, 0x3e0293ee, v4
	v_mul_f32_e32 v62, 0x3e0293ee, v62
	v_sub_f32_e32 v9, v9, v148
	v_sub_f32_e32 v5, v5, v149
	v_sub_f32_e32 v58, v58, v148
	v_exp_f32_e32 v8, v8
	v_exp_f32_e32 v4, v4
	v_exp_f32_e32 v152, v62
	v_mul_f32_e32 v9, 0x3e0293ee, v9
	v_mul_f32_e32 v5, 0x3e0293ee, v5
	v_sub_f32_e32 v62, v65, v149
	v_mul_f32_e32 v58, 0x3e0293ee, v58
	v_sub_f32_e32 v59, v59, v148
	v_exp_f32_e32 v9, v9
	v_exp_f32_e32 v5, v5
	v_mul_f32_e32 v62, 0x3e0293ee, v62
	v_exp_f32_e32 v58, v58
	v_mul_f32_e32 v59, 0x3e0293ee, v59
	v_exp_f32_e32 v153, v62
	v_add_f32_e32 v62, 0, v6
	v_add_f32_e32 v63, 0, v2
	v_exp_f32_e32 v59, v59
	v_add_f32_e32 v62, v7, v62
	v_add_f32_e32 v63, v3, v63
	v_add_f32_e32 v62, v8, v62
	v_add_f32_e32 v63, v4, v63
	v_add_f32_e32 v62, v9, v62
	v_add_f32_e32 v63, v5, v63
	v_sub_f32_e32 v60, v60, v148
	v_add_f32_e32 v62, v58, v62
	v_add_f32_e32 v63, v150, v63
	v_mul_f32_e32 v60, 0x3e0293ee, v60
	v_sub_f32_e32 v61, v61, v148
	v_add_f32_e32 v62, v59, v62
	v_add_f32_e32 v63, v151, v63
	v_cvt_pk_bf16_f32 v64, v58, v59
	v_cvt_pk_bf16_f32 v59, v4, v5
	v_sub_f32_e32 v4, v50, v149
	v_sub_f32_e32 v50, v56, v148
	v_exp_f32_e32 v60, v60
	v_mul_f32_e32 v61, 0x3e0293ee, v61
	v_add_f32_e32 v63, v152, v63
	v_mul_f32_e32 v50, 0x3e0293ee, v50
	v_exp_f32_e32 v61, v61
	v_add_f32_e32 v155, v153, v63
	v_cvt_pk_bf16_f32 v63, v8, v9
	v_sub_f32_e32 v8, v51, v149
	v_exp_f32_e32 v51, v50
	v_sub_f32_e32 v50, v146, v148
	v_mul_f32_e32 v50, 0x3e0293ee, v50
	v_cvt_pk_bf16_f32 v58, v2, v3
	v_sub_f32_e32 v2, v54, v148
	v_exp_f32_e32 v54, v50
	v_sub_f32_e32 v50, v52, v149
	v_add_f32_e32 v62, v60, v62
	v_mul_f32_e32 v50, 0x3e0293ee, v50
	v_add_f32_e32 v154, v61, v62
	v_cvt_pk_bf16_f32 v62, v6, v7
	v_sub_f32_e32 v6, v55, v148
	v_exp_f32_e32 v55, v50
	v_sub_f32_e32 v50, v124, v149
	v_mul_f32_e32 v50, 0x3e0293ee, v50
	v_sub_f32_e32 v5, v122, v149
	v_exp_f32_e32 v122, v50
	v_sub_f32_e32 v50, v57, v148
	v_mul_f32_e32 v50, 0x3e0293ee, v50
	v_mul_f32_e32 v4, 0x3e0293ee, v4
	v_exp_f32_e32 v52, v50
	v_sub_f32_e32 v50, v147, v148
	v_mul_f32_e32 v2, 0x3e0293ee, v2
	v_exp_f32_e32 v4, v4
	v_mul_f32_e32 v8, 0x3e0293ee, v8
	v_mul_f32_e32 v50, 0x3e0293ee, v50
	v_exp_f32_e32 v2, v2
	v_mul_f32_e32 v6, 0x3e0293ee, v6
	v_exp_f32_e32 v8, v8
	v_exp_f32_e32 v56, v50
	v_sub_f32_e32 v50, v53, v149
	v_exp_f32_e32 v6, v6
	v_mul_f32_e32 v50, 0x3e0293ee, v50
	v_sub_f32_e32 v3, v144, v148
	v_mul_f32_e32 v5, 0x3e0293ee, v5
	v_sub_f32_e32 v9, v123, v149
	v_exp_f32_e32 v57, v50
	v_sub_f32_e32 v50, v125, v149
	v_mul_f32_e32 v3, 0x3e0293ee, v3
	v_exp_f32_e32 v5, v5
	v_sub_f32_e32 v7, v145, v148
	v_mul_f32_e32 v9, 0x3e0293ee, v9
	v_mul_f32_e32 v50, 0x3e0293ee, v50
	v_add_f32_e32 v53, v4, v155
	v_exp_f32_e32 v3, v3
	v_mul_f32_e32 v7, 0x3e0293ee, v7
	v_exp_f32_e32 v9, v9
	v_exp_f32_e32 v123, v50
	v_add_f32_e32 v50, v2, v154
	v_add_f32_e32 v53, v8, v53
	v_exp_f32_e32 v7, v7
	v_add_f32_e32 v50, v6, v50
	v_add_f32_e32 v53, v55, v53
	v_add_f32_e32 v50, v51, v50
	v_add_f32_e32 v53, v57, v53
	v_add_f32_e32 v50, v52, v50
	v_add_f32_e32 v53, v5, v53
	v_add_f32_e32 v50, v3, v50
	v_add_f32_e32 v53, v9, v53
	v_add_f32_e32 v50, v7, v50
	v_add_f32_e32 v53, v122, v53
	v_add_f32_e32 v50, v54, v50
	v_add_f32_e32 v125, v123, v53
	v_cvt_pk_bf16_f32 v53, v54, v56
	v_cvt_pk_bf16_f32 v54, v4, v8
	v_sub_f32_e32 v4, v42, v149
	v_sub_f32_e32 v42, v48, v148
	v_mul_f32_e32 v42, 0x3e0293ee, v42
	v_sub_f32_e32 v8, v43, v149
	v_exp_f32_e32 v43, v42
	v_sub_f32_e32 v42, v120, v148
	v_mul_f32_e32 v42, 0x3e0293ee, v42
	v_add_f32_e32 v124, v56, v50
	v_cvt_pk_bf16_f32 v50, v2, v6
	v_sub_f32_e32 v2, v46, v148
	v_exp_f32_e32 v46, v42
	v_sub_f32_e32 v42, v44, v149
	v_mul_f32_e32 v42, 0x3e0293ee, v42
	v_sub_f32_e32 v6, v47, v148
	v_exp_f32_e32 v47, v42
	v_sub_f32_e32 v42, v116, v149
	v_mul_f32_e32 v42, 0x3e0293ee, v42
	v_cvt_pk_bf16_f32 v56, v5, v9
	v_sub_f32_e32 v5, v114, v149
	v_exp_f32_e32 v114, v42
	v_sub_f32_e32 v42, v49, v148
	v_mul_f32_e32 v42, 0x3e0293ee, v42
	v_mul_f32_e32 v4, 0x3e0293ee, v4
	v_exp_f32_e32 v44, v42
	v_sub_f32_e32 v42, v121, v148
	v_mul_f32_e32 v2, 0x3e0293ee, v2
	v_exp_f32_e32 v4, v4
	v_mul_f32_e32 v8, 0x3e0293ee, v8
	v_mul_f32_e32 v42, 0x3e0293ee, v42
	v_exp_f32_e32 v2, v2
	v_mul_f32_e32 v6, 0x3e0293ee, v6
	v_exp_f32_e32 v8, v8
	v_exp_f32_e32 v48, v42
	v_sub_f32_e32 v42, v45, v149
	v_exp_f32_e32 v6, v6
	v_mul_f32_e32 v42, 0x3e0293ee, v42
	v_cvt_pk_bf16_f32 v51, v51, v52
	v_cvt_pk_bf16_f32 v52, v3, v7
	v_sub_f32_e32 v3, v118, v148
	v_mul_f32_e32 v5, 0x3e0293ee, v5
	v_sub_f32_e32 v9, v115, v149
	v_exp_f32_e32 v49, v42
	v_sub_f32_e32 v42, v117, v149
	v_mul_f32_e32 v3, 0x3e0293ee, v3
	v_exp_f32_e32 v5, v5
	v_sub_f32_e32 v7, v119, v148
	v_mul_f32_e32 v9, 0x3e0293ee, v9
	v_mul_f32_e32 v42, 0x3e0293ee, v42
	v_add_f32_e32 v45, v4, v125
	v_exp_f32_e32 v3, v3
	v_mul_f32_e32 v7, 0x3e0293ee, v7
	v_exp_f32_e32 v9, v9
	v_exp_f32_e32 v115, v42
	v_add_f32_e32 v42, v2, v124
	v_add_f32_e32 v45, v8, v45
	v_exp_f32_e32 v7, v7
	v_add_f32_e32 v42, v6, v42
	v_add_f32_e32 v45, v47, v45
	v_add_f32_e32 v42, v43, v42
	v_add_f32_e32 v45, v49, v45
	v_add_f32_e32 v42, v44, v42
	v_add_f32_e32 v45, v5, v45
	v_add_f32_e32 v42, v3, v42
	v_add_f32_e32 v45, v9, v45
; __device__ __forceinline__ unsigned pk2(float lo, float hi) { const f32x2c_t v = {lo, hi}; return __builtin_bit_cast(unsigned, __builtin_convertvector(v, bf16x2c_t)); }
; __device__ __forceinline__ void mem_attn(const Params& P, int l, LAS unsigned char* lds, int item, int tid) {
;     ...
;         for (int s = 0; s < 8; ++s) { float p[8], r[8];
; #pragma unroll
;             for (int j = 0; j < 4; ++j) { p[j] = __builtin_amdgcn_exp2f((sa[2 * s][j] - mxa) * sc); p[4 + j] = __builtin_amdgcn_exp2f((sa[2 * s + 1][j] - mxa) * sc); r[j] = __builtin_amdgcn_exp2f((sb[2 * s][j] - mxb) * sc); r[4 + j] = __builtin_amdgcn_exp2f((sb[2 * s + 1][j] - mxb) * sc); }
; #pragma unroll
;             for (int j = 0; j < 8; ++j) { lsa += p[j]; lsb += r[j]; }
;             v4u pw; pw.x = pk2(p[0], p[1]); pw.y = pk2(p[2], p[3]); pw.z = pk2(p[4], p[5]); pw.w = pk2(p[6], p[7]); pa[s] = __builtin_bit_cast(bf16x8, pw);
;             v4u rw; rw.x = pk2(r[0], r[1]); rw.y = pk2(r[2], r[3]); rw.z = pk2(r[4], r[5]); rw.w = pk2(r[6], r[7]); pbb[s] = __builtin_bit_cast(bf16x8, rw); }
	v_add_f32_e32 v42, v7, v42
	v_add_f32_e32 v45, v114, v45
	v_add_f32_e32 v42, v46, v42
	v_add_f32_e32 v117, v115, v45
	v_cvt_pk_bf16_f32 v45, v46, v48
	v_cvt_pk_bf16_f32 v46, v4, v8
	v_sub_f32_e32 v4, v34, v149
	v_sub_f32_e32 v34, v40, v148
	v_mul_f32_e32 v34, 0x3e0293ee, v34
	v_sub_f32_e32 v8, v35, v149
	v_exp_f32_e32 v35, v34
	v_sub_f32_e32 v34, v112, v148
	v_mul_f32_e32 v34, 0x3e0293ee, v34
	v_add_f32_e32 v116, v48, v42
	v_cvt_pk_bf16_f32 v42, v2, v6
	v_sub_f32_e32 v2, v38, v148
	v_exp_f32_e32 v38, v34
	v_sub_f32_e32 v34, v36, v149
	v_mul_f32_e32 v34, 0x3e0293ee, v34
	v_sub_f32_e32 v6, v39, v148
	v_exp_f32_e32 v39, v34
	v_sub_f32_e32 v34, v108, v149
	v_mul_f32_e32 v34, 0x3e0293ee, v34
	v_cvt_pk_bf16_f32 v48, v5, v9
	v_sub_f32_e32 v5, v106, v149
	v_exp_f32_e32 v106, v34
	v_sub_f32_e32 v34, v41, v148
	v_mul_f32_e32 v34, 0x3e0293ee, v34
	v_mul_f32_e32 v4, 0x3e0293ee, v4
	v_exp_f32_e32 v36, v34
	v_sub_f32_e32 v34, v113, v148
	v_mul_f32_e32 v2, 0x3e0293ee, v2
	v_exp_f32_e32 v4, v4
	v_mul_f32_e32 v8, 0x3e0293ee, v8
	v_mul_f32_e32 v34, 0x3e0293ee, v34
	v_exp_f32_e32 v2, v2
	v_mul_f32_e32 v6, 0x3e0293ee, v6
	v_exp_f32_e32 v8, v8
	v_exp_f32_e32 v40, v34
	v_sub_f32_e32 v34, v37, v149
	v_exp_f32_e32 v6, v6
	v_mul_f32_e32 v34, 0x3e0293ee, v34
	v_cvt_pk_bf16_f32 v43, v43, v44
	v_cvt_pk_bf16_f32 v44, v3, v7
	v_sub_f32_e32 v3, v110, v148
	v_mul_f32_e32 v5, 0x3e0293ee, v5
	v_sub_f32_e32 v9, v107, v149
	v_exp_f32_e32 v41, v34
	v_sub_f32_e32 v34, v109, v149
	v_mul_f32_e32 v3, 0x3e0293ee, v3
	v_exp_f32_e32 v5, v5
	v_sub_f32_e32 v7, v111, v148
	v_mul_f32_e32 v9, 0x3e0293ee, v9
	v_mul_f32_e32 v34, 0x3e0293ee, v34
	v_add_f32_e32 v37, v4, v117
	v_exp_f32_e32 v3, v3
	v_mul_f32_e32 v7, 0x3e0293ee, v7
	v_exp_f32_e32 v9, v9
	v_exp_f32_e32 v107, v34
	v_add_f32_e32 v34, v2, v116
	v_add_f32_e32 v37, v8, v37
	v_exp_f32_e32 v7, v7
	v_add_f32_e32 v34, v6, v34
	v_add_f32_e32 v37, v39, v37
	v_add_f32_e32 v34, v35, v34
	v_add_f32_e32 v37, v41, v37
	v_add_f32_e32 v34, v36, v34
	v_add_f32_e32 v37, v5, v37
	v_add_f32_e32 v34, v3, v34
	v_add_f32_e32 v37, v9, v37
	v_add_f32_e32 v34, v7, v34
	v_add_f32_e32 v37, v106, v37
	v_add_f32_e32 v34, v38, v34
	v_add_f32_e32 v109, v107, v37
	v_cvt_pk_bf16_f32 v37, v38, v40
	v_cvt_pk_bf16_f32 v38, v4, v8
	v_sub_f32_e32 v4, v26, v149
	v_sub_f32_e32 v26, v32, v148
	v_mul_f32_e32 v26, 0x3e0293ee, v26
	v_sub_f32_e32 v8, v27, v149
	v_exp_f32_e32 v27, v26
	v_sub_f32_e32 v26, v104, v148
	v_mul_f32_e32 v26, 0x3e0293ee, v26
	v_add_f32_e32 v108, v40, v34
	v_cvt_pk_bf16_f32 v34, v2, v6
	v_sub_f32_e32 v2, v30, v148
	v_exp_f32_e32 v30, v26
	v_sub_f32_e32 v26, v28, v149
	v_mul_f32_e32 v26, 0x3e0293ee, v26
	v_sub_f32_e32 v6, v31, v148
	v_exp_f32_e32 v31, v26
	v_sub_f32_e32 v26, v100, v149
	v_mul_f32_e32 v26, 0x3e0293ee, v26
	v_cvt_pk_bf16_f32 v40, v5, v9
	v_sub_f32_e32 v5, v98, v149
	v_exp_f32_e32 v98, v26
	v_sub_f32_e32 v26, v33, v148
	v_mul_f32_e32 v26, 0x3e0293ee, v26
	v_mul_f32_e32 v4, 0x3e0293ee, v4
	v_exp_f32_e32 v28, v26
	v_sub_f32_e32 v26, v105, v148
	v_mul_f32_e32 v2, 0x3e0293ee, v2
	v_exp_f32_e32 v4, v4
	v_mul_f32_e32 v8, 0x3e0293ee, v8
	v_mul_f32_e32 v26, 0x3e0293ee, v26
	v_exp_f32_e32 v2, v2
	v_mul_f32_e32 v6, 0x3e0293ee, v6
	v_exp_f32_e32 v8, v8
	v_exp_f32_e32 v32, v26
	v_sub_f32_e32 v26, v29, v149
	v_exp_f32_e32 v6, v6
	v_mul_f32_e32 v26, 0x3e0293ee, v26
	v_cvt_pk_bf16_f32 v35, v35, v36
	v_cvt_pk_bf16_f32 v36, v3, v7
	v_sub_f32_e32 v3, v102, v148
	v_mul_f32_e32 v5, 0x3e0293ee, v5
	v_sub_f32_e32 v9, v99, v149
	v_exp_f32_e32 v33, v26
	v_sub_f32_e32 v26, v101, v149
	v_mul_f32_e32 v3, 0x3e0293ee, v3
	v_exp_f32_e32 v5, v5
	v_sub_f32_e32 v7, v103, v148
	v_mul_f32_e32 v9, 0x3e0293ee, v9
	v_mul_f32_e32 v26, 0x3e0293ee, v26
	v_add_f32_e32 v29, v4, v109
	v_exp_f32_e32 v3, v3
	v_mul_f32_e32 v7, 0x3e0293ee, v7
	v_exp_f32_e32 v9, v9
	v_exp_f32_e32 v99, v26
	v_add_f32_e32 v26, v2, v108
	v_add_f32_e32 v29, v8, v29
	v_exp_f32_e32 v7, v7
	v_add_f32_e32 v26, v6, v26
	v_add_f32_e32 v29, v31, v29
	v_add_f32_e32 v26, v27, v26
	v_add_f32_e32 v29, v33, v29
	v_add_f32_e32 v26, v28, v26
	v_add_f32_e32 v29, v5, v29
	v_add_f32_e32 v26, v3, v26
	v_add_f32_e32 v29, v9, v29
	v_add_f32_e32 v26, v7, v26
	v_add_f32_e32 v29, v98, v29
	v_add_f32_e32 v26, v30, v26
	v_add_f32_e32 v101, v99, v29
	v_cvt_pk_bf16_f32 v29, v30, v32
	v_cvt_pk_bf16_f32 v30, v4, v8
	v_sub_f32_e32 v4, v18, v149
	v_sub_f32_e32 v18, v24, v148
	v_mul_f32_e32 v18, 0x3e0293ee, v18
	v_sub_f32_e32 v8, v19, v149
	v_exp_f32_e32 v19, v18
	v_sub_f32_e32 v18, v96, v148
	v_mul_f32_e32 v18, 0x3e0293ee, v18
	v_add_f32_e32 v100, v32, v26
	v_cvt_pk_bf16_f32 v26, v2, v6
	v_sub_f32_e32 v2, v22, v148
	v_exp_f32_e32 v22, v18
	v_sub_f32_e32 v18, v20, v149
	v_mul_f32_e32 v18, 0x3e0293ee, v18
	v_sub_f32_e32 v6, v23, v148
	v_exp_f32_e32 v23, v18
	v_sub_f32_e32 v18, v92, v149
	v_mul_f32_e32 v18, 0x3e0293ee, v18
	v_cvt_pk_bf16_f32 v32, v5, v9
	v_sub_f32_e32 v5, v90, v149
	v_exp_f32_e32 v90, v18
	v_sub_f32_e32 v18, v25, v148
	v_mul_f32_e32 v18, 0x3e0293ee, v18
	v_mul_f32_e32 v4, 0x3e0293ee, v4
	v_exp_f32_e32 v20, v18
	v_sub_f32_e32 v18, v97, v148
	v_mul_f32_e32 v2, 0x3e0293ee, v2
	v_exp_f32_e32 v4, v4
	v_mul_f32_e32 v8, 0x3e0293ee, v8
	v_mul_f32_e32 v18, 0x3e0293ee, v18
	v_exp_f32_e32 v2, v2
	v_mul_f32_e32 v6, 0x3e0293ee, v6
	v_exp_f32_e32 v8, v8
	v_exp_f32_e32 v24, v18
	v_sub_f32_e32 v18, v21, v149
	v_exp_f32_e32 v6, v6
	v_mul_f32_e32 v18, 0x3e0293ee, v18
	v_cvt_pk_bf16_f32 v27, v27, v28
	v_cvt_pk_bf16_f32 v28, v3, v7
	v_sub_f32_e32 v3, v94, v148
	v_mul_f32_e32 v5, 0x3e0293ee, v5
	v_sub_f32_e32 v9, v91, v149
	v_exp_f32_e32 v25, v18
	v_sub_f32_e32 v18, v93, v149
	v_mul_f32_e32 v3, 0x3e0293ee, v3
	v_exp_f32_e32 v5, v5
; #define LAS __attribute__((address_space(3)))
; __device__ __forceinline__ unsigned pk2(float lo, float hi) { const f32x2c_t v = {lo, hi}; return __builtin_bit_cast(unsigned, __builtin_convertvector(v, bf16x2c_t)); }
; #define MFMA16(a, b, c) __builtin_amdgcn_mfma_f32_16x16x32_bf16((a), (b), (c), 0, 0, 0)
; __device__ __forceinline__ s16x4 trread(const LAS unsigned char* p) { return __builtin_bit_cast(s16x4, __builtin_amdgcn_ds_read_tr16_b64_v4i16((LAS s16x4*)p)); }
; __device__ __forceinline__ bf16x8 cat8(s16x4 lo, s16x4 hi) { return (bf16x8){lo[0], lo[1], lo[2], lo[3], hi[0], hi[1], hi[2], hi[3]}; }
; __device__ __forceinline__ void mem_attn(const Params& P, int l, LAS unsigned char* lds, int item, int tid) {
;     ...
;             for (int j = 0; j < 4; ++j) { p[j] = __builtin_amdgcn_exp2f((sa[2 * s][j] - mxa) * sc); p[4 + j] = __builtin_amdgcn_exp2f((sa[2 * s + 1][j] - mxa) * sc); r[j] = __builtin_amdgcn_exp2f((sb[2 * s][j] - mxb) * sc); r[4 + j] = __builtin_amdgcn_exp2f((sb[2 * s + 1][j] - mxb) * sc); }
; #pragma unroll
;             for (int j = 0; j < 8; ++j) { lsa += p[j]; lsb += r[j]; }
;             v4u pw; pw.x = pk2(p[0], p[1]); pw.y = pk2(p[2], p[3]); pw.z = pk2(p[4], p[5]); pw.w = pk2(p[6], p[7]); pa[s] = __builtin_bit_cast(bf16x8, pw);
;             v4u rw; rw.x = pk2(r[0], r[1]); rw.y = pk2(r[2], r[3]); rw.z = pk2(r[4], r[5]); rw.w = pk2(r[6], r[7]); pbb[s] = __builtin_bit_cast(bf16x8, rw); }
;         lsa += __shfl_xor(lsa, 16); lsa += __shfl_xor(lsa, 32); lsb += __shfl_xor(lsb, 16); lsb += __shfl_xor(lsb, 32);
;         f32x4 oa[8], ob[8];
; #pragma unroll
;         for (int et = 0; et < 8; ++et) { oa[et] = (f32x4){0.f, 0.f, 0.f, 0.f}; ob[et] = (f32x4){0.f, 0.f, 0.f, 0.f}; }
; #pragma unroll
;         for (int s = 0; s < 8; ++s) { const LAS unsigned char* vp = VS + (32 * s + quad * 4 + (i >> 2)) * 288 + (4 * (i & 3)) * 2;
; #pragma unroll
;             for (int et = 0; et < 8; ++et) { const bf16x8 va = cat8(trread(vp + et * 32), trread(vp + et * 32 + 16 * 288)); oa[et] = MFMA16(va, pa[s], oa[et]); ob[et] = MFMA16(va, pbb[s], ob[et]); }
	v_sub_f32_e32 v7, v95, v148
	v_mul_f32_e32 v9, 0x3e0293ee, v9
	v_mul_f32_e32 v18, 0x3e0293ee, v18
	v_add_f32_e32 v21, v4, v101
	v_exp_f32_e32 v3, v3
	v_mul_f32_e32 v7, 0x3e0293ee, v7
	v_exp_f32_e32 v9, v9
	v_exp_f32_e32 v91, v18
	v_add_f32_e32 v18, v2, v100
	v_add_f32_e32 v21, v8, v21
	v_exp_f32_e32 v7, v7
	v_add_f32_e32 v18, v6, v18
	v_add_f32_e32 v21, v23, v21
	v_add_f32_e32 v18, v19, v18
	v_add_f32_e32 v21, v25, v21
	v_add_f32_e32 v18, v20, v18
	v_add_f32_e32 v21, v5, v21
	v_add_f32_e32 v18, v3, v18
	v_add_f32_e32 v21, v9, v21
	v_add_f32_e32 v18, v7, v18
	v_add_f32_e32 v21, v90, v21
	v_add_f32_e32 v18, v22, v18
	v_add_f32_e32 v93, v91, v21
	v_cvt_pk_bf16_f32 v21, v22, v24
	v_cvt_pk_bf16_f32 v22, v4, v8
	v_sub_f32_e32 v4, v10, v149
	v_sub_f32_e32 v10, v16, v148
	v_mul_f32_e32 v10, 0x3e0293ee, v10
	v_sub_f32_e32 v8, v11, v149
	v_exp_f32_e32 v11, v10
	v_sub_f32_e32 v10, v88, v148
	v_mul_f32_e32 v10, 0x3e0293ee, v10
	v_add_f32_e32 v92, v24, v18
	v_cvt_pk_bf16_f32 v18, v2, v6
	v_sub_f32_e32 v2, v14, v148
	v_exp_f32_e32 v14, v10
	v_sub_f32_e32 v10, v12, v149
	v_mul_f32_e32 v10, 0x3e0293ee, v10
	v_sub_f32_e32 v6, v15, v148
	v_exp_f32_e32 v15, v10
	v_sub_f32_e32 v10, v84, v149
	v_mul_f32_e32 v10, 0x3e0293ee, v10
	v_cvt_pk_bf16_f32 v24, v5, v9
	v_sub_f32_e32 v5, v82, v149
	v_exp_f32_e32 v82, v10
	v_sub_f32_e32 v10, v17, v148
	v_mul_f32_e32 v10, 0x3e0293ee, v10
	v_mul_f32_e32 v4, 0x3e0293ee, v4
	v_exp_f32_e32 v12, v10
	v_sub_f32_e32 v10, v89, v148
	v_mul_f32_e32 v2, 0x3e0293ee, v2
	v_exp_f32_e32 v4, v4
	v_mul_f32_e32 v8, 0x3e0293ee, v8
	v_mul_f32_e32 v10, 0x3e0293ee, v10
	v_exp_f32_e32 v2, v2
	v_mul_f32_e32 v6, 0x3e0293ee, v6
	v_exp_f32_e32 v8, v8
	v_exp_f32_e32 v16, v10
	v_sub_f32_e32 v10, v13, v149
	v_exp_f32_e32 v6, v6
	v_mul_f32_e32 v10, 0x3e0293ee, v10
	v_cvt_pk_bf16_f32 v19, v19, v20
	v_cvt_pk_bf16_f32 v20, v3, v7
	v_sub_f32_e32 v3, v86, v148
	v_mul_f32_e32 v5, 0x3e0293ee, v5
	v_sub_f32_e32 v7, v87, v148
	v_sub_f32_e32 v9, v83, v149
	v_exp_f32_e32 v17, v10
	v_sub_f32_e32 v10, v85, v149
	v_mul_f32_e32 v3, 0x3e0293ee, v3
	v_exp_f32_e32 v5, v5
	v_mul_f32_e32 v7, 0x3e0293ee, v7
	v_mul_f32_e32 v9, 0x3e0293ee, v9
	v_mul_f32_e32 v10, 0x3e0293ee, v10
	v_add_f32_e32 v13, v4, v93
	v_exp_f32_e32 v3, v3
	v_exp_f32_e32 v7, v7
	v_exp_f32_e32 v9, v9
	v_exp_f32_e32 v83, v10
	v_add_f32_e32 v10, v2, v92
	v_add_f32_e32 v13, v8, v13
	v_add_f32_e32 v10, v6, v10
	v_add_f32_e32 v13, v15, v13
	v_add_f32_e32 v10, v11, v10
	v_add_f32_e32 v13, v17, v13
	v_add_f32_e32 v10, v12, v10
	v_add_f32_e32 v13, v5, v13
	v_add_f32_e32 v10, v3, v10
	v_add_f32_e32 v13, v9, v13
	v_cvt_pk_bf16_f32 v11, v11, v12
	v_cvt_pk_bf16_f32 v12, v3, v7
	v_sub_f32_e32 v3, v78, v148
	v_add_f32_e32 v10, v7, v10
	v_add_f32_e32 v13, v82, v13
	v_mul_f32_e32 v3, 0x3e0293ee, v3
	v_add_f32_e32 v10, v14, v10
	v_add_f32_e32 v85, v83, v13
	v_cvt_pk_bf16_f32 v13, v14, v16
	v_cvt_pk_bf16_f32 v14, v4, v8
	v_exp_f32_e32 v4, v3
	v_sub_f32_e32 v3, v66, v149
	v_mul_f32_e32 v3, 0x3e0293ee, v3
	v_add_f32_e32 v84, v16, v10
	v_cvt_pk_bf16_f32 v10, v2, v6
	v_exp_f32_e32 v6, v3
	v_sub_f32_e32 v3, v74, v149
	v_sub_f32_e32 v2, v70, v148
	v_mul_f32_e32 v3, 0x3e0293ee, v3
	v_mul_f32_e32 v2, 0x3e0293ee, v2
	v_exp_f32_e32 v8, v3
	v_sub_f32_e32 v3, v71, v148
	v_exp_f32_e32 v2, v2
	v_mul_f32_e32 v3, 0x3e0293ee, v3
	v_sub_f32_e32 v66, v72, v148
	v_exp_f32_e32 v3, v3
	v_mul_f32_e32 v66, 0x3e0293ee, v66
	v_sub_f32_e32 v71, v73, v148
	v_sub_f32_e32 v7, v67, v149
	v_exp_f32_e32 v66, v66
	v_mul_f32_e32 v71, 0x3e0293ee, v71
	v_cvt_pk_bf16_f32 v16, v5, v9
	v_sub_f32_e32 v5, v79, v148
	v_mul_f32_e32 v7, 0x3e0293ee, v7
	v_sub_f32_e32 v68, v68, v149
	v_exp_f32_e32 v71, v71
	v_mul_f32_e32 v5, 0x3e0293ee, v5
	v_exp_f32_e32 v7, v7
	v_sub_f32_e32 v67, v80, v148
	v_mul_f32_e32 v68, 0x3e0293ee, v68
	v_sub_f32_e32 v69, v69, v149
	v_add_f32_e32 v74, v2, v84
	v_exp_f32_e32 v5, v5
	v_mul_f32_e32 v67, 0x3e0293ee, v67
	v_exp_f32_e32 v68, v68
	v_sub_f32_e32 v72, v81, v148
	v_mul_f32_e32 v69, 0x3e0293ee, v69
	v_add_f32_e32 v74, v3, v74
	v_sub_f32_e32 v9, v75, v149
	v_exp_f32_e32 v67, v67
	v_mul_f32_e32 v72, 0x3e0293ee, v72
	v_exp_f32_e32 v69, v69
	v_add_f32_e32 v74, v66, v74
	v_mul_f32_e32 v9, 0x3e0293ee, v9
	v_sub_f32_e32 v70, v76, v149
	v_exp_f32_e32 v72, v72
	v_add_f32_e32 v75, v6, v85
	v_add_f32_e32 v74, v71, v74
	v_exp_f32_e32 v9, v9
	v_mul_f32_e32 v70, 0x3e0293ee, v70
	v_sub_f32_e32 v73, v77, v149
	v_add_f32_e32 v75, v7, v75
	v_add_f32_e32 v74, v4, v74
	v_exp_f32_e32 v70, v70
	v_mul_f32_e32 v73, 0x3e0293ee, v73
	v_add_f32_e32 v75, v68, v75
	v_add_f32_e32 v74, v5, v74
	v_exp_f32_e32 v73, v73
	v_add_f32_e32 v75, v69, v75
	v_add_f32_e32 v74, v67, v74
	v_add_f32_e32 v75, v8, v75
	v_add_f32_e32 v74, v72, v74
	v_add_f32_e32 v75, v9, v75
	v_cvt_pk_bf16_f32 v2, v2, v3
	v_cvt_pk_bf16_f32 v3, v66, v71
	ds_bpermute_b32 v66, v179, v74
	v_add_f32_e32 v75, v70, v75
	v_add_f32_e32 v75, v73, v75
	v_cvt_pk_bf16_f32 v4, v4, v5
	v_cvt_pk_bf16_f32 v5, v67, v72
	v_cvt_pk_bf16_f32 v8, v8, v9
	v_cvt_pk_bf16_f32 v9, v70, v73
	ds_read_b64_tr_b16 v[72:73], v182 offset:4608
	ds_read_b64_tr_b16 v[70:71], v182
	ds_read_b64_tr_b16 v[78:79], v182 offset:32
	ds_read_b64_tr_b16 v[80:81], v182 offset:4640
	v_cvt_pk_bf16_f32 v6, v6, v7
	v_cvt_pk_bf16_f32 v7, v68, v69
	s_waitcnt lgkmcnt(4)
; #define LAS __attribute__((address_space(3)))
; #define MFMA16(a, b, c) __builtin_amdgcn_mfma_f32_16x16x32_bf16((a), (b), (c), 0, 0, 0)
; __device__ __forceinline__ s16x4 trread(const LAS unsigned char* p) { return __builtin_bit_cast(s16x4, __builtin_amdgcn_ds_read_tr16_b64_v4i16((LAS s16x4*)p)); }
; __device__ __forceinline__ bf16x8 cat8(s16x4 lo, s16x4 hi) { return (bf16x8){lo[0], lo[1], lo[2], lo[3], hi[0], hi[1], hi[2], hi[3]}; }
; __device__ __forceinline__ void mem_attn(const Params& P, int l, LAS unsigned char* lds, int item, int tid) {
;     ...
;         lsa += __shfl_xor(lsa, 16); lsa += __shfl_xor(lsa, 32); lsb += __shfl_xor(lsb, 16); lsb += __shfl_xor(lsb, 32);
;         f32x4 oa[8], ob[8];
; #pragma unroll
;         for (int et = 0; et < 8; ++et) { oa[et] = (f32x4){0.f, 0.f, 0.f, 0.f}; ob[et] = (f32x4){0.f, 0.f, 0.f, 0.f}; }
; #pragma unroll
;         for (int s = 0; s < 8; ++s) { const LAS unsigned char* vp = VS + (32 * s + quad * 4 + (i >> 2)) * 288 + (4 * (i & 3)) * 2;
; #pragma unroll
;             for (int et = 0; et < 8; ++et) { const bf16x8 va = cat8(trread(vp + et * 32), trread(vp + et * 32 + 16 * 288)); oa[et] = MFMA16(va, pa[s], oa[et]); ob[et] = MFMA16(va, pbb[s], ob[et]); }
;             __builtin_amdgcn_sched_barrier(0); }
	v_add_f32_e32 v66, v74, v66
	ds_bpermute_b32 v68, v179, v75
	ds_bpermute_b32 v67, v180, v66
	ds_read_b64_tr_b16 v[86:87], v182 offset:64
	ds_read_b64_tr_b16 v[88:89], v182 offset:4672
	ds_read_b64_tr_b16 v[94:95], v182 offset:96
	ds_read_b64_tr_b16 v[96:97], v182 offset:4704
	ds_read_b64_tr_b16 v[102:103], v182 offset:128
	ds_read_b64_tr_b16 v[104:105], v182 offset:4736
	ds_read_b64_tr_b16 v[110:111], v182 offset:160
	ds_read_b64_tr_b16 v[112:113], v182 offset:4768
	ds_read_b64_tr_b16 v[118:119], v182 offset:192
	ds_read_b64_tr_b16 v[120:121], v182 offset:4800
	ds_read_b64_tr_b16 v[144:145], v182 offset:224
	ds_read_b64_tr_b16 v[146:147], v182 offset:4832
	v_cvt_pk_bf16_f32 v65, v60, v61
	v_cvt_pk_bf16_f32 v60, v150, v151
	v_cvt_pk_bf16_f32 v61, v152, v153
	v_cvt_pk_bf16_f32 v55, v55, v57
	v_cvt_pk_bf16_f32 v57, v122, v123
	s_waitcnt lgkmcnt(13)
	v_add_f32_e32 v123, v75, v68
	v_cvt_pk_bf16_f32 v47, v47, v49
	v_cvt_pk_bf16_f32 v49, v114, v115
	v_cvt_pk_bf16_f32 v39, v39, v41
	v_cvt_pk_bf16_f32 v41, v106, v107
	v_cvt_pk_bf16_f32 v31, v31, v33
	v_cvt_pk_bf16_f32 v33, v98, v99
	v_cvt_pk_bf16_f32 v23, v23, v25
	v_cvt_pk_bf16_f32 v25, v90, v91
	v_cvt_pk_bf16_f32 v15, v15, v17
	v_cvt_pk_bf16_f32 v17, v82, v83
	ds_bpermute_b32 v124, v180, v123
	s_waitcnt lgkmcnt(13)
	v_add_f32_e32 v122, v66, v67
	v_mfma_f32_16x16x32_bf16 v[66:69], v[70:73], v[62:65], 0
	v_mfma_f32_16x16x32_bf16 v[70:73], v[70:73], v[58:61], 0
	v_mfma_f32_16x16x32_bf16 v[74:77], v[78:81], v[62:65], 0
	v_mfma_f32_16x16x32_bf16 v[78:81], v[78:81], v[58:61], 0
	s_waitcnt lgkmcnt(11)
	v_mfma_f32_16x16x32_bf16 v[82:85], v[86:89], v[62:65], 0
	v_mfma_f32_16x16x32_bf16 v[86:89], v[86:89], v[58:61], 0
	s_waitcnt lgkmcnt(9)
	v_mfma_f32_16x16x32_bf16 v[90:93], v[94:97], v[62:65], 0
	v_mfma_f32_16x16x32_bf16 v[94:97], v[94:97], v[58:61], 0
	s_waitcnt lgkmcnt(7)
	v_mfma_f32_16x16x32_bf16 v[98:101], v[102:105], v[62:65], 0
	v_mfma_f32_16x16x32_bf16 v[102:105], v[102:105], v[58:61], 0
	s_waitcnt lgkmcnt(5)
	v_mfma_f32_16x16x32_bf16 v[106:109], v[110:113], v[62:65], 0
	v_mfma_f32_16x16x32_bf16 v[110:113], v[110:113], v[58:61], 0
	s_waitcnt lgkmcnt(3)
	v_mfma_f32_16x16x32_bf16 v[114:117], v[118:121], v[62:65], 0
	v_mfma_f32_16x16x32_bf16 v[118:121], v[118:121], v[58:61], 0
	s_waitcnt lgkmcnt(1)
	v_mfma_f32_16x16x32_bf16 v[62:65], v[144:147], v[62:65], 0
	v_mfma_f32_16x16x32_bf16 v[58:61], v[144:147], v[58:61], 0
	ds_read_b64_tr_b16 v[146:147], v182 offset:13824
	ds_read_b64_tr_b16 v[144:145], v182 offset:9216
	ds_read_b64_tr_b16 v[148:149], v182 offset:9248
	ds_read_b64_tr_b16 v[150:151], v182 offset:13856
	s_waitcnt lgkmcnt(2)
	v_mfma_f32_16x16x32_bf16 v[66:69], v[144:147], v[50:53], v[66:69]
	v_mfma_f32_16x16x32_bf16 v[70:73], v[144:147], v[54:57], v[70:73]
	ds_read_b64_tr_b16 v[144:145], v182 offset:9280
	ds_read_b64_tr_b16 v[146:147], v182 offset:13888
	s_waitcnt lgkmcnt(0)
	v_mfma_f32_16x16x32_bf16 v[82:85], v[144:147], v[50:53], v[82:85]
	v_mfma_f32_16x16x32_bf16 v[86:89], v[144:147], v[54:57], v[86:89]
	ds_read_b64_tr_b16 v[144:145], v182 offset:9312
	ds_read_b64_tr_b16 v[146:147], v182 offset:13920
	s_waitcnt lgkmcnt(0)
	v_mfma_f32_16x16x32_bf16 v[90:93], v[144:147], v[50:53], v[90:93]
	v_mfma_f32_16x16x32_bf16 v[94:97], v[144:147], v[54:57], v[94:97]
	ds_read_b64_tr_b16 v[144:145], v182 offset:9344
	ds_read_b64_tr_b16 v[146:147], v182 offset:13952
	s_waitcnt lgkmcnt(0)
	v_mfma_f32_16x16x32_bf16 v[98:101], v[144:147], v[50:53], v[98:101]
	v_mfma_f32_16x16x32_bf16 v[102:105], v[144:147], v[54:57], v[102:105]
	ds_read_b64_tr_b16 v[144:145], v182 offset:9376
	ds_read_b64_tr_b16 v[146:147], v182 offset:13984
	s_waitcnt lgkmcnt(0)
	v_mfma_f32_16x16x32_bf16 v[106:109], v[144:147], v[50:53], v[106:109]
	v_mfma_f32_16x16x32_bf16 v[110:113], v[144:147], v[54:57], v[110:113]
	ds_read_b64_tr_b16 v[144:145], v182 offset:9408
	ds_read_b64_tr_b16 v[146:147], v182 offset:14016
	s_waitcnt lgkmcnt(0)
	v_mfma_f32_16x16x32_bf16 v[114:117], v[144:147], v[50:53], v[114:117]
	v_mfma_f32_16x16x32_bf16 v[118:121], v[144:147], v[54:57], v[118:121]
	ds_read_b64_tr_b16 v[144:145], v182 offset:9440
	ds_read_b64_tr_b16 v[146:147], v182 offset:14048
	v_mfma_f32_16x16x32_bf16 v[74:77], v[148:151], v[50:53], v[74:77]
	v_mfma_f32_16x16x32_bf16 v[78:81], v[148:151], v[54:57], v[78:81]
	s_waitcnt lgkmcnt(0)
	v_mfma_f32_16x16x32_bf16 v[50:53], v[144:147], v[50:53], v[62:65]
	v_mfma_f32_16x16x32_bf16 v[54:57], v[144:147], v[54:57], v[58:61]
	s_nop 2
	ds_read_b64_tr_b16 v[60:61], v182 offset:23040
	ds_read_b64_tr_b16 v[58:59], v182 offset:18432
	ds_read_b64_tr_b16 v[62:63], v182 offset:18464
	ds_read_b64_tr_b16 v[64:65], v182 offset:23072
	s_waitcnt lgkmcnt(2)
	v_mfma_f32_16x16x32_bf16 v[66:69], v[58:61], v[42:45], v[66:69]
	v_mfma_f32_16x16x32_bf16 v[58:61], v[58:61], v[46:49], v[70:73]
	s_waitcnt lgkmcnt(0)
	v_mfma_f32_16x16x32_bf16 v[70:73], v[62:65], v[42:45], v[74:77]
	s_nop 2
	ds_read_b64_tr_b16 v[74:75], v182 offset:18496
	ds_read_b64_tr_b16 v[76:77], v182 offset:23104
	v_mfma_f32_16x16x32_bf16 v[62:65], v[62:65], v[46:49], v[78:81]
	s_waitcnt lgkmcnt(0)
	v_mfma_f32_16x16x32_bf16 v[78:81], v[74:77], v[42:45], v[82:85]
	s_nop 2
	ds_read_b64_tr_b16 v[82:83], v182 offset:18528
	ds_read_b64_tr_b16 v[84:85], v182 offset:23136
	v_mfma_f32_16x16x32_bf16 v[74:77], v[74:77], v[46:49], v[86:89]
	s_waitcnt lgkmcnt(0)
	v_mfma_f32_16x16x32_bf16 v[86:89], v[82:85], v[42:45], v[90:93]
	s_nop 2
	ds_read_b64_tr_b16 v[90:91], v182 offset:18560
	ds_read_b64_tr_b16 v[92:93], v182 offset:23168
	v_mfma_f32_16x16x32_bf16 v[82:85], v[82:85], v[46:49], v[94:97]
	s_waitcnt lgkmcnt(0)
; #define LAS __attribute__((address_space(3)))
; #define MFMA16(a, b, c) __builtin_amdgcn_mfma_f32_16x16x32_bf16((a), (b), (c), 0, 0, 0)
; __device__ __forceinline__ s16x4 trread(const LAS unsigned char* p) { return __builtin_bit_cast(s16x4, __builtin_amdgcn_ds_read_tr16_b64_v4i16((LAS s16x4*)p)); }
; __device__ __forceinline__ bf16x8 cat8(s16x4 lo, s16x4 hi) { return (bf16x8){lo[0], lo[1], lo[2], lo[3], hi[0], hi[1], hi[2], hi[3]}; }
; __device__ __forceinline__ void mem_attn(const Params& P, int l, LAS unsigned char* lds, int item, int tid) {
;     ...
;         for (int s = 0; s < 8; ++s) { const LAS unsigned char* vp = VS + (32 * s + quad * 4 + (i >> 2)) * 288 + (4 * (i & 3)) * 2;
; #pragma unroll
;             for (int et = 0; et < 8; ++et) { const bf16x8 va = cat8(trread(vp + et * 32), trread(vp + et * 32 + 16 * 288)); oa[et] = MFMA16(va, pa[s], oa[et]); ob[et] = MFMA16(va, pbb[s], ob[et]); }
;             __builtin_amdgcn_sched_barrier(0); }
	v_mfma_f32_16x16x32_bf16 v[94:97], v[90:93], v[42:45], v[98:101]
	s_nop 2
	ds_read_b64_tr_b16 v[98:99], v182 offset:18592
	ds_read_b64_tr_b16 v[100:101], v182 offset:23200
	v_mfma_f32_16x16x32_bf16 v[90:93], v[90:93], v[46:49], v[102:105]
	s_waitcnt lgkmcnt(0)
	v_mfma_f32_16x16x32_bf16 v[102:105], v[98:101], v[42:45], v[106:109]
	s_nop 2
	ds_read_b64_tr_b16 v[106:107], v182 offset:18624
	ds_read_b64_tr_b16 v[108:109], v182 offset:23232
	v_mfma_f32_16x16x32_bf16 v[98:101], v[98:101], v[46:49], v[110:113]
	s_waitcnt lgkmcnt(0)
	v_mfma_f32_16x16x32_bf16 v[110:113], v[106:109], v[42:45], v[114:117]
	s_nop 2
	ds_read_b64_tr_b16 v[114:115], v182 offset:18656
	ds_read_b64_tr_b16 v[116:117], v182 offset:23264
	v_mfma_f32_16x16x32_bf16 v[106:109], v[106:109], v[46:49], v[118:121]
	s_waitcnt lgkmcnt(0)
	v_mfma_f32_16x16x32_bf16 v[42:45], v[114:117], v[42:45], v[50:53]
	v_mfma_f32_16x16x32_bf16 v[46:49], v[114:117], v[46:49], v[54:57]
	s_nop 1
	ds_read_b64_tr_b16 v[52:53], v182 offset:32256
	ds_read_b64_tr_b16 v[50:51], v182 offset:27648
	ds_read_b64_tr_b16 v[54:55], v182 offset:27680
	ds_read_b64_tr_b16 v[56:57], v182 offset:32288
	s_waitcnt lgkmcnt(2)
	v_mfma_f32_16x16x32_bf16 v[66:69], v[50:53], v[34:37], v[66:69]
	v_mfma_f32_16x16x32_bf16 v[50:53], v[50:53], v[38:41], v[58:61]
	s_waitcnt lgkmcnt(0)
	v_mfma_f32_16x16x32_bf16 v[58:61], v[54:57], v[34:37], v[70:73]
	v_mfma_f32_16x16x32_bf16 v[54:57], v[54:57], v[38:41], v[62:65]
	s_nop 2
	ds_read_b64_tr_b16 v[62:63], v182 offset:27712
	ds_read_b64_tr_b16 v[64:65], v182 offset:32320
	s_waitcnt lgkmcnt(0)
	v_mfma_f32_16x16x32_bf16 v[70:73], v[62:65], v[34:37], v[78:81]
	v_mfma_f32_16x16x32_bf16 v[62:65], v[62:65], v[38:41], v[74:77]
	s_nop 2
	ds_read_b64_tr_b16 v[74:75], v182 offset:27744
	ds_read_b64_tr_b16 v[76:77], v182 offset:32352
	s_waitcnt lgkmcnt(0)
	v_mfma_f32_16x16x32_bf16 v[78:81], v[74:77], v[34:37], v[86:89]
	v_mfma_f32_16x16x32_bf16 v[74:77], v[74:77], v[38:41], v[82:85]
	s_nop 2
	ds_read_b64_tr_b16 v[82:83], v182 offset:27776
	ds_read_b64_tr_b16 v[84:85], v182 offset:32384
	s_waitcnt lgkmcnt(0)
	v_mfma_f32_16x16x32_bf16 v[86:89], v[82:85], v[34:37], v[94:97]
	v_mfma_f32_16x16x32_bf16 v[82:85], v[82:85], v[38:41], v[90:93]
	s_nop 2
	ds_read_b64_tr_b16 v[90:91], v182 offset:27808
	ds_read_b64_tr_b16 v[92:93], v182 offset:32416
	s_waitcnt lgkmcnt(0)
	v_mfma_f32_16x16x32_bf16 v[94:97], v[90:93], v[34:37], v[102:105]
	v_mfma_f32_16x16x32_bf16 v[90:93], v[90:93], v[38:41], v[98:101]
	s_nop 2
	ds_read_b64_tr_b16 v[98:99], v182 offset:27840
	ds_read_b64_tr_b16 v[100:101], v182 offset:32448
	s_waitcnt lgkmcnt(0)
	v_mfma_f32_16x16x32_bf16 v[102:105], v[98:101], v[34:37], v[110:113]
	v_mfma_f32_16x16x32_bf16 v[98:101], v[98:101], v[38:41], v[106:109]
	s_nop 2
	ds_read_b64_tr_b16 v[106:107], v182 offset:27872
	ds_read_b64_tr_b16 v[108:109], v182 offset:32480
	s_waitcnt lgkmcnt(0)
	v_mfma_f32_16x16x32_bf16 v[34:37], v[106:109], v[34:37], v[42:45]
	v_mfma_f32_16x16x32_bf16 v[38:41], v[106:109], v[38:41], v[46:49]
	s_nop 1
	ds_read_b64_tr_b16 v[44:45], v182 offset:41472
	ds_read_b64_tr_b16 v[42:43], v182 offset:36864
	ds_read_b64_tr_b16 v[46:47], v182 offset:36896
	ds_read_b64_tr_b16 v[48:49], v182 offset:41504
	s_waitcnt lgkmcnt(2)
	v_mfma_f32_16x16x32_bf16 v[66:69], v[42:45], v[26:29], v[66:69]
	v_mfma_f32_16x16x32_bf16 v[42:45], v[42:45], v[30:33], v[50:53]
	s_waitcnt lgkmcnt(0)
	v_mfma_f32_16x16x32_bf16 v[50:53], v[46:49], v[26:29], v[58:61]
	v_mfma_f32_16x16x32_bf16 v[46:49], v[46:49], v[30:33], v[54:57]
	s_nop 2
	ds_read_b64_tr_b16 v[54:55], v182 offset:36928
	ds_read_b64_tr_b16 v[56:57], v182 offset:41536
	s_waitcnt lgkmcnt(0)
	v_mfma_f32_16x16x32_bf16 v[58:61], v[54:57], v[26:29], v[70:73]
	v_mfma_f32_16x16x32_bf16 v[54:57], v[54:57], v[30:33], v[62:65]
	s_nop 2
	ds_read_b64_tr_b16 v[62:63], v182 offset:36960
	ds_read_b64_tr_b16 v[64:65], v182 offset:41568
	s_waitcnt lgkmcnt(0)
	v_mfma_f32_16x16x32_bf16 v[70:73], v[62:65], v[26:29], v[78:81]
	v_mfma_f32_16x16x32_bf16 v[62:65], v[62:65], v[30:33], v[74:77]
	s_nop 2
	ds_read_b64_tr_b16 v[74:75], v182 offset:36992
	ds_read_b64_tr_b16 v[76:77], v182 offset:41600
	s_waitcnt lgkmcnt(0)
	v_mfma_f32_16x16x32_bf16 v[78:81], v[74:77], v[26:29], v[86:89]
	v_mfma_f32_16x16x32_bf16 v[74:77], v[74:77], v[30:33], v[82:85]
	s_nop 2
	ds_read_b64_tr_b16 v[82:83], v182 offset:37024
	ds_read_b64_tr_b16 v[84:85], v182 offset:41632
	s_waitcnt lgkmcnt(0)
	v_mfma_f32_16x16x32_bf16 v[86:89], v[82:85], v[26:29], v[94:97]
	v_mfma_f32_16x16x32_bf16 v[82:85], v[82:85], v[30:33], v[90:93]
	s_nop 2
	ds_read_b64_tr_b16 v[90:91], v182 offset:37056
	ds_read_b64_tr_b16 v[92:93], v182 offset:41664
	s_waitcnt lgkmcnt(0)
	v_mfma_f32_16x16x32_bf16 v[94:97], v[90:93], v[26:29], v[102:105]
	v_mfma_f32_16x16x32_bf16 v[90:93], v[90:93], v[30:33], v[98:101]
	s_nop 2
	ds_read_b64_tr_b16 v[98:99], v182 offset:37088
	ds_read_b64_tr_b16 v[100:101], v182 offset:41696
	s_waitcnt lgkmcnt(0)
	v_mfma_f32_16x16x32_bf16 v[26:29], v[98:101], v[26:29], v[34:37]
	v_mfma_f32_16x16x32_bf16 v[30:33], v[98:101], v[30:33], v[38:41]
	s_nop 1
	ds_read_b64_tr_b16 v[36:37], v182 offset:50688
	ds_read_b64_tr_b16 v[34:35], v182 offset:46080
	ds_read_b64_tr_b16 v[38:39], v182 offset:46112
	ds_read_b64_tr_b16 v[40:41], v182 offset:50720
	s_waitcnt lgkmcnt(2)
	v_mfma_f32_16x16x32_bf16 v[66:69], v[34:37], v[18:21], v[66:69]
	v_mfma_f32_16x16x32_bf16 v[34:37], v[34:37], v[22:25], v[42:45]
	s_waitcnt lgkmcnt(0)
	v_mfma_f32_16x16x32_bf16 v[42:45], v[38:41], v[18:21], v[50:53]
	v_mfma_f32_16x16x32_bf16 v[38:41], v[38:41], v[22:25], v[46:49]
	s_nop 2
	ds_read_b64_tr_b16 v[46:47], v182 offset:46144
	ds_read_b64_tr_b16 v[48:49], v182 offset:50752
	s_waitcnt lgkmcnt(0)
; #define LAS __attribute__((address_space(3)))
; #define MFMA16(a, b, c) __builtin_amdgcn_mfma_f32_16x16x32_bf16((a), (b), (c), 0, 0, 0)
; __device__ __forceinline__ s16x4 trread(const LAS unsigned char* p) { return __builtin_bit_cast(s16x4, __builtin_amdgcn_ds_read_tr16_b64_v4i16((LAS s16x4*)p)); }
; __device__ __forceinline__ bf16x8 cat8(s16x4 lo, s16x4 hi) { return (bf16x8){lo[0], lo[1], lo[2], lo[3], hi[0], hi[1], hi[2], hi[3]}; }
; __device__ __forceinline__ void mem_attn(const Params& P, int l, LAS unsigned char* lds, int item, int tid) {
;     ...
;         for (int s = 0; s < 8; ++s) { const LAS unsigned char* vp = VS + (32 * s + quad * 4 + (i >> 2)) * 288 + (4 * (i & 3)) * 2;
; #pragma unroll
;             for (int et = 0; et < 8; ++et) { const bf16x8 va = cat8(trread(vp + et * 32), trread(vp + et * 32 + 16 * 288)); oa[et] = MFMA16(va, pa[s], oa[et]); ob[et] = MFMA16(va, pbb[s], ob[et]); }
;             __builtin_amdgcn_sched_barrier(0); }
	v_mfma_f32_16x16x32_bf16 v[50:53], v[46:49], v[18:21], v[58:61]
	v_mfma_f32_16x16x32_bf16 v[46:49], v[46:49], v[22:25], v[54:57]
	s_nop 2
	ds_read_b64_tr_b16 v[54:55], v182 offset:46176
	ds_read_b64_tr_b16 v[56:57], v182 offset:50784
	s_waitcnt lgkmcnt(0)
	v_mfma_f32_16x16x32_bf16 v[58:61], v[54:57], v[18:21], v[70:73]
	v_mfma_f32_16x16x32_bf16 v[54:57], v[54:57], v[22:25], v[62:65]
	s_nop 2
	ds_read_b64_tr_b16 v[62:63], v182 offset:46208
	ds_read_b64_tr_b16 v[64:65], v182 offset:50816
	s_waitcnt lgkmcnt(0)
	v_mfma_f32_16x16x32_bf16 v[70:73], v[62:65], v[18:21], v[78:81]
	v_mfma_f32_16x16x32_bf16 v[62:65], v[62:65], v[22:25], v[74:77]
	s_nop 2
	ds_read_b64_tr_b16 v[74:75], v182 offset:46240
	ds_read_b64_tr_b16 v[76:77], v182 offset:50848
	s_waitcnt lgkmcnt(0)
	v_mfma_f32_16x16x32_bf16 v[78:81], v[74:77], v[18:21], v[86:89]
	v_mfma_f32_16x16x32_bf16 v[74:77], v[74:77], v[22:25], v[82:85]
	s_nop 2
	ds_read_b64_tr_b16 v[82:83], v182 offset:46272
	ds_read_b64_tr_b16 v[84:85], v182 offset:50880
	s_waitcnt lgkmcnt(0)
	v_mfma_f32_16x16x32_bf16 v[86:89], v[82:85], v[18:21], v[94:97]
	v_mfma_f32_16x16x32_bf16 v[82:85], v[82:85], v[22:25], v[90:93]
	s_nop 2
	ds_read_b64_tr_b16 v[90:91], v182 offset:46304
	ds_read_b64_tr_b16 v[92:93], v182 offset:50912
	s_waitcnt lgkmcnt(0)
	v_mfma_f32_16x16x32_bf16 v[18:21], v[90:93], v[18:21], v[26:29]
	v_mfma_f32_16x16x32_bf16 v[22:25], v[90:93], v[22:25], v[30:33]
	s_nop 1
	ds_read_b64_tr_b16 v[28:29], v182 offset:59904
	ds_read_b64_tr_b16 v[26:27], v182 offset:55296
	ds_read_b64_tr_b16 v[30:31], v182 offset:55328
	ds_read_b64_tr_b16 v[32:33], v182 offset:59936
	s_waitcnt lgkmcnt(2)
	v_mfma_f32_16x16x32_bf16 v[66:69], v[26:29], v[10:13], v[66:69]
	v_mfma_f32_16x16x32_bf16 v[26:29], v[26:29], v[14:17], v[34:37]
	s_waitcnt lgkmcnt(0)
	v_mfma_f32_16x16x32_bf16 v[34:37], v[30:33], v[10:13], v[42:45]
	v_mfma_f32_16x16x32_bf16 v[30:33], v[30:33], v[14:17], v[38:41]
	s_nop 2
	ds_read_b64_tr_b16 v[38:39], v182 offset:55360
	ds_read_b64_tr_b16 v[40:41], v182 offset:59968
	s_waitcnt lgkmcnt(0)
	v_mfma_f32_16x16x32_bf16 v[42:45], v[38:41], v[10:13], v[50:53]
	v_mfma_f32_16x16x32_bf16 v[38:41], v[38:41], v[14:17], v[46:49]
	s_nop 2
	ds_read_b64_tr_b16 v[46:47], v182 offset:55392
	ds_read_b64_tr_b16 v[48:49], v182 offset:60000
	ds_read_b64_tr_b16 v[50:51], v182 offset:55424
	ds_read_b64_tr_b16 v[52:53], v182 offset:60032
	s_waitcnt lgkmcnt(0)
	v_mfma_f32_16x16x32_bf16 v[70:73], v[50:53], v[10:13], v[70:73]
	v_mfma_f32_16x16x32_bf16 v[90:93], v[50:53], v[14:17], v[62:65]
	ds_read_b64_tr_b16 v[50:51], v182 offset:55456
	ds_read_b64_tr_b16 v[52:53], v182 offset:60064
	s_waitcnt lgkmcnt(0)
	v_mfma_f32_16x16x32_bf16 v[78:81], v[50:53], v[10:13], v[78:81]
	v_mfma_f32_16x16x32_bf16 v[74:77], v[50:53], v[14:17], v[74:77]
	ds_read_b64_tr_b16 v[50:51], v182 offset:55488
	ds_read_b64_tr_b16 v[52:53], v182 offset:60096
	s_waitcnt lgkmcnt(0)
	v_mfma_f32_16x16x32_bf16 v[86:89], v[50:53], v[10:13], v[86:89]
	v_mfma_f32_16x16x32_bf16 v[82:85], v[50:53], v[14:17], v[82:85]
	ds_read_b64_tr_b16 v[50:51], v182 offset:55520
	ds_read_b64_tr_b16 v[52:53], v182 offset:60128
	v_mfma_f32_16x16x32_bf16 v[58:61], v[46:49], v[10:13], v[58:61]
	v_mfma_f32_16x16x32_bf16 v[46:49], v[46:49], v[14:17], v[54:57]
	s_waitcnt lgkmcnt(0)
	v_mfma_f32_16x16x32_bf16 v[94:97], v[50:53], v[10:13], v[18:21]
	v_mfma_f32_16x16x32_bf16 v[98:101], v[50:53], v[14:17], v[22:25]
	ds_read_b64_tr_b16 v[12:13], v183
	ds_read_b64_tr_b16 v[10:11], v182 offset:64512
	ds_read_b64_tr_b16 v[14:15], v182 offset:64544
	ds_read_b64_tr_b16 v[16:17], v184
	s_waitcnt lgkmcnt(2)
	v_mfma_f32_16x16x32_bf16 v[62:65], v[10:13], v[2:5], v[66:69]
	v_mfma_f32_16x16x32_bf16 v[50:53], v[10:13], v[6:9], v[26:29]
	ds_read_b64_tr_b16 v[10:11], v182 offset:64576
	ds_read_b64_tr_b16 v[12:13], v185
	s_waitcnt lgkmcnt(0)
	v_mfma_f32_16x16x32_bf16 v[42:45], v[10:13], v[2:5], v[42:45]
	v_mfma_f32_16x16x32_bf16 v[22:25], v[10:13], v[6:9], v[38:41]
	ds_read_b64_tr_b16 v[10:11], v182 offset:64608
	ds_read_b64_tr_b16 v[12:13], v186
	s_waitcnt lgkmcnt(0)
	v_mfma_f32_16x16x32_bf16 v[66:69], v[10:13], v[2:5], v[58:61]
	v_mfma_f32_16x16x32_bf16 v[54:57], v[10:13], v[6:9], v[46:49]
	ds_read_b64_tr_b16 v[10:11], v182 offset:64640
	ds_read_b64_tr_b16 v[12:13], v187
	v_mfma_f32_16x16x32_bf16 v[34:37], v[14:17], v[2:5], v[34:37]
	v_mfma_f32_16x16x32_bf16 v[14:17], v[14:17], v[6:9], v[30:33]
	s_waitcnt lgkmcnt(0)
	v_mfma_f32_16x16x32_bf16 v[46:49], v[10:13], v[2:5], v[70:73]
	v_mfma_f32_16x16x32_bf16 v[30:33], v[10:13], v[6:9], v[90:93]
	ds_read_b64_tr_b16 v[10:11], v182 offset:64672
	ds_read_b64_tr_b16 v[12:13], v188
	s_waitcnt lgkmcnt(0)
	v_mfma_f32_16x16x32_bf16 v[38:41], v[10:13], v[2:5], v[78:81]
	v_mfma_f32_16x16x32_bf16 v[18:21], v[10:13], v[6:9], v[74:77]
	ds_read_b64_tr_b16 v[10:11], v182 offset:64704
	ds_read_b64_tr_b16 v[12:13], v189
	ds_read_b64_tr_b16 v[70:71], v182 offset:64736
	ds_read_b64_tr_b16 v[72:73], v190
	s_waitcnt lgkmcnt(2)
	v_mfma_f32_16x16x32_bf16 v[26:29], v[10:13], v[2:5], v[86:89]
	v_mfma_f32_16x16x32_bf16 v[10:13], v[10:13], v[6:9], v[82:85]
	s_waitcnt lgkmcnt(0)
; __device__ __forceinline__ float bf_lo(unsigned u) { return __uint_as_float(u << 16); }
; __device__ __forceinline__ float bf_hi(unsigned u) { return __uint_as_float(u & 0xffff0000u); }
; __device__ __forceinline__ unsigned pk2(float lo, float hi) { const f32x2c_t v = {lo, hi}; return __builtin_bit_cast(unsigned, __builtin_convertvector(v, bf16x2c_t)); }
; __device__ __forceinline__ void mem_attn(const Params& P, int l, LAS unsigned char* lds, int item, int tid) {
;     ...
;         const float rla = 1.0f / lsa, rlb = 1.0f / lsb;
; #pragma unroll
;         for (int et = 0; et < 8; ++et) { const int e = et * 16 + quad * 4;
;             const v2u g0 = *(const v2u*)(z + tt0 * ZP + ZC_MG + h * 128 + e), g1 = *(const v2u*)(z + tt1 * ZP + ZC_MG + h * 128 + e);
;             v2u o; o.x = pk2(oa[et][0] * rla * bf_lo(g0.x), oa[et][1] * rla * bf_hi(g0.x)); o.y = pk2(oa[et][2] * rla * bf_lo(g0.y), oa[et][3] * rla * bf_hi(g0.y));
;             *(v2u*)(mix + tt0 * 2048 + 1536 + h * 128 + e) = o;
;             v2u o2; o2.x = pk2(ob[et][0] * rlb * bf_lo(g1.x), ob[et][1] * rlb * bf_hi(g1.x)); o2.y = pk2(ob[et][2] * rlb * bf_lo(g1.y), ob[et][3] * rlb * bf_hi(g1.y));
;             *(v2u*)(mix + tt1 * 2048 + 1536 + h * 128 + e) = o2; }
	v_mfma_f32_16x16x32_bf16 v[58:61], v[70:73], v[2:5], v[94:97]
	v_mfma_f32_16x16x32_bf16 v[2:5], v[70:73], v[6:9], v[98:101]
	v_div_scale_f32 v6, s[8:9], v122, v122, 1.0
	v_rcp_f32_e32 v8, v6
	v_add_f32_e32 v7, v123, v124
	v_mov_b32_e32 v173, v1
	v_lshl_add_u64 v[74:75], v[176:177], 0, v[172:173]
	v_fma_f32 v9, -v6, v8, 1.0
	v_fmac_f32_e32 v8, v9, v8
	v_div_scale_f32 v9, vcc, 1.0, v122, 1.0
	v_mul_f32_e32 v70, v9, v8
	v_fma_f32 v71, -v6, v70, v9
	v_fmac_f32_e32 v70, v71, v8
	v_fma_f32 v6, -v6, v70, v9
	v_div_fmas_f32 v6, v6, v8, v70
	v_div_scale_f32 v8, s[8:9], v7, v7, 1.0
	v_rcp_f32_e32 v9, v8
	s_mov_b64 s[8:9], 0x2c00
	v_lshl_add_u64 v[76:77], v[74:75], 0, s[8:9]
	s_mov_b64 s[8:9], 0x62c00
	v_fma_f32 v70, -v8, v9, 1.0
	v_fmac_f32_e32 v9, v70, v9
	v_div_scale_f32 v70, vcc, 1.0, v7, 1.0
	v_mul_f32_e32 v71, v70, v9
	v_fma_f32 v72, -v8, v71, v70
	v_fmac_f32_e32 v71, v72, v9
	v_fma_f32 v8, -v8, v71, v70
	v_div_fmas_f32 v8, v8, v9, v71
	v_add_co_u32_e32 v78, vcc, s42, v74
	s_mov_b32 s7, 0x62000
	s_nop 0
	v_addc_co_u32_e32 v79, vcc, 0, v75, vcc
	global_load_dwordx2 v[192:193], v[78:79], off offset:3072
	v_lshl_add_u64 v[80:81], v[74:75], 0, s[8:9]
	v_add_co_u32_e32 v74, vcc, s7, v74
	v_div_fixup_f32 v6, v6, v122, 1.0
	s_nop 0
	v_addc_co_u32_e32 v75, vcc, 0, v75, vcc
	global_load_dwordx2 v[194:195], v[74:75], off offset:3072
	global_load_dwordx2 v[196:197], v[76:77], off offset:32
	global_load_dwordx2 v[198:199], v[80:81], off offset:32
	global_load_dwordx2 v[200:201], v[76:77], off offset:64
	global_load_dwordx2 v[202:203], v[80:81], off offset:64
	global_load_dwordx2 v[204:205], v[76:77], off offset:96
	global_load_dwordx2 v[206:207], v[80:81], off offset:96
	global_load_dwordx2 v[208:209], v[76:77], off offset:128
	global_load_dwordx2 v[210:211], v[80:81], off offset:128
	global_load_dwordx2 v[212:213], v[76:77], off offset:160
	global_load_dwordx2 v[214:215], v[80:81], off offset:160
	global_load_dwordx2 v[216:217], v[76:77], off offset:192
	global_load_dwordx2 v[218:219], v[80:81], off offset:192
	global_load_dwordx2 v[220:221], v[76:77], off offset:224
	global_load_dwordx2 v[222:223], v[80:81], off offset:224
	v_pk_mul_f32 v[62:63], v[6:7], v[62:63] op_sel_hi:[0,1]
	v_pk_mul_f32 v[64:65], v[6:7], v[64:65] op_sel_hi:[0,1]
	v_lshlrev_b64 v[70:71], 12, v[174:175]
	v_div_fixup_f32 v8, v8, v7, 1.0
	v_pk_mul_f32 v[50:51], v[8:9], v[50:51] op_sel_hi:[0,1]
	v_pk_mul_f32 v[52:53], v[8:9], v[52:53] op_sel_hi:[0,1]
	v_or_b32_e32 v72, 0x10000, v70
	v_mov_b32_e32 v73, v71
	v_pk_mul_f32 v[34:35], v[6:7], v[34:35] op_sel_hi:[0,1]
	v_pk_mul_f32 v[36:37], v[6:7], v[36:37] op_sel_hi:[0,1]
	v_pk_mul_f32 v[14:15], v[8:9], v[14:15] op_sel_hi:[0,1]
	v_pk_mul_f32 v[16:17], v[8:9], v[16:17] op_sel_hi:[0,1]
	v_pk_mul_f32 v[10:11], v[8:9], v[10:11] op_sel_hi:[0,1]
	v_pk_mul_f32 v[12:13], v[8:9], v[12:13] op_sel_hi:[0,1]
	v_pk_mul_f32 v[2:3], v[8:9], v[2:3] op_sel_hi:[0,1]
	v_pk_mul_f32 v[4:5], v[8:9], v[4:5] op_sel_hi:[0,1]
	s_movk_i32 s7, 0x100
	s_and_b64 vcc, exec, s[0:1]
	s_mov_b64 s[0:1], 0
	s_waitcnt vmcnt(15)
	v_lshlrev_b32_e32 v82, 16, v192
	v_and_b32_e32 v83, 0xffff0000, v192
	v_lshlrev_b32_e32 v78, 16, v193
	v_and_b32_e32 v79, 0xffff0000, v193
	v_pk_mul_f32 v[62:63], v[62:63], v[82:83]
	v_pk_mul_f32 v[64:65], v[64:65], v[78:79]
	v_cvt_pk_bf16_f32 v62, v62, v63
	v_cvt_pk_bf16_f32 v63, v64, v65
	v_lshl_add_u64 v[64:65], v[126:127], 0, v[70:71]
	global_store_dwordx2 v[64:65], v[62:63], off offset:3072
	s_waitcnt vmcnt(15)
	v_lshlrev_b32_e32 v62, 16, v194
	v_and_b32_e32 v63, 0xffff0000, v194
	v_pk_mul_f32 v[50:51], v[50:51], v[62:63]
	v_lshlrev_b32_e32 v62, 16, v195
	v_and_b32_e32 v63, 0xffff0000, v195
	v_pk_mul_f32 v[52:53], v[52:53], v[62:63]
	v_cvt_pk_bf16_f32 v50, v50, v51
	v_cvt_pk_bf16_f32 v51, v52, v53
	v_lshl_add_u64 v[52:53], v[126:127], 0, v[72:73]
	global_store_dwordx2 v[52:53], v[50:51], off offset:3072
	s_nop 0
	s_waitcnt vmcnt(15)
	v_lshlrev_b32_e32 v70, 16, v196
	v_and_b32_e32 v71, 0xffff0000, v196
	v_lshlrev_b32_e32 v50, 16, v197
	v_and_b32_e32 v51, 0xffff0000, v197
	v_pk_mul_f32 v[34:35], v[34:35], v[70:71]
	v_pk_mul_f32 v[36:37], v[36:37], v[50:51]
	v_cvt_pk_bf16_f32 v34, v34, v35
	v_cvt_pk_bf16_f32 v35, v36, v37
	global_store_dwordx2 v[64:65], v[34:35], off offset:3104
	s_waitcnt vmcnt(15)
	v_lshlrev_b32_e32 v34, 16, v198
	v_and_b32_e32 v35, 0xffff0000, v198
	v_pk_mul_f32 v[14:15], v[14:15], v[34:35]
	v_lshlrev_b32_e32 v34, 16, v199
	v_and_b32_e32 v35, 0xffff0000, v199
	v_pk_mul_f32 v[16:17], v[16:17], v[34:35]
	v_cvt_pk_bf16_f32 v14, v14, v15
	v_cvt_pk_bf16_f32 v15, v16, v17
	global_store_dwordx2 v[52:53], v[14:15], off offset:3104
	s_nop 0
	v_pk_mul_f32 v[34:35], v[6:7], v[42:43] op_sel_hi:[0,1]
	s_waitcnt vmcnt(15)
	v_lshlrev_b32_e32 v36, 16, v200
	v_and_b32_e32 v37, 0xffff0000, v200
	v_pk_mul_f32 v[34:35], v[34:35], v[36:37]
	v_lshlrev_b32_e32 v36, 16, v201
	v_cvt_pk_bf16_f32 v14, v34, v35
	v_pk_mul_f32 v[34:35], v[6:7], v[44:45] op_sel_hi:[0,1]
	v_and_b32_e32 v37, 0xffff0000, v201
	v_pk_mul_f32 v[34:35], v[34:35], v[36:37]
	s_nop 0
	v_cvt_pk_bf16_f32 v15, v34, v35
	global_store_dwordx2 v[64:65], v[14:15], off offset:3136
	v_pk_mul_f32 v[14:15], v[8:9], v[22:23] op_sel_hi:[0,1]
	s_waitcnt vmcnt(15)
; __device__ __forceinline__ float bf_lo(unsigned u) { return __uint_as_float(u << 16); }
; __device__ __forceinline__ float bf_hi(unsigned u) { return __uint_as_float(u & 0xffff0000u); }
; __device__ __forceinline__ unsigned pk2(float lo, float hi) { const f32x2c_t v = {lo, hi}; return __builtin_bit_cast(unsigned, __builtin_convertvector(v, bf16x2c_t)); }
; __device__ __forceinline__ void mem_attn(const Params& P, int l, LAS unsigned char* lds, int item, int tid) {
;     ...
;         const float rla = 1.0f / lsa, rlb = 1.0f / lsb;
; #pragma unroll
;         for (int et = 0; et < 8; ++et) { const int e = et * 16 + quad * 4;
;             const v2u g0 = *(const v2u*)(z + tt0 * ZP + ZC_MG + h * 128 + e), g1 = *(const v2u*)(z + tt1 * ZP + ZC_MG + h * 128 + e);
;             v2u o; o.x = pk2(oa[et][0] * rla * bf_lo(g0.x), oa[et][1] * rla * bf_hi(g0.x)); o.y = pk2(oa[et][2] * rla * bf_lo(g0.y), oa[et][3] * rla * bf_hi(g0.y));
;             *(v2u*)(mix + tt0 * 2048 + 1536 + h * 128 + e) = o;
;             v2u o2; o2.x = pk2(ob[et][0] * rlb * bf_lo(g1.x), ob[et][1] * rlb * bf_hi(g1.x)); o2.y = pk2(ob[et][2] * rlb * bf_lo(g1.y), ob[et][3] * rlb * bf_hi(g1.y));
;             *(v2u*)(mix + tt1 * 2048 + 1536 + h * 128 + e) = o2; }
	v_lshlrev_b32_e32 v22, 16, v202
	v_and_b32_e32 v23, 0xffff0000, v202
	v_pk_mul_f32 v[14:15], v[14:15], v[22:23]
	v_pk_mul_f32 v[22:23], v[8:9], v[24:25] op_sel_hi:[0,1]
	v_lshlrev_b32_e32 v16, 16, v203
	v_and_b32_e32 v17, 0xffff0000, v203
	v_pk_mul_f32 v[16:17], v[22:23], v[16:17]
	v_cvt_pk_bf16_f32 v14, v14, v15
	v_cvt_pk_bf16_f32 v15, v16, v17
	global_store_dwordx2 v[52:53], v[14:15], off offset:3136
	s_nop 0
	v_pk_mul_f32 v[22:23], v[6:7], v[66:67] op_sel_hi:[0,1]
	s_waitcnt vmcnt(15)
	v_lshlrev_b32_e32 v24, 16, v204
	v_and_b32_e32 v25, 0xffff0000, v204
	v_pk_mul_f32 v[22:23], v[22:23], v[24:25]
	v_lshlrev_b32_e32 v24, 16, v205
	v_cvt_pk_bf16_f32 v14, v22, v23
	v_pk_mul_f32 v[22:23], v[6:7], v[68:69] op_sel_hi:[0,1]
	v_and_b32_e32 v25, 0xffff0000, v205
	v_pk_mul_f32 v[22:23], v[22:23], v[24:25]
	s_nop 0
	v_cvt_pk_bf16_f32 v15, v22, v23
	global_store_dwordx2 v[64:65], v[14:15], off offset:3168
	v_pk_mul_f32 v[14:15], v[8:9], v[54:55] op_sel_hi:[0,1]
	s_waitcnt vmcnt(15)
	v_lshlrev_b32_e32 v22, 16, v206
	v_and_b32_e32 v23, 0xffff0000, v206
	v_pk_mul_f32 v[14:15], v[14:15], v[22:23]
	v_pk_mul_f32 v[22:23], v[8:9], v[56:57] op_sel_hi:[0,1]
	v_lshlrev_b32_e32 v16, 16, v207
	v_and_b32_e32 v17, 0xffff0000, v207
	v_pk_mul_f32 v[16:17], v[22:23], v[16:17]
	v_cvt_pk_bf16_f32 v14, v14, v15
	v_cvt_pk_bf16_f32 v15, v16, v17
	global_store_dwordx2 v[52:53], v[14:15], off offset:3168
	s_nop 0
	v_pk_mul_f32 v[22:23], v[6:7], v[46:47] op_sel_hi:[0,1]
	s_waitcnt vmcnt(15)
	v_lshlrev_b32_e32 v24, 16, v208
	v_and_b32_e32 v25, 0xffff0000, v208
	v_pk_mul_f32 v[22:23], v[22:23], v[24:25]
	v_lshlrev_b32_e32 v24, 16, v209
	v_cvt_pk_bf16_f32 v14, v22, v23
	v_pk_mul_f32 v[22:23], v[6:7], v[48:49] op_sel_hi:[0,1]
	v_and_b32_e32 v25, 0xffff0000, v209
	v_pk_mul_f32 v[22:23], v[22:23], v[24:25]
	s_nop 0
	v_cvt_pk_bf16_f32 v15, v22, v23
	global_store_dwordx2 v[64:65], v[14:15], off offset:3200
	v_pk_mul_f32 v[14:15], v[8:9], v[30:31] op_sel_hi:[0,1]
	s_waitcnt vmcnt(15)
	v_lshlrev_b32_e32 v22, 16, v210
	v_and_b32_e32 v23, 0xffff0000, v210
	v_pk_mul_f32 v[14:15], v[14:15], v[22:23]
	v_pk_mul_f32 v[22:23], v[8:9], v[32:33] op_sel_hi:[0,1]
	v_lshlrev_b32_e32 v16, 16, v211
	v_and_b32_e32 v17, 0xffff0000, v211
	v_pk_mul_f32 v[16:17], v[22:23], v[16:17]
	v_cvt_pk_bf16_f32 v14, v14, v15
	v_cvt_pk_bf16_f32 v15, v16, v17
	global_store_dwordx2 v[52:53], v[14:15], off offset:3200
	s_nop 0
	v_pk_mul_f32 v[22:23], v[6:7], v[38:39] op_sel_hi:[0,1]
	s_waitcnt vmcnt(15)
	v_lshlrev_b32_e32 v24, 16, v212
	v_and_b32_e32 v25, 0xffff0000, v212
	v_pk_mul_f32 v[22:23], v[22:23], v[24:25]
	v_lshlrev_b32_e32 v24, 16, v213
	v_cvt_pk_bf16_f32 v14, v22, v23
	v_pk_mul_f32 v[22:23], v[6:7], v[40:41] op_sel_hi:[0,1]
	v_and_b32_e32 v25, 0xffff0000, v213
	v_pk_mul_f32 v[22:23], v[22:23], v[24:25]
	s_nop 0
	v_cvt_pk_bf16_f32 v15, v22, v23
	global_store_dwordx2 v[64:65], v[14:15], off offset:3232
	v_pk_mul_f32 v[14:15], v[8:9], v[18:19] op_sel_hi:[0,1]
	s_waitcnt vmcnt(15)
	v_lshlrev_b32_e32 v18, 16, v214
	v_and_b32_e32 v19, 0xffff0000, v214
	v_pk_mul_f32 v[14:15], v[14:15], v[18:19]
	v_pk_mul_f32 v[18:19], v[8:9], v[20:21] op_sel_hi:[0,1]
	v_lshlrev_b32_e32 v16, 16, v215
	v_and_b32_e32 v17, 0xffff0000, v215
	v_pk_mul_f32 v[16:17], v[18:19], v[16:17]
	v_cvt_pk_bf16_f32 v14, v14, v15
	v_cvt_pk_bf16_f32 v15, v16, v17
	global_store_dwordx2 v[52:53], v[14:15], off offset:3232
	s_nop 0
	v_pk_mul_f32 v[18:19], v[6:7], v[26:27] op_sel_hi:[0,1]
	s_waitcnt vmcnt(15)
	v_lshlrev_b32_e32 v20, 16, v216
	v_and_b32_e32 v21, 0xffff0000, v216
	v_pk_mul_f32 v[18:19], v[18:19], v[20:21]
	v_lshlrev_b32_e32 v20, 16, v217
	v_cvt_pk_bf16_f32 v14, v18, v19
	v_pk_mul_f32 v[18:19], v[6:7], v[28:29] op_sel_hi:[0,1]
	v_and_b32_e32 v21, 0xffff0000, v217
	v_pk_mul_f32 v[18:19], v[18:19], v[20:21]
	s_nop 0
	v_cvt_pk_bf16_f32 v15, v18, v19
	global_store_dwordx2 v[64:65], v[14:15], off offset:3264
	s_waitcnt vmcnt(15)
	v_lshlrev_b32_e32 v14, 16, v218
	v_and_b32_e32 v15, 0xffff0000, v218
	v_pk_mul_f32 v[10:11], v[10:11], v[14:15]
	v_lshlrev_b32_e32 v14, 16, v219
	v_and_b32_e32 v15, 0xffff0000, v219
	v_pk_mul_f32 v[12:13], v[12:13], v[14:15]
	v_cvt_pk_bf16_f32 v10, v10, v11
	v_cvt_pk_bf16_f32 v11, v12, v13
	global_store_dwordx2 v[52:53], v[10:11], off offset:3264
	s_nop 0
	v_pk_mul_f32 v[14:15], v[6:7], v[58:59] op_sel_hi:[0,1]
	v_pk_mul_f32 v[6:7], v[6:7], v[60:61] op_sel_hi:[0,1]
	s_waitcnt vmcnt(15)
	v_lshlrev_b32_e32 v16, 16, v220
	v_and_b32_e32 v17, 0xffff0000, v220
	v_pk_mul_f32 v[14:15], v[14:15], v[16:17]
	s_nop 0
	v_cvt_pk_bf16_f32 v10, v14, v15
	v_lshlrev_b32_e32 v14, 16, v221
	v_and_b32_e32 v15, 0xffff0000, v221
	v_pk_mul_f32 v[6:7], v[6:7], v[14:15]
	s_nop 0
	v_cvt_pk_bf16_f32 v11, v6, v7
	s_waitcnt vmcnt(14)
	v_lshlrev_b32_e32 v6, 16, v222
	v_and_b32_e32 v7, 0xffff0000, v222
	v_pk_mul_f32 v[2:3], v[2:3], v[6:7]
	v_lshlrev_b32_e32 v6, 16, v223
	v_and_b32_e32 v7, 0xffff0000, v223
	v_pk_mul_f32 v[4:5], v[4:5], v[6:7]
	v_cvt_pk_bf16_f32 v2, v2, v3
	v_cvt_pk_bf16_f32 v3, v4, v5
	global_store_dwordx2 v[64:65], v[10:11], off offset:3296
	global_store_dwordx2 v[52:53], v[2:3], off offset:3296
	s_cbranch_vccnz .LBB0_415
	v_readlane_b32 s0, v253, 63
	s_add_i32 s6, s0, s6
	s_cmpk_gt_i32 s6, 0x7f
	s_cbranch_scc0 .LBB0_414

; __device__ __forceinline__ float bf_lo(unsigned u) { return __uint_as_float(u << 16); }
; __device__ __forceinline__ float bf_hi(unsigned u) { return __uint_as_float(u & 0xffff0000u); }
; __device__ __forceinline__ unsigned pk2(float lo, float hi) { const f32x2c_t v = {lo, hi}; return __builtin_bit_cast(unsigned, __builtin_convertvector(v, bf16x2c_t)); }
; __device__ __forceinline__ void gla_scan(const Params& P, int tid, int cu, int ncu) {
;     const bf16* Ut = (const bf16*)(P.ws + WS_U); bf16* St = (bf16*)(P.ws + WS_Y); const float* dv = (const float*)(P.ws + WS_DV);
;     const int NW = 16 * 8192, half = NW / 2;
;     for (int wk = cu * NTHR + tid; wk < half; wk += ncu * NTHR) {
;         const int wa = wk, wb = wk + half;
;         const int bha = wa >> 13, pa = wa & 8191, bhb = wb >> 13, pb = wb & 8191; const int da = (pa & 31) * 4, db = (pb & 31) * 4;
;         float a0 = 0.f, a1 = 0.f, a2 = 0.f, a3 = 0.f, b0 = 0.f, b1 = 0.f, b2 = 0.f, b3 = 0.f;
;         const size_t basea = (size_t)bha * 64 * 32768 + (size_t)pa * 4, baseb = (size_t)bhb * 64 * 32768 + (size_t)pb * 4;
; #pragma unroll 8
;         for (int n = 0; n < 64; ++n) {
;             const v2u ua = *(const v2u*)(Ut + basea + (size_t)n * 32768), ub = *(const v2u*)(Ut + baseb + (size_t)n * 32768);
;             const f32x4 dda = *(const f32x4*)(dv + (size_t)(bha * 64 + n) * 128 + da), ddb = *(const f32x4*)(dv + (size_t)(bhb * 64 + n) * 128 + db);
;             v2u oa, ob; oa.x = pk2(a0, a1); oa.y = pk2(a2, a3); ob.x = pk2(b0, b1); ob.y = pk2(b2, b3);
;             *(v2u*)(St + basea + (size_t)n * 32768) = oa; *(v2u*)(St + baseb + (size_t)n * 32768) = ob;
;             a0 = a0 * dda[0] + bf_lo(ua.x); a1 = a1 * dda[1] + bf_hi(ua.x); a2 = a2 * dda[2] + bf_lo(ua.y); a3 = a3 * dda[3] + bf_hi(ua.y);
;             b0 = b0 * ddb[0] + bf_lo(ub.x); b1 = b1 * ddb[1] + bf_hi(ub.x); b2 = b2 * ddb[2] + bf_lo(ub.y); b3 = b3 * ddb[3] + bf_hi(ub.y);
;         }
.Lscan_pre:
	s_mov_b32 s8, 0x10000
	s_mov_b32 s9, 0
	v_lshl_add_u64 v[10:11], s[60:61], 0, v[4:5]
	v_lshl_add_u64 v[12:13], s[60:61], 0, v[2:3]
	v_lshl_add_u64 v[14:15], s[60:61], 0, v[4:5]
	v_lshl_add_u64 v[16:17], s[60:61], 0, v[2:3]
	v_lshl_add_u64 v[26:27], s[60:61], 0, v[6:7]
	v_lshl_add_u64 v[30:31], s[60:61], 0, v[8:9]
	v_add_co_u32_e32 v10, vcc, 0x10a00000, v10
	s_nop 1
	v_addc_co_u32_e32 v11, vcc, 0, v11, vcc
	v_add_co_u32_e32 v12, vcc, 0x10a00000, v12
	s_nop 1
	v_addc_co_u32_e32 v13, vcc, 0, v13, vcc
	v_add_co_u32_e32 v14, vcc, 0xca00000, v14
	s_nop 1
	v_addc_co_u32_e32 v15, vcc, 0, v15, vcc
	v_add_co_u32_e32 v16, vcc, 0xca00000, v16
	s_nop 1
	v_addc_co_u32_e32 v17, vcc, 0, v17, vcc
	v_add_co_u32_e32 v26, vcc, 0x2d400000, v26
	s_nop 1
	v_addc_co_u32_e32 v27, vcc, 0, v27, vcc
	v_add_co_u32_e32 v30, vcc, 0x2d400000, v30
	s_nop 1
	v_addc_co_u32_e32 v31, vcc, 0, v31, vcc
	v_mov_b32_e32 v18, 0
	v_mov_b32_e32 v19, 0
	v_mov_b32_e32 v20, 0
	v_mov_b32_e32 v21, 0
	v_mov_b32_e32 v22, 0
	v_mov_b32_e32 v23, 0
	v_mov_b32_e32 v24, 0
	v_mov_b32_e32 v25, 0
	global_load_dwordx2 v[48:49], v[10:11], off
	global_load_dwordx2 v[50:51], v[12:13], off
	global_load_dwordx4 v[52:55], v[26:27], off
	global_load_dwordx4 v[56:59], v[30:31], off
	v_lshl_add_u64 v[10:11], v[10:11], 0, s[8:9]
	v_lshl_add_u64 v[12:13], v[12:13], 0, s[8:9]
	global_load_dwordx2 v[60:61], v[10:11], off
	global_load_dwordx2 v[62:63], v[12:13], off
	global_load_dwordx4 v[64:67], v[26:27], off offset:512
	global_load_dwordx4 v[68:71], v[30:31], off offset:512
	v_lshl_add_u64 v[10:11], v[10:11], 0, s[8:9]
	v_lshl_add_u64 v[12:13], v[12:13], 0, s[8:9]
	global_load_dwordx2 v[72:73], v[10:11], off
	global_load_dwordx2 v[74:75], v[12:13], off
	global_load_dwordx4 v[76:79], v[26:27], off offset:1024
	global_load_dwordx4 v[80:83], v[30:31], off offset:1024
	v_lshl_add_u64 v[10:11], v[10:11], 0, s[8:9]
	v_lshl_add_u64 v[12:13], v[12:13], 0, s[8:9]
	global_load_dwordx2 v[84:85], v[10:11], off
	global_load_dwordx2 v[86:87], v[12:13], off
	global_load_dwordx4 v[88:91], v[26:27], off offset:1536
	global_load_dwordx4 v[92:95], v[30:31], off offset:1536
	v_lshl_add_u64 v[10:11], v[10:11], 0, s[8:9]
	v_lshl_add_u64 v[12:13], v[12:13], 0, s[8:9]
	global_load_dwordx2 v[96:97], v[10:11], off
	global_load_dwordx2 v[98:99], v[12:13], off
	global_load_dwordx4 v[100:103], v[26:27], off offset:2048
	global_load_dwordx4 v[104:107], v[30:31], off offset:2048
	v_lshl_add_u64 v[10:11], v[10:11], 0, s[8:9]
	v_lshl_add_u64 v[12:13], v[12:13], 0, s[8:9]
	global_load_dwordx2 v[108:109], v[10:11], off
	global_load_dwordx2 v[110:111], v[12:13], off
	global_load_dwordx4 v[112:115], v[26:27], off offset:2560
	global_load_dwordx4 v[116:119], v[30:31], off offset:2560
	v_lshl_add_u64 v[10:11], v[10:11], 0, s[8:9]
	v_lshl_add_u64 v[12:13], v[12:13], 0, s[8:9]
	global_load_dwordx2 v[144:145], v[10:11], off
	global_load_dwordx2 v[146:147], v[12:13], off
	global_load_dwordx4 v[148:151], v[26:27], off offset:3072
	global_load_dwordx4 v[152:155], v[30:31], off offset:3072
	v_lshl_add_u64 v[10:11], v[10:11], 0, s[8:9]
	v_lshl_add_u64 v[12:13], v[12:13], 0, s[8:9]
	global_load_dwordx2 v[156:157], v[10:11], off
	global_load_dwordx2 v[158:159], v[12:13], off
	global_load_dwordx4 v[160:163], v[26:27], off offset:3584
	global_load_dwordx4 v[164:167], v[30:31], off offset:3584
	v_lshl_add_u64 v[10:11], v[10:11], 0, s[8:9]
	v_lshl_add_u64 v[12:13], v[12:13], 0, s[8:9]
	v_lshl_add_u64 v[26:27], v[26:27], 0, s[96:97]
	v_lshl_add_u64 v[30:31], v[30:31], 0, s[96:97]
	s_mov_b32 s4, 8
.Lscan_loop:
	v_cvt_pk_bf16_f32 v34, v18, v19
	v_cvt_pk_bf16_f32 v35, v20, v21
	v_cvt_pk_bf16_f32 v36, v22, v23
	v_cvt_pk_bf16_f32 v37, v24, v25
	global_store_dwordx2 v[14:15], v[34:35], off
	global_store_dwordx2 v[16:17], v[36:37], off
	v_lshl_add_u64 v[14:15], v[14:15], 0, s[8:9]
	v_lshl_add_u64 v[16:17], v[16:17], 0, s[8:9]
	s_waitcnt vmcnt(30)
	v_lshlrev_b32_e32 v32, 16, v48
	v_and_b32_e32 v33, 0xffff0000, v48
	v_pk_fma_f32 v[18:19], v[18:19], v[52:53], v[32:33]
	v_lshlrev_b32_e32 v32, 16, v49
	v_and_b32_e32 v33, 0xffff0000, v49
	v_pk_fma_f32 v[20:21], v[20:21], v[54:55], v[32:33]
	v_lshlrev_b32_e32 v32, 16, v50
	v_and_b32_e32 v33, 0xffff0000, v50
	v_pk_fma_f32 v[22:23], v[22:23], v[56:57], v[32:33]
	v_lshlrev_b32_e32 v32, 16, v51
	v_and_b32_e32 v33, 0xffff0000, v51
	v_pk_fma_f32 v[24:25], v[24:25], v[58:59], v[32:33]
	global_load_dwordx2 v[48:49], v[10:11], off
	global_load_dwordx2 v[50:51], v[12:13], off
	global_load_dwordx4 v[52:55], v[26:27], off
	global_load_dwordx4 v[56:59], v[30:31], off
	v_lshl_add_u64 v[10:11], v[10:11], 0, s[8:9]
	v_lshl_add_u64 v[12:13], v[12:13], 0, s[8:9]
	v_cvt_pk_bf16_f32 v34, v18, v19
	v_cvt_pk_bf16_f32 v35, v20, v21
	v_cvt_pk_bf16_f32 v36, v22, v23
	v_cvt_pk_bf16_f32 v37, v24, v25
	global_store_dwordx2 v[14:15], v[34:35], off
	global_store_dwordx2 v[16:17], v[36:37], off
	v_lshl_add_u64 v[14:15], v[14:15], 0, s[8:9]
	v_lshl_add_u64 v[16:17], v[16:17], 0, s[8:9]
	s_waitcnt vmcnt(32)
	v_lshlrev_b32_e32 v32, 16, v60
	v_and_b32_e32 v33, 0xffff0000, v60
	v_pk_fma_f32 v[18:19], v[18:19], v[64:65], v[32:33]
	v_lshlrev_b32_e32 v32, 16, v61
	v_and_b32_e32 v33, 0xffff0000, v61
	v_pk_fma_f32 v[20:21], v[20:21], v[66:67], v[32:33]
	v_lshlrev_b32_e32 v32, 16, v62
	v_and_b32_e32 v33, 0xffff0000, v62
	v_pk_fma_f32 v[22:23], v[22:23], v[68:69], v[32:33]
	v_lshlrev_b32_e32 v32, 16, v63
	v_and_b32_e32 v33, 0xffff0000, v63
	v_pk_fma_f32 v[24:25], v[24:25], v[70:71], v[32:33]
	global_load_dwordx2 v[60:61], v[10:11], off
	global_load_dwordx2 v[62:63], v[12:13], off
	global_load_dwordx4 v[64:67], v[26:27], off offset:512
	global_load_dwordx4 v[68:71], v[30:31], off offset:512
	v_lshl_add_u64 v[10:11], v[10:11], 0, s[8:9]
	v_lshl_add_u64 v[12:13], v[12:13], 0, s[8:9]
	v_cvt_pk_bf16_f32 v34, v18, v19
	v_cvt_pk_bf16_f32 v35, v20, v21
	v_cvt_pk_bf16_f32 v36, v22, v23
	v_cvt_pk_bf16_f32 v37, v24, v25
	global_store_dwordx2 v[14:15], v[34:35], off
	global_store_dwordx2 v[16:17], v[36:37], off
	v_lshl_add_u64 v[14:15], v[14:15], 0, s[8:9]
	v_lshl_add_u64 v[16:17], v[16:17], 0, s[8:9]
	s_waitcnt vmcnt(34)
; __device__ __forceinline__ float bf_lo(unsigned u) { return __uint_as_float(u << 16); }
; __device__ __forceinline__ float bf_hi(unsigned u) { return __uint_as_float(u & 0xffff0000u); }
; __device__ __forceinline__ unsigned pk2(float lo, float hi) { const f32x2c_t v = {lo, hi}; return __builtin_bit_cast(unsigned, __builtin_convertvector(v, bf16x2c_t)); }
; __device__ __forceinline__ void gla_scan(const Params& P, int tid, int cu, int ncu) {
;     const bf16* Ut = (const bf16*)(P.ws + WS_U); bf16* St = (bf16*)(P.ws + WS_Y); const float* dv = (const float*)(P.ws + WS_DV);
;     const int NW = 16 * 8192, half = NW / 2;
;     for (int wk = cu * NTHR + tid; wk < half; wk += ncu * NTHR) {
;         const int wa = wk, wb = wk + half;
;         const int bha = wa >> 13, pa = wa & 8191, bhb = wb >> 13, pb = wb & 8191; const int da = (pa & 31) * 4, db = (pb & 31) * 4;
;         float a0 = 0.f, a1 = 0.f, a2 = 0.f, a3 = 0.f, b0 = 0.f, b1 = 0.f, b2 = 0.f, b3 = 0.f;
;         const size_t basea = (size_t)bha * 64 * 32768 + (size_t)pa * 4, baseb = (size_t)bhb * 64 * 32768 + (size_t)pb * 4;
; #pragma unroll 8
;         for (int n = 0; n < 64; ++n) {
;             const v2u ua = *(const v2u*)(Ut + basea + (size_t)n * 32768), ub = *(const v2u*)(Ut + baseb + (size_t)n * 32768);
;             const f32x4 dda = *(const f32x4*)(dv + (size_t)(bha * 64 + n) * 128 + da), ddb = *(const f32x4*)(dv + (size_t)(bhb * 64 + n) * 128 + db);
;             v2u oa, ob; oa.x = pk2(a0, a1); oa.y = pk2(a2, a3); ob.x = pk2(b0, b1); ob.y = pk2(b2, b3);
;             *(v2u*)(St + basea + (size_t)n * 32768) = oa; *(v2u*)(St + baseb + (size_t)n * 32768) = ob;
;             a0 = a0 * dda[0] + bf_lo(ua.x); a1 = a1 * dda[1] + bf_hi(ua.x); a2 = a2 * dda[2] + bf_lo(ua.y); a3 = a3 * dda[3] + bf_hi(ua.y);
;             b0 = b0 * ddb[0] + bf_lo(ub.x); b1 = b1 * ddb[1] + bf_hi(ub.x); b2 = b2 * ddb[2] + bf_lo(ub.y); b3 = b3 * ddb[3] + bf_hi(ub.y);
;         }
	v_lshlrev_b32_e32 v32, 16, v72
	v_and_b32_e32 v33, 0xffff0000, v72
	v_pk_fma_f32 v[18:19], v[18:19], v[76:77], v[32:33]
	v_lshlrev_b32_e32 v32, 16, v73
	v_and_b32_e32 v33, 0xffff0000, v73
	v_pk_fma_f32 v[20:21], v[20:21], v[78:79], v[32:33]
	v_lshlrev_b32_e32 v32, 16, v74
	v_and_b32_e32 v33, 0xffff0000, v74
	v_pk_fma_f32 v[22:23], v[22:23], v[80:81], v[32:33]
	v_lshlrev_b32_e32 v32, 16, v75
	v_and_b32_e32 v33, 0xffff0000, v75
	v_pk_fma_f32 v[24:25], v[24:25], v[82:83], v[32:33]
	global_load_dwordx2 v[72:73], v[10:11], off
	global_load_dwordx2 v[74:75], v[12:13], off
	global_load_dwordx4 v[76:79], v[26:27], off offset:1024
	global_load_dwordx4 v[80:83], v[30:31], off offset:1024
	v_lshl_add_u64 v[10:11], v[10:11], 0, s[8:9]
	v_lshl_add_u64 v[12:13], v[12:13], 0, s[8:9]
	v_cvt_pk_bf16_f32 v34, v18, v19
	v_cvt_pk_bf16_f32 v35, v20, v21
	v_cvt_pk_bf16_f32 v36, v22, v23
	v_cvt_pk_bf16_f32 v37, v24, v25
	global_store_dwordx2 v[14:15], v[34:35], off
	global_store_dwordx2 v[16:17], v[36:37], off
	v_lshl_add_u64 v[14:15], v[14:15], 0, s[8:9]
	v_lshl_add_u64 v[16:17], v[16:17], 0, s[8:9]
	s_waitcnt vmcnt(36)
	v_lshlrev_b32_e32 v32, 16, v84
	v_and_b32_e32 v33, 0xffff0000, v84
	v_pk_fma_f32 v[18:19], v[18:19], v[88:89], v[32:33]
	v_lshlrev_b32_e32 v32, 16, v85
	v_and_b32_e32 v33, 0xffff0000, v85
	v_pk_fma_f32 v[20:21], v[20:21], v[90:91], v[32:33]
	v_lshlrev_b32_e32 v32, 16, v86
	v_and_b32_e32 v33, 0xffff0000, v86
	v_pk_fma_f32 v[22:23], v[22:23], v[92:93], v[32:33]
	v_lshlrev_b32_e32 v32, 16, v87
	v_and_b32_e32 v33, 0xffff0000, v87
	v_pk_fma_f32 v[24:25], v[24:25], v[94:95], v[32:33]
	global_load_dwordx2 v[84:85], v[10:11], off
	global_load_dwordx2 v[86:87], v[12:13], off
	global_load_dwordx4 v[88:91], v[26:27], off offset:1536
	global_load_dwordx4 v[92:95], v[30:31], off offset:1536
	v_lshl_add_u64 v[10:11], v[10:11], 0, s[8:9]
	v_lshl_add_u64 v[12:13], v[12:13], 0, s[8:9]
	v_cvt_pk_bf16_f32 v34, v18, v19
	v_cvt_pk_bf16_f32 v35, v20, v21
	v_cvt_pk_bf16_f32 v36, v22, v23
	v_cvt_pk_bf16_f32 v37, v24, v25
	global_store_dwordx2 v[14:15], v[34:35], off
	global_store_dwordx2 v[16:17], v[36:37], off
	v_lshl_add_u64 v[14:15], v[14:15], 0, s[8:9]
	v_lshl_add_u64 v[16:17], v[16:17], 0, s[8:9]
	s_waitcnt vmcnt(38)
	v_lshlrev_b32_e32 v32, 16, v96
	v_and_b32_e32 v33, 0xffff0000, v96
	v_pk_fma_f32 v[18:19], v[18:19], v[100:101], v[32:33]
	v_lshlrev_b32_e32 v32, 16, v97
	v_and_b32_e32 v33, 0xffff0000, v97
	v_pk_fma_f32 v[20:21], v[20:21], v[102:103], v[32:33]
	v_lshlrev_b32_e32 v32, 16, v98
	v_and_b32_e32 v33, 0xffff0000, v98
	v_pk_fma_f32 v[22:23], v[22:23], v[104:105], v[32:33]
	v_lshlrev_b32_e32 v32, 16, v99
	v_and_b32_e32 v33, 0xffff0000, v99
	v_pk_fma_f32 v[24:25], v[24:25], v[106:107], v[32:33]
	global_load_dwordx2 v[96:97], v[10:11], off
	global_load_dwordx2 v[98:99], v[12:13], off
	global_load_dwordx4 v[100:103], v[26:27], off offset:2048
	global_load_dwordx4 v[104:107], v[30:31], off offset:2048
	v_lshl_add_u64 v[10:11], v[10:11], 0, s[8:9]
	v_lshl_add_u64 v[12:13], v[12:13], 0, s[8:9]
	v_cvt_pk_bf16_f32 v34, v18, v19
	v_cvt_pk_bf16_f32 v35, v20, v21
	v_cvt_pk_bf16_f32 v36, v22, v23
	v_cvt_pk_bf16_f32 v37, v24, v25
	global_store_dwordx2 v[14:15], v[34:35], off
	global_store_dwordx2 v[16:17], v[36:37], off
	v_lshl_add_u64 v[14:15], v[14:15], 0, s[8:9]
	v_lshl_add_u64 v[16:17], v[16:17], 0, s[8:9]
	s_waitcnt vmcnt(40)
	v_lshlrev_b32_e32 v32, 16, v108
	v_and_b32_e32 v33, 0xffff0000, v108
	v_pk_fma_f32 v[18:19], v[18:19], v[112:113], v[32:33]
	v_lshlrev_b32_e32 v32, 16, v109
	v_and_b32_e32 v33, 0xffff0000, v109
	v_pk_fma_f32 v[20:21], v[20:21], v[114:115], v[32:33]
	v_lshlrev_b32_e32 v32, 16, v110
	v_and_b32_e32 v33, 0xffff0000, v110
	v_pk_fma_f32 v[22:23], v[22:23], v[116:117], v[32:33]
	v_lshlrev_b32_e32 v32, 16, v111
	v_and_b32_e32 v33, 0xffff0000, v111
	v_pk_fma_f32 v[24:25], v[24:25], v[118:119], v[32:33]
	global_load_dwordx2 v[108:109], v[10:11], off
	global_load_dwordx2 v[110:111], v[12:13], off
	global_load_dwordx4 v[112:115], v[26:27], off offset:2560
	global_load_dwordx4 v[116:119], v[30:31], off offset:2560
	v_lshl_add_u64 v[10:11], v[10:11], 0, s[8:9]
	v_lshl_add_u64 v[12:13], v[12:13], 0, s[8:9]
	v_cvt_pk_bf16_f32 v34, v18, v19
	v_cvt_pk_bf16_f32 v35, v20, v21
	v_cvt_pk_bf16_f32 v36, v22, v23
	v_cvt_pk_bf16_f32 v37, v24, v25
	global_store_dwordx2 v[14:15], v[34:35], off
	global_store_dwordx2 v[16:17], v[36:37], off
	v_lshl_add_u64 v[14:15], v[14:15], 0, s[8:9]
	v_lshl_add_u64 v[16:17], v[16:17], 0, s[8:9]
	s_waitcnt vmcnt(42)
	v_lshlrev_b32_e32 v32, 16, v144
	v_and_b32_e32 v33, 0xffff0000, v144
	v_pk_fma_f32 v[18:19], v[18:19], v[148:149], v[32:33]
	v_lshlrev_b32_e32 v32, 16, v145
	v_and_b32_e32 v33, 0xffff0000, v145
	v_pk_fma_f32 v[20:21], v[20:21], v[150:151], v[32:33]
	v_lshlrev_b32_e32 v32, 16, v146
	v_and_b32_e32 v33, 0xffff0000, v146
	v_pk_fma_f32 v[22:23], v[22:23], v[152:153], v[32:33]
	v_lshlrev_b32_e32 v32, 16, v147
	v_and_b32_e32 v33, 0xffff0000, v147
	v_pk_fma_f32 v[24:25], v[24:25], v[154:155], v[32:33]
	global_load_dwordx2 v[144:145], v[10:11], off
	global_load_dwordx2 v[146:147], v[12:13], off
	global_load_dwordx4 v[148:151], v[26:27], off offset:3072
	global_load_dwordx4 v[152:155], v[30:31], off offset:3072
	v_lshl_add_u64 v[10:11], v[10:11], 0, s[8:9]
	v_lshl_add_u64 v[12:13], v[12:13], 0, s[8:9]
	v_cvt_pk_bf16_f32 v34, v18, v19
	v_cvt_pk_bf16_f32 v35, v20, v21
	v_cvt_pk_bf16_f32 v36, v22, v23
	v_cvt_pk_bf16_f32 v37, v24, v25
	global_store_dwordx2 v[14:15], v[34:35], off
	global_store_dwordx2 v[16:17], v[36:37], off
	v_lshl_add_u64 v[14:15], v[14:15], 0, s[8:9]
	v_lshl_add_u64 v[16:17], v[16:17], 0, s[8:9]
	s_waitcnt vmcnt(44)
	v_lshlrev_b32_e32 v32, 16, v156
	v_and_b32_e32 v33, 0xffff0000, v156
	v_pk_fma_f32 v[18:19], v[18:19], v[160:161], v[32:33]
	v_lshlrev_b32_e32 v32, 16, v157
	v_and_b32_e32 v33, 0xffff0000, v157
	v_pk_fma_f32 v[20:21], v[20:21], v[162:163], v[32:33]
	v_lshlrev_b32_e32 v32, 16, v158
	v_and_b32_e32 v33, 0xffff0000, v158
	v_pk_fma_f32 v[22:23], v[22:23], v[164:165], v[32:33]
	v_lshlrev_b32_e32 v32, 16, v159
	v_and_b32_e32 v33, 0xffff0000, v159
	v_pk_fma_f32 v[24:25], v[24:25], v[166:167], v[32:33]
	global_load_dwordx2 v[156:157], v[10:11], off
	global_load_dwordx2 v[158:159], v[12:13], off
	global_load_dwordx4 v[160:163], v[26:27], off offset:3584
	global_load_dwordx4 v[164:167], v[30:31], off offset:3584
	v_lshl_add_u64 v[10:11], v[10:11], 0, s[8:9]
	v_lshl_add_u64 v[12:13], v[12:13], 0, s[8:9]
	v_lshl_add_u64 v[26:27], v[26:27], 0, s[96:97]
	v_lshl_add_u64 v[30:31], v[30:31], 0, s[96:97]
	s_add_i32 s4, s4, -1
	s_cmp_eq_u32 s4, 0
	s_cbranch_scc0 .Lscan_loop
	s_waitcnt vmcnt(0)
	v_readlane_b32 s4, v254, 5
	s_nop 1
	v_add_u32_e32 v28, s4, v28
	s_mov_b32 s4, 0xffff
	v_cmp_lt_i32_e32 vcc, s4, v28
	v_readlane_b32 s4, v255, 7
	s_or_b64 s[6:7], vcc, s[6:7]
	s_nop 0
	v_add_u32_e32 v29, s4, v29
	s_andn2_b64 exec, exec, s[6:7]
	s_cbranch_execnz .LBB0_450

; #define LAS __attribute__((address_space(3)))
; __device__ __forceinline__ float logsig(float x) { return fminf(x, 0.f) - __logf(1.f + __expf(-fabsf(x))); }
; __device__ __forceinline__ void gla_decay(LAS float* gd, LAS float* tot, int tid, const float (&w)[16], float bias, float (&bv)[16], float& blast) {
;     const int d = tid & 127, rg = tid >> 7;
;     float run = 0.f;
; #pragma unroll
;     for (int c = 0; c < 16; ++c) { const LAS f32x4* g4 = (const LAS f32x4*)(gd + (rg * 16 + c) * 16); float a = bias;
; #pragma unroll
;         for (int q = 0; q < 4; ++q) { const f32x4 g = g4[q]; a += g[0] * w[4 * q] + g[1] * w[4 * q + 1] + g[2] * w[4 * q + 2] + g[3] * w[4 * q + 3]; }
;         run += logsig(a) * 0.0625f; bv[c] = run; }
; __device__ __forceinline__ void gla_step3(const Params& P, int l, LAS unsigned char* lds, int item, int tid) {
;     ...
;     store_v(VT, tid, vr);
;     __syncthreads();
;     float bv[16], blast;
;     gla_decay(GD, TOT, tid, wv, bias, bv, blast);
.LBB0_642:
	s_or_b64 exec, exec, s[0:1]
	s_waitcnt vmcnt(0)
	v_and_b32_e32 v36, 0x1f0, v114
	v_add_u32_e32 v36, 0, v36
	s_movk_i32 s15, 0x220
	v_mad_u64_u32 v[114:115], s[0:1], v115, s15, v[36:37]
	ds_write_b128 v114, v[38:41] offset:34816
	v_mad_u64_u32 v[38:39], s[0:1], v116, s15, v[36:37]
	ds_write_b128 v38, v[42:45] offset:34816
	v_mad_u64_u32 v[38:39], s[0:1], v117, s15, v[36:37]
	v_mad_u64_u32 v[36:37], s[0:1], v118, s15, v[36:37]
	v_readlane_b32 s17, v255, 18
	ds_write_b128 v38, v[46:49] offset:34816
	ds_write_b128 v36, v[50:53] offset:34816
	v_lshl_add_u32 v37, v77, 10, s17
	s_waitcnt lgkmcnt(0)
	s_barrier
	ds_read_b128 v[192:195], v37
	ds_read_b128 v[196:199], v37 offset:16
	ds_read_b128 v[200:203], v37 offset:32
	ds_read_b128 v[204:207], v37 offset:48
	ds_read_b128 v[208:211], v37 offset:64
	ds_read_b128 v[212:215], v37 offset:80
	ds_read_b128 v[216:219], v37 offset:96
	ds_read_b128 v[220:223], v37 offset:112
	v_bfe_u32 v35, v59, 4, 2
	s_waitcnt lgkmcnt(4)
	v_mul_f32_e32 v36, v107, v193
	v_fmac_f32_e32 v36, v106, v192
	v_mul_f32_e32 v38, v99, v197
	v_fmac_f32_e32 v36, v110, v194
	v_fmac_f32_e32 v38, v98, v196
	v_fmac_f32_e32 v36, v111, v195
	v_fmac_f32_e32 v38, v104, v198
	v_add_f32_e32 v36, v112, v36
	v_fmac_f32_e32 v38, v105, v199
	v_add_f32_e32 v36, v36, v38
	v_mul_f32_e32 v38, v101, v201
	v_fmac_f32_e32 v38, v100, v200
	v_fmac_f32_e32 v38, v108, v202
	v_fmac_f32_e32 v38, v109, v203
	v_add_f32_e32 v36, v36, v38
	v_mul_f32_e32 v38, v97, v205
	v_fmac_f32_e32 v38, v96, v204
	v_fmac_f32_e32 v38, v103, v206
	v_fmac_f32_e32 v38, v102, v207
	ds_read_b128 v[192:195], v37 offset:128
	ds_read_b128 v[196:199], v37 offset:144
	ds_read_b128 v[200:203], v37 offset:160
	ds_read_b128 v[204:207], v37 offset:176
	v_add_f32_e32 v36, v36, v38
	v_min_f32_e32 v38, 0, v36
	v_mul_f32_e64 v36, |v36|, s90
	v_exp_f32_e32 v36, v36
	s_movk_i32 s16, 0x110
	v_lshlrev_b32_e32 v34, 3, v35
	v_add_f32_e32 v36, 1.0, v36
	v_cmp_gt_f32_e32 vcc, s74, v36
	s_movk_i32 s9, 0x90
	s_nop 0
	v_cndmask_b32_e64 v39, 0, 32, vcc
	v_ldexp_f32 v36, v36, v39
	v_log_f32_e32 v36, v36
	s_nop 0
	v_mul_f32_e32 v39, 0x3f317217, v36
	v_fma_f32 v39, v36, s75, -v39
	v_fmac_f32_e32 v39, 0x3377d1cf, v36
	v_fmac_f32_e32 v39, 0x3f317217, v36
	v_cmp_lt_f32_e64 s[0:1], |v36|, s63
	s_nop 1
	v_cndmask_b32_e64 v36, v36, v39, s[0:1]
	v_cndmask_b32_e32 v39, 0, v240, vcc
	v_sub_f32_e32 v36, v36, v39
	v_sub_f32_e32 v36, v38, v36
	s_mov_b32 s0, 0x3d800000
	v_fma_f32 v36, v36, s0, 0
	s_waitcnt lgkmcnt(4)
	v_mul_f32_e32 v39, v107, v209
	v_fmac_f32_e32 v39, v106, v208
	v_fmac_f32_e32 v39, v110, v210
	v_fmac_f32_e32 v39, v111, v211
	v_add_f32_e32 v42, v112, v39
	v_mul_f32_e32 v39, v99, v213
	v_fmac_f32_e32 v39, v98, v212
	v_fmac_f32_e32 v39, v104, v214
	v_fmac_f32_e32 v39, v105, v215
	v_add_f32_e32 v42, v42, v39
	v_mul_f32_e32 v39, v101, v217
	v_fmac_f32_e32 v39, v100, v216
	v_fmac_f32_e32 v39, v108, v218
	v_fmac_f32_e32 v39, v109, v219
	v_add_f32_e32 v42, v42, v39
	v_mul_f32_e32 v39, v97, v221
	v_fmac_f32_e32 v39, v96, v220
	v_fmac_f32_e32 v39, v103, v222
	v_fmac_f32_e32 v39, v102, v223
	ds_read_b128 v[208:211], v37 offset:192
	ds_read_b128 v[212:215], v37 offset:208
	ds_read_b128 v[216:219], v37 offset:224
	ds_read_b128 v[220:223], v37 offset:240
	v_add_f32_e32 v38, v42, v39
	v_min_f32_e32 v39, 0, v38
	v_mul_f32_e64 v38, |v38|, s90
	v_exp_f32_e32 v38, v38
	s_nop 0
	v_add_f32_e32 v38, 1.0, v38
	v_cmp_gt_f32_e32 vcc, s74, v38
	s_nop 1
	v_cndmask_b32_e64 v40, 0, 32, vcc
	v_ldexp_f32 v38, v38, v40
	v_log_f32_e32 v38, v38
	s_nop 0
	v_mul_f32_e32 v40, 0x3f317217, v38
	v_fma_f32 v40, v38, s75, -v40
	v_fmac_f32_e32 v40, 0x3377d1cf, v38
	v_fmac_f32_e32 v40, 0x3f317217, v38
	v_cmp_lt_f32_e64 s[0:1], |v38|, s63
	s_nop 1
	v_cndmask_b32_e64 v38, v38, v40, s[0:1]
	v_cndmask_b32_e32 v40, 0, v240, vcc
	v_sub_f32_e32 v38, v38, v40
	v_sub_f32_e32 v38, v39, v38
	v_fmamk_f32 v38, v38, 0x3d800000, v36
	s_waitcnt lgkmcnt(4)
	v_mul_f32_e32 v39, v107, v193
	v_fmac_f32_e32 v39, v106, v192
	v_fmac_f32_e32 v39, v110, v194
	v_fmac_f32_e32 v39, v111, v195
	v_add_f32_e32 v39, v112, v39
	v_mul_f32_e32 v41, v99, v197
	v_fmac_f32_e32 v41, v98, v196
	v_fmac_f32_e32 v41, v104, v198
	v_fmac_f32_e32 v41, v105, v199
	v_add_f32_e32 v39, v39, v41
	v_mul_f32_e32 v41, v101, v201
	v_fmac_f32_e32 v41, v100, v200
	v_fmac_f32_e32 v41, v108, v202
	v_fmac_f32_e32 v41, v109, v203
	v_add_f32_e32 v39, v39, v41
	v_mul_f32_e32 v41, v97, v205
	v_fmac_f32_e32 v41, v96, v204
	v_fmac_f32_e32 v41, v103, v206
	v_fmac_f32_e32 v41, v102, v207
	ds_read_b128 v[192:195], v37 offset:256
	ds_read_b128 v[196:199], v37 offset:272
	ds_read_b128 v[200:203], v37 offset:288
	ds_read_b128 v[204:207], v37 offset:304
	v_add_f32_e32 v39, v39, v41
	v_min_f32_e32 v40, 0, v39
	v_mul_f32_e64 v39, |v39|, s90
	v_exp_f32_e32 v39, v39
	s_nop 0
	v_add_f32_e32 v39, 1.0, v39
	v_cmp_gt_f32_e32 vcc, s74, v39
	s_nop 1
	v_cndmask_b32_e64 v41, 0, 32, vcc
	v_ldexp_f32 v39, v39, v41
	v_log_f32_e32 v39, v39
	s_nop 0
	v_mul_f32_e32 v41, 0x3f317217, v39
	v_fma_f32 v41, v39, s75, -v41
	v_fmac_f32_e32 v41, 0x3377d1cf, v39
	v_fmac_f32_e32 v41, 0x3f317217, v39
	v_cmp_lt_f32_e64 s[0:1], |v39|, s63
	s_nop 1
	v_cndmask_b32_e64 v39, v39, v41, s[0:1]
	v_cndmask_b32_e32 v41, 0, v240, vcc
	v_sub_f32_e32 v39, v39, v41
	v_sub_f32_e32 v39, v40, v39
	v_fmamk_f32 v39, v39, 0x3d800000, v38
	s_waitcnt lgkmcnt(4)
; #define LAS __attribute__((address_space(3)))
; __device__ __forceinline__ float logsig(float x) { return fminf(x, 0.f) - __logf(1.f + __expf(-fabsf(x))); }
; __device__ __forceinline__ void gla_decay(LAS float* gd, LAS float* tot, int tid, const float (&w)[16], float bias, float (&bv)[16], float& blast) {
;     const int d = tid & 127, rg = tid >> 7;
;     float run = 0.f;
; #pragma unroll
;     for (int c = 0; c < 16; ++c) { const LAS f32x4* g4 = (const LAS f32x4*)(gd + (rg * 16 + c) * 16); float a = bias;
; #pragma unroll
;         for (int q = 0; q < 4; ++q) { const f32x4 g = g4[q]; a += g[0] * w[4 * q] + g[1] * w[4 * q + 1] + g[2] * w[4 * q + 2] + g[3] * w[4 * q + 3]; }
;         run += logsig(a) * 0.0625f; bv[c] = run; }
	v_mul_f32_e32 v41, v107, v209
	v_fmac_f32_e32 v41, v106, v208
	v_fmac_f32_e32 v41, v110, v210
	v_fmac_f32_e32 v41, v111, v211
	v_add_f32_e32 v44, v112, v41
	v_mul_f32_e32 v41, v99, v213
	v_fmac_f32_e32 v41, v98, v212
	v_fmac_f32_e32 v41, v104, v214
	v_fmac_f32_e32 v41, v105, v215
	v_add_f32_e32 v44, v44, v41
	v_mul_f32_e32 v41, v101, v217
	v_fmac_f32_e32 v41, v100, v216
	v_fmac_f32_e32 v41, v108, v218
	v_fmac_f32_e32 v41, v109, v219
	v_add_f32_e32 v44, v44, v41
	v_mul_f32_e32 v41, v97, v221
	v_fmac_f32_e32 v41, v96, v220
	v_fmac_f32_e32 v41, v103, v222
	v_fmac_f32_e32 v41, v102, v223
	ds_read_b128 v[208:211], v37 offset:320
	ds_read_b128 v[212:215], v37 offset:336
	ds_read_b128 v[216:219], v37 offset:352
	ds_read_b128 v[220:223], v37 offset:368
	v_add_f32_e32 v40, v44, v41
	v_min_f32_e32 v41, 0, v40
	v_mul_f32_e64 v40, |v40|, s90
	v_exp_f32_e32 v40, v40
	s_nop 0
	v_add_f32_e32 v40, 1.0, v40
	v_cmp_gt_f32_e32 vcc, s74, v40
	s_nop 1
	v_cndmask_b32_e64 v42, 0, 32, vcc
	v_ldexp_f32 v40, v40, v42
	v_log_f32_e32 v40, v40
	s_nop 0
	v_mul_f32_e32 v42, 0x3f317217, v40
	v_fma_f32 v42, v40, s75, -v42
	v_fmac_f32_e32 v42, 0x3377d1cf, v40
	v_fmac_f32_e32 v42, 0x3f317217, v40
	v_cmp_lt_f32_e64 s[0:1], |v40|, s63
	s_nop 1
	v_cndmask_b32_e64 v40, v40, v42, s[0:1]
	v_cndmask_b32_e32 v42, 0, v240, vcc
	v_sub_f32_e32 v40, v40, v42
	v_sub_f32_e32 v40, v41, v40
	v_fmamk_f32 v40, v40, 0x3d800000, v39
	s_waitcnt lgkmcnt(4)
	v_mul_f32_e32 v41, v107, v193
	v_fmac_f32_e32 v41, v106, v192
	v_fmac_f32_e32 v41, v110, v194
	v_fmac_f32_e32 v41, v111, v195
	v_add_f32_e32 v41, v112, v41
	v_mul_f32_e32 v43, v99, v197
	v_fmac_f32_e32 v43, v98, v196
	v_fmac_f32_e32 v43, v104, v198
	v_fmac_f32_e32 v43, v105, v199
	v_add_f32_e32 v41, v41, v43
	v_mul_f32_e32 v43, v101, v201
	v_fmac_f32_e32 v43, v100, v200
	v_fmac_f32_e32 v43, v108, v202
	v_fmac_f32_e32 v43, v109, v203
	v_add_f32_e32 v41, v41, v43
	v_mul_f32_e32 v43, v97, v205
	v_fmac_f32_e32 v43, v96, v204
	v_fmac_f32_e32 v43, v103, v206
	v_fmac_f32_e32 v43, v102, v207
	ds_read_b128 v[192:195], v37 offset:384
	ds_read_b128 v[196:199], v37 offset:400
	ds_read_b128 v[200:203], v37 offset:416
	ds_read_b128 v[204:207], v37 offset:432
	v_add_f32_e32 v41, v41, v43
	v_min_f32_e32 v42, 0, v41
	v_mul_f32_e64 v41, |v41|, s90
	v_exp_f32_e32 v41, v41
	s_nop 0
	v_add_f32_e32 v41, 1.0, v41
	v_cmp_gt_f32_e32 vcc, s74, v41
	s_nop 1
	v_cndmask_b32_e64 v43, 0, 32, vcc
	v_ldexp_f32 v41, v41, v43
	v_log_f32_e32 v41, v41
	s_nop 0
	v_mul_f32_e32 v43, 0x3f317217, v41
	v_fma_f32 v43, v41, s75, -v43
	v_fmac_f32_e32 v43, 0x3377d1cf, v41
	v_fmac_f32_e32 v43, 0x3f317217, v41
	v_cmp_lt_f32_e64 s[0:1], |v41|, s63
	s_nop 1
	v_cndmask_b32_e64 v41, v41, v43, s[0:1]
	v_cndmask_b32_e32 v43, 0, v240, vcc
	v_sub_f32_e32 v41, v41, v43
	v_sub_f32_e32 v41, v42, v41
	v_fmamk_f32 v41, v41, 0x3d800000, v40
	s_waitcnt lgkmcnt(4)
	v_mul_f32_e32 v43, v107, v209
	v_fmac_f32_e32 v43, v106, v208
	v_fmac_f32_e32 v43, v110, v210
	v_fmac_f32_e32 v43, v111, v211
	v_add_f32_e32 v46, v112, v43
	v_mul_f32_e32 v43, v99, v213
	v_fmac_f32_e32 v43, v98, v212
	v_fmac_f32_e32 v43, v104, v214
	v_fmac_f32_e32 v43, v105, v215
	v_add_f32_e32 v46, v46, v43
	v_mul_f32_e32 v43, v101, v217
	v_fmac_f32_e32 v43, v100, v216
	v_fmac_f32_e32 v43, v108, v218
	v_fmac_f32_e32 v43, v109, v219
	v_add_f32_e32 v46, v46, v43
	v_mul_f32_e32 v43, v97, v221
	v_fmac_f32_e32 v43, v96, v220
	v_fmac_f32_e32 v43, v103, v222
	v_fmac_f32_e32 v43, v102, v223
	ds_read_b128 v[208:211], v37 offset:448
	ds_read_b128 v[212:215], v37 offset:464
	ds_read_b128 v[216:219], v37 offset:480
	ds_read_b128 v[220:223], v37 offset:496
	v_add_f32_e32 v42, v46, v43
	v_min_f32_e32 v43, 0, v42
	v_mul_f32_e64 v42, |v42|, s90
	v_exp_f32_e32 v42, v42
	s_nop 0
	v_add_f32_e32 v42, 1.0, v42
	v_cmp_gt_f32_e32 vcc, s74, v42
	s_nop 1
	v_cndmask_b32_e64 v44, 0, 32, vcc
	v_ldexp_f32 v42, v42, v44
	v_log_f32_e32 v42, v42
	s_nop 0
	v_mul_f32_e32 v44, 0x3f317217, v42
	v_fma_f32 v44, v42, s75, -v44
	v_fmac_f32_e32 v44, 0x3377d1cf, v42
	v_fmac_f32_e32 v44, 0x3f317217, v42
	v_cmp_lt_f32_e64 s[0:1], |v42|, s63
	s_nop 1
	v_cndmask_b32_e64 v42, v42, v44, s[0:1]
	v_cndmask_b32_e32 v44, 0, v240, vcc
	v_sub_f32_e32 v42, v42, v44
	v_sub_f32_e32 v42, v43, v42
	v_fmamk_f32 v42, v42, 0x3d800000, v41
	s_waitcnt lgkmcnt(4)
	v_mul_f32_e32 v43, v107, v193
	v_fmac_f32_e32 v43, v106, v192
	v_fmac_f32_e32 v43, v110, v194
	v_fmac_f32_e32 v43, v111, v195
	v_add_f32_e32 v43, v112, v43
	v_mul_f32_e32 v45, v99, v197
	v_fmac_f32_e32 v45, v98, v196
	v_fmac_f32_e32 v45, v104, v198
	v_fmac_f32_e32 v45, v105, v199
	v_add_f32_e32 v43, v43, v45
	v_mul_f32_e32 v45, v101, v201
	v_fmac_f32_e32 v45, v100, v200
	v_fmac_f32_e32 v45, v108, v202
	v_fmac_f32_e32 v45, v109, v203
	v_add_f32_e32 v43, v43, v45
	v_mul_f32_e32 v45, v97, v205
	v_fmac_f32_e32 v45, v96, v204
	v_fmac_f32_e32 v45, v103, v206
	v_fmac_f32_e32 v45, v102, v207
	ds_read_b128 v[192:195], v37 offset:512
	ds_read_b128 v[196:199], v37 offset:528
	ds_read_b128 v[200:203], v37 offset:544
	ds_read_b128 v[204:207], v37 offset:560
	v_add_f32_e32 v43, v43, v45
	v_min_f32_e32 v44, 0, v43
	v_mul_f32_e64 v43, |v43|, s90
	v_exp_f32_e32 v43, v43
	s_nop 0
	v_add_f32_e32 v43, 1.0, v43
	v_cmp_gt_f32_e32 vcc, s74, v43
	s_nop 1
	v_cndmask_b32_e64 v45, 0, 32, vcc
	v_ldexp_f32 v43, v43, v45
	v_log_f32_e32 v43, v43
	s_nop 0
	v_mul_f32_e32 v45, 0x3f317217, v43
	v_fma_f32 v45, v43, s75, -v45
	v_fmac_f32_e32 v45, 0x3377d1cf, v43
	v_fmac_f32_e32 v45, 0x3f317217, v43
	v_cmp_lt_f32_e64 s[0:1], |v43|, s63
	s_nop 1
	v_cndmask_b32_e64 v43, v43, v45, s[0:1]
	v_cndmask_b32_e32 v45, 0, v240, vcc
	v_sub_f32_e32 v43, v43, v45
	v_sub_f32_e32 v43, v44, v43
	v_fmamk_f32 v43, v43, 0x3d800000, v42
	s_waitcnt lgkmcnt(4)
; #define LAS __attribute__((address_space(3)))
; __device__ __forceinline__ float logsig(float x) { return fminf(x, 0.f) - __logf(1.f + __expf(-fabsf(x))); }
; __device__ __forceinline__ void gla_decay(LAS float* gd, LAS float* tot, int tid, const float (&w)[16], float bias, float (&bv)[16], float& blast) {
;     const int d = tid & 127, rg = tid >> 7;
;     float run = 0.f;
; #pragma unroll
;     for (int c = 0; c < 16; ++c) { const LAS f32x4* g4 = (const LAS f32x4*)(gd + (rg * 16 + c) * 16); float a = bias;
; #pragma unroll
;         for (int q = 0; q < 4; ++q) { const f32x4 g = g4[q]; a += g[0] * w[4 * q] + g[1] * w[4 * q + 1] + g[2] * w[4 * q + 2] + g[3] * w[4 * q + 3]; }
;         run += logsig(a) * 0.0625f; bv[c] = run; }
	v_mul_f32_e32 v45, v107, v209
	v_fmac_f32_e32 v45, v106, v208
	v_fmac_f32_e32 v45, v110, v210
	v_fmac_f32_e32 v45, v111, v211
	v_add_f32_e32 v48, v112, v45
	v_mul_f32_e32 v45, v99, v213
	v_fmac_f32_e32 v45, v98, v212
	v_fmac_f32_e32 v45, v104, v214
	v_fmac_f32_e32 v45, v105, v215
	v_add_f32_e32 v48, v48, v45
	v_mul_f32_e32 v45, v101, v217
	v_fmac_f32_e32 v45, v100, v216
	v_fmac_f32_e32 v45, v108, v218
	v_fmac_f32_e32 v45, v109, v219
	v_add_f32_e32 v48, v48, v45
	v_mul_f32_e32 v45, v97, v221
	v_fmac_f32_e32 v45, v96, v220
	v_fmac_f32_e32 v45, v103, v222
	v_fmac_f32_e32 v45, v102, v223
	ds_read_b128 v[208:211], v37 offset:576
	ds_read_b128 v[212:215], v37 offset:592
	ds_read_b128 v[216:219], v37 offset:608
	ds_read_b128 v[220:223], v37 offset:624
	v_add_f32_e32 v44, v48, v45
	v_min_f32_e32 v45, 0, v44
	v_mul_f32_e64 v44, |v44|, s90
	v_exp_f32_e32 v44, v44
	s_nop 0
	v_add_f32_e32 v44, 1.0, v44
	v_cmp_gt_f32_e32 vcc, s74, v44
	s_nop 1
	v_cndmask_b32_e64 v46, 0, 32, vcc
	v_ldexp_f32 v44, v44, v46
	v_log_f32_e32 v44, v44
	s_nop 0
	v_mul_f32_e32 v46, 0x3f317217, v44
	v_fma_f32 v46, v44, s75, -v46
	v_fmac_f32_e32 v46, 0x3377d1cf, v44
	v_fmac_f32_e32 v46, 0x3f317217, v44
	v_cmp_lt_f32_e64 s[0:1], |v44|, s63
	s_nop 1
	v_cndmask_b32_e64 v44, v44, v46, s[0:1]
	v_cndmask_b32_e32 v46, 0, v240, vcc
	v_sub_f32_e32 v44, v44, v46
	v_sub_f32_e32 v44, v45, v44
	v_fmamk_f32 v44, v44, 0x3d800000, v43
	s_waitcnt lgkmcnt(4)
	v_mul_f32_e32 v45, v107, v193
	v_fmac_f32_e32 v45, v106, v192
	v_fmac_f32_e32 v45, v110, v194
	v_fmac_f32_e32 v45, v111, v195
	v_add_f32_e32 v45, v112, v45
	v_mul_f32_e32 v47, v99, v197
	v_fmac_f32_e32 v47, v98, v196
	v_fmac_f32_e32 v47, v104, v198
	v_fmac_f32_e32 v47, v105, v199
	v_add_f32_e32 v45, v45, v47
	v_mul_f32_e32 v47, v101, v201
	v_fmac_f32_e32 v47, v100, v200
	v_fmac_f32_e32 v47, v108, v202
	v_fmac_f32_e32 v47, v109, v203
	v_add_f32_e32 v45, v45, v47
	v_mul_f32_e32 v47, v97, v205
	v_fmac_f32_e32 v47, v96, v204
	v_fmac_f32_e32 v47, v103, v206
	v_fmac_f32_e32 v47, v102, v207
	ds_read_b128 v[192:195], v37 offset:640
	ds_read_b128 v[196:199], v37 offset:656
	ds_read_b128 v[200:203], v37 offset:672
	ds_read_b128 v[204:207], v37 offset:688
	v_add_f32_e32 v45, v45, v47
	v_min_f32_e32 v46, 0, v45
	v_mul_f32_e64 v45, |v45|, s90
	v_exp_f32_e32 v45, v45
	s_nop 0
	v_add_f32_e32 v45, 1.0, v45
	v_cmp_gt_f32_e32 vcc, s74, v45
	s_nop 1
	v_cndmask_b32_e64 v47, 0, 32, vcc
	v_ldexp_f32 v45, v45, v47
	v_log_f32_e32 v45, v45
	s_nop 0
	v_mul_f32_e32 v47, 0x3f317217, v45
	v_fma_f32 v47, v45, s75, -v47
	v_fmac_f32_e32 v47, 0x3377d1cf, v45
	v_fmac_f32_e32 v47, 0x3f317217, v45
	v_cmp_lt_f32_e64 s[0:1], |v45|, s63
	s_nop 1
	v_cndmask_b32_e64 v45, v45, v47, s[0:1]
	v_cndmask_b32_e32 v47, 0, v240, vcc
	v_sub_f32_e32 v45, v45, v47
	v_sub_f32_e32 v45, v46, v45
	v_fmamk_f32 v45, v45, 0x3d800000, v44
	s_waitcnt lgkmcnt(4)
	v_mul_f32_e32 v47, v107, v209
	v_fmac_f32_e32 v47, v106, v208
	v_fmac_f32_e32 v47, v110, v210
	v_fmac_f32_e32 v47, v111, v211
	v_add_f32_e32 v50, v112, v47
	v_mul_f32_e32 v47, v99, v213
	v_fmac_f32_e32 v47, v98, v212
	v_fmac_f32_e32 v47, v104, v214
	v_fmac_f32_e32 v47, v105, v215
	v_add_f32_e32 v50, v50, v47
	v_mul_f32_e32 v47, v101, v217
	v_fmac_f32_e32 v47, v100, v216
	v_fmac_f32_e32 v47, v108, v218
	v_fmac_f32_e32 v47, v109, v219
	v_add_f32_e32 v50, v50, v47
	v_mul_f32_e32 v47, v97, v221
	v_fmac_f32_e32 v47, v96, v220
	v_fmac_f32_e32 v47, v103, v222
	v_fmac_f32_e32 v47, v102, v223
	ds_read_b128 v[208:211], v37 offset:704
	ds_read_b128 v[212:215], v37 offset:720
	ds_read_b128 v[216:219], v37 offset:736
	ds_read_b128 v[220:223], v37 offset:752
	v_add_f32_e32 v46, v50, v47
	v_min_f32_e32 v47, 0, v46
	v_mul_f32_e64 v46, |v46|, s90
	v_exp_f32_e32 v46, v46
	s_nop 0
	v_add_f32_e32 v46, 1.0, v46
	v_cmp_gt_f32_e32 vcc, s74, v46
	s_nop 1
	v_cndmask_b32_e64 v48, 0, 32, vcc
	v_ldexp_f32 v46, v46, v48
	v_log_f32_e32 v46, v46
	s_nop 0
	v_mul_f32_e32 v48, 0x3f317217, v46
	v_fma_f32 v48, v46, s75, -v48
	v_fmac_f32_e32 v48, 0x3377d1cf, v46
	v_fmac_f32_e32 v48, 0x3f317217, v46
	v_cmp_lt_f32_e64 s[0:1], |v46|, s63
	s_nop 1
	v_cndmask_b32_e64 v46, v46, v48, s[0:1]
	v_cndmask_b32_e32 v48, 0, v240, vcc
	v_sub_f32_e32 v46, v46, v48
	v_sub_f32_e32 v46, v47, v46
	v_fmamk_f32 v46, v46, 0x3d800000, v45
	s_waitcnt lgkmcnt(4)
	v_mul_f32_e32 v47, v107, v193
	v_fmac_f32_e32 v47, v106, v192
	v_fmac_f32_e32 v47, v110, v194
	v_fmac_f32_e32 v47, v111, v195
	v_add_f32_e32 v47, v112, v47
	v_mul_f32_e32 v49, v99, v197
	v_fmac_f32_e32 v49, v98, v196
	v_fmac_f32_e32 v49, v104, v198
	v_fmac_f32_e32 v49, v105, v199
	v_add_f32_e32 v47, v47, v49
	v_mul_f32_e32 v49, v101, v201
	v_fmac_f32_e32 v49, v100, v200
	v_fmac_f32_e32 v49, v108, v202
	v_fmac_f32_e32 v49, v109, v203
	v_add_f32_e32 v47, v47, v49
	v_mul_f32_e32 v49, v97, v205
	v_fmac_f32_e32 v49, v96, v204
	v_fmac_f32_e32 v49, v103, v206
	v_fmac_f32_e32 v49, v102, v207
	ds_read_b128 v[192:195], v37 offset:768
	ds_read_b128 v[196:199], v37 offset:784
	ds_read_b128 v[200:203], v37 offset:800
	ds_read_b128 v[204:207], v37 offset:816
	v_add_f32_e32 v47, v47, v49
	v_min_f32_e32 v48, 0, v47
	v_mul_f32_e64 v47, |v47|, s90
	v_exp_f32_e32 v47, v47
	s_nop 0
	v_add_f32_e32 v47, 1.0, v47
	v_cmp_gt_f32_e32 vcc, s74, v47
	s_nop 1
	v_cndmask_b32_e64 v49, 0, 32, vcc
	v_ldexp_f32 v47, v47, v49
	v_log_f32_e32 v47, v47
	s_nop 0
	v_mul_f32_e32 v49, 0x3f317217, v47
	v_fma_f32 v49, v47, s75, -v49
	v_fmac_f32_e32 v49, 0x3377d1cf, v47
	v_fmac_f32_e32 v49, 0x3f317217, v47
	v_cmp_lt_f32_e64 s[0:1], |v47|, s63
	s_nop 1
	v_cndmask_b32_e64 v47, v47, v49, s[0:1]
	v_cndmask_b32_e32 v49, 0, v240, vcc
	v_sub_f32_e32 v47, v47, v49
	v_sub_f32_e32 v47, v48, v47
	v_fmamk_f32 v47, v47, 0x3d800000, v46
	s_waitcnt lgkmcnt(4)
; #define LAS __attribute__((address_space(3)))
; __device__ __forceinline__ float logsig(float x) { return fminf(x, 0.f) - __logf(1.f + __expf(-fabsf(x))); }
; __device__ __forceinline__ void gla_decay(LAS float* gd, LAS float* tot, int tid, const float (&w)[16], float bias, float (&bv)[16], float& blast) {
;     const int d = tid & 127, rg = tid >> 7;
;     float run = 0.f;
; #pragma unroll
;     for (int c = 0; c < 16; ++c) { const LAS f32x4* g4 = (const LAS f32x4*)(gd + (rg * 16 + c) * 16); float a = bias;
; #pragma unroll
;         for (int q = 0; q < 4; ++q) { const f32x4 g = g4[q]; a += g[0] * w[4 * q] + g[1] * w[4 * q + 1] + g[2] * w[4 * q + 2] + g[3] * w[4 * q + 3]; }
;         run += logsig(a) * 0.0625f; bv[c] = run; }
;     tot[rg * 128 + d] = run;
	v_mul_f32_e32 v49, v107, v209
	v_fmac_f32_e32 v49, v106, v208
	v_fmac_f32_e32 v49, v110, v210
	v_fmac_f32_e32 v49, v111, v211
	v_add_f32_e32 v52, v112, v49
	v_mul_f32_e32 v49, v99, v213
	v_fmac_f32_e32 v49, v98, v212
	v_fmac_f32_e32 v49, v104, v214
	v_fmac_f32_e32 v49, v105, v215
	v_add_f32_e32 v52, v52, v49
	v_mul_f32_e32 v49, v101, v217
	v_fmac_f32_e32 v49, v100, v216
	v_fmac_f32_e32 v49, v108, v218
	v_fmac_f32_e32 v49, v109, v219
	v_add_f32_e32 v52, v52, v49
	v_mul_f32_e32 v49, v97, v221
	v_fmac_f32_e32 v49, v96, v220
	v_fmac_f32_e32 v49, v103, v222
	v_fmac_f32_e32 v49, v102, v223
	ds_read_b128 v[208:211], v37 offset:832
	ds_read_b128 v[212:215], v37 offset:848
	ds_read_b128 v[216:219], v37 offset:864
	ds_read_b128 v[220:223], v37 offset:880
	v_add_f32_e32 v48, v52, v49
	v_min_f32_e32 v49, 0, v48
	v_mul_f32_e64 v48, |v48|, s90
	v_exp_f32_e32 v48, v48
	s_nop 0
	v_add_f32_e32 v48, 1.0, v48
	v_cmp_gt_f32_e32 vcc, s74, v48
	s_nop 1
	v_cndmask_b32_e64 v50, 0, 32, vcc
	v_ldexp_f32 v48, v48, v50
	v_log_f32_e32 v48, v48
	s_nop 0
	v_mul_f32_e32 v50, 0x3f317217, v48
	v_fma_f32 v50, v48, s75, -v50
	v_fmac_f32_e32 v50, 0x3377d1cf, v48
	v_fmac_f32_e32 v50, 0x3f317217, v48
	v_cmp_lt_f32_e64 s[0:1], |v48|, s63
	s_nop 1
	v_cndmask_b32_e64 v48, v48, v50, s[0:1]
	v_cndmask_b32_e32 v50, 0, v240, vcc
	v_sub_f32_e32 v48, v48, v50
	v_sub_f32_e32 v48, v49, v48
	v_fmamk_f32 v48, v48, 0x3d800000, v47
	s_waitcnt lgkmcnt(4)
	v_mul_f32_e32 v49, v107, v193
	v_fmac_f32_e32 v49, v106, v192
	v_fmac_f32_e32 v49, v110, v194
	v_fmac_f32_e32 v49, v111, v195
	v_add_f32_e32 v49, v112, v49
	v_mul_f32_e32 v51, v99, v197
	v_fmac_f32_e32 v51, v98, v196
	v_fmac_f32_e32 v51, v104, v198
	v_fmac_f32_e32 v51, v105, v199
	v_add_f32_e32 v49, v49, v51
	v_mul_f32_e32 v51, v101, v201
	v_fmac_f32_e32 v51, v100, v200
	v_fmac_f32_e32 v51, v108, v202
	v_fmac_f32_e32 v51, v109, v203
	v_add_f32_e32 v49, v49, v51
	v_mul_f32_e32 v51, v97, v205
	v_fmac_f32_e32 v51, v96, v204
	v_fmac_f32_e32 v51, v103, v206
	v_fmac_f32_e32 v51, v102, v207
	ds_read_b128 v[192:195], v37 offset:896
	ds_read_b128 v[196:199], v37 offset:912
	ds_read_b128 v[200:203], v37 offset:928
	ds_read_b128 v[204:207], v37 offset:944
	v_add_f32_e32 v49, v49, v51
	v_min_f32_e32 v50, 0, v49
	v_mul_f32_e64 v49, |v49|, s90
	v_exp_f32_e32 v49, v49
	s_nop 0
	v_add_f32_e32 v49, 1.0, v49
	v_cmp_gt_f32_e32 vcc, s74, v49
	s_nop 1
	v_cndmask_b32_e64 v51, 0, 32, vcc
	v_ldexp_f32 v49, v49, v51
	v_log_f32_e32 v49, v49
	s_nop 0
	v_mul_f32_e32 v51, 0x3f317217, v49
	v_fma_f32 v51, v49, s75, -v51
	v_fmac_f32_e32 v51, 0x3377d1cf, v49
	v_fmac_f32_e32 v51, 0x3f317217, v49
	v_cmp_lt_f32_e64 s[0:1], |v49|, s63
	s_nop 1
	v_cndmask_b32_e64 v49, v49, v51, s[0:1]
	v_cndmask_b32_e32 v51, 0, v240, vcc
	v_sub_f32_e32 v49, v49, v51
	v_sub_f32_e32 v49, v50, v49
	v_fmamk_f32 v49, v49, 0x3d800000, v48
	s_waitcnt lgkmcnt(4)
	v_mul_f32_e32 v51, v107, v209
	v_fmac_f32_e32 v51, v106, v208
	v_fmac_f32_e32 v51, v110, v210
	v_fmac_f32_e32 v51, v111, v211
	v_add_f32_e32 v113, v112, v51
	v_mul_f32_e32 v51, v99, v213
	v_fmac_f32_e32 v51, v98, v212
	v_fmac_f32_e32 v51, v104, v214
	v_fmac_f32_e32 v51, v105, v215
	v_add_f32_e32 v113, v113, v51
	v_mul_f32_e32 v51, v101, v217
	v_fmac_f32_e32 v51, v100, v216
	v_fmac_f32_e32 v51, v108, v218
	v_fmac_f32_e32 v51, v109, v219
	v_add_f32_e32 v113, v113, v51
	v_mul_f32_e32 v51, v97, v221
	v_fmac_f32_e32 v51, v96, v220
	v_fmac_f32_e32 v51, v103, v222
	v_fmac_f32_e32 v51, v102, v223
	ds_read_b128 v[208:211], v37 offset:960
	ds_read_b128 v[212:215], v37 offset:976
	ds_read_b128 v[216:219], v37 offset:992
	ds_read_b128 v[220:223], v37 offset:1008
	v_add_f32_e32 v50, v113, v51
	v_min_f32_e32 v51, 0, v50
	v_mul_f32_e64 v50, |v50|, s90
	v_exp_f32_e32 v50, v50
	s_nop 0
	v_add_f32_e32 v50, 1.0, v50
	v_cmp_gt_f32_e32 vcc, s74, v50
	s_nop 1
	v_cndmask_b32_e64 v52, 0, 32, vcc
	v_ldexp_f32 v50, v50, v52
	v_log_f32_e32 v50, v50
	s_nop 0
	v_mul_f32_e32 v52, 0x3f317217, v50
	v_fma_f32 v52, v50, s75, -v52
	v_fmac_f32_e32 v52, 0x3377d1cf, v50
	v_fmac_f32_e32 v52, 0x3f317217, v50
	v_cmp_lt_f32_e64 s[0:1], |v50|, s63
	s_nop 1
	v_cndmask_b32_e64 v50, v50, v52, s[0:1]
	v_cndmask_b32_e32 v52, 0, v240, vcc
	v_sub_f32_e32 v50, v50, v52
	v_sub_f32_e32 v50, v51, v50
	s_waitcnt lgkmcnt(4)
	v_mul_f32_e32 v51, v107, v193
	v_fmac_f32_e32 v51, v106, v192
	v_fmac_f32_e32 v51, v110, v194
	v_fmac_f32_e32 v51, v111, v195
	v_add_f32_e32 v51, v112, v51
	v_fmamk_f32 v50, v50, 0x3d800000, v49
	v_mul_f32_e32 v52, v99, v197
	v_fmac_f32_e32 v52, v98, v196
	v_fmac_f32_e32 v52, v104, v198
	v_fmac_f32_e32 v52, v105, v199
	v_add_f32_e32 v51, v51, v52
	v_mul_f32_e32 v52, v101, v201
	v_fmac_f32_e32 v52, v100, v200
	v_fmac_f32_e32 v52, v108, v202
	v_fmac_f32_e32 v52, v109, v203
	v_add_f32_e32 v51, v51, v52
	v_mul_f32_e32 v52, v97, v205
	v_fmac_f32_e32 v52, v96, v204
	v_fmac_f32_e32 v52, v103, v206
	v_fmac_f32_e32 v52, v102, v207
	v_add_f32_e32 v51, v51, v52
	v_min_f32_e32 v52, 0, v51
	v_mul_f32_e64 v51, |v51|, s90
	v_exp_f32_e32 v51, v51
	s_nop 0
	v_add_f32_e32 v51, 1.0, v51
	v_cmp_gt_f32_e32 vcc, s74, v51
	s_nop 1
	v_cndmask_b32_e64 v53, 0, 32, vcc
	v_ldexp_f32 v51, v51, v53
	v_log_f32_e32 v51, v51
	s_nop 0
	v_mul_f32_e32 v53, 0x3f317217, v51
	v_fma_f32 v53, v51, s75, -v53
	v_fmac_f32_e32 v53, 0x3377d1cf, v51
	v_fmac_f32_e32 v53, 0x3f317217, v51
	v_cmp_lt_f32_e64 s[0:1], |v51|, s63
	s_nop 1
	v_cndmask_b32_e64 v51, v51, v53, s[0:1]
	v_cndmask_b32_e32 v53, 0, v240, vcc
	v_sub_f32_e32 v51, v51, v53
	v_sub_f32_e32 v51, v52, v51
	s_waitcnt lgkmcnt(0)
	v_mul_f32_e32 v52, v107, v209
	v_fmac_f32_e32 v52, v106, v208
	v_fmac_f32_e32 v52, v110, v210
	v_fmac_f32_e32 v52, v111, v211
	v_add_f32_e32 v52, v112, v52
	v_fmamk_f32 v51, v51, 0x3d800000, v50
	v_mul_f32_e32 v53, v99, v213
	v_fmac_f32_e32 v53, v98, v212
	v_fmac_f32_e32 v53, v104, v214
	v_fmac_f32_e32 v53, v105, v215
	v_add_f32_e32 v52, v52, v53
	v_mul_f32_e32 v53, v101, v217
	v_fmac_f32_e32 v53, v100, v216
	v_fmac_f32_e32 v53, v108, v218
	v_fmac_f32_e32 v53, v109, v219
	v_add_f32_e32 v52, v52, v53
	v_mul_f32_e32 v37, v97, v221
	v_fmac_f32_e32 v37, v96, v220
	v_fmac_f32_e32 v37, v103, v222
	v_fmac_f32_e32 v37, v102, v223
	v_add_f32_e32 v37, v52, v37
	v_min_f32_e32 v52, 0, v37
	v_mul_f32_e64 v37, |v37|, s90
	v_exp_f32_e32 v37, v37
	s_nop 0
	v_add_f32_e32 v37, 1.0, v37
	v_cmp_gt_f32_e32 vcc, s74, v37
	s_nop 1
	v_cndmask_b32_e64 v53, 0, 32, vcc
	v_ldexp_f32 v37, v37, v53
	v_log_f32_e32 v37, v37
	s_nop 0
	v_mul_f32_e32 v53, 0x3f317217, v37
	v_fma_f32 v53, v37, s75, -v53
	v_fmac_f32_e32 v53, 0x3377d1cf, v37
	v_fmac_f32_e32 v53, 0x3f317217, v37
	v_cmp_lt_f32_e64 s[0:1], |v37|, s63
	s_nop 1
	v_cndmask_b32_e64 v37, v37, v53, s[0:1]
	v_cndmask_b32_e32 v53, 0, v240, vcc
	v_sub_f32_e32 v37, v37, v53
	v_sub_f32_e32 v37, v52, v37
	v_readlane_b32 s0, v255, 19
	v_fmamk_f32 v96, v37, 0x3d800000, v51
	v_cmp_lt_i32_e32 vcc, 0, v77
	v_lshl_add_u32 v37, v59, 2, s0
	ds_write_b32 v37, v96
	v_lshl_add_u32 v37, v83, 2, s0
	s_waitcnt lgkmcnt(0)
	s_barrier
; #define LAS __attribute__((address_space(3)))
; __device__ __forceinline__ unsigned f2bf(float f) { return pk2(f, 0.f) & 0xffffu; }
; __device__ __forceinline__ float bf2f(bf16 v) { return __uint_as_float(((unsigned)v) << 16); }
; __device__ __forceinline__ void gla_decay(LAS float* gd, LAS float* tot, int tid, const float (&w)[16], float bias, float (&bv)[16], float& blast) {
;     ...
;     tot[rg * 128 + d] = run;
;     __syncthreads();
;     const float t0 = tot[d], t1 = tot[128 + d], t2 = tot[256 + d], t3 = tot[384 + d];
;     const float off = (rg > 0 ? t0 : 0.f) + (rg > 1 ? t1 : 0.f) + (rg > 2 ? t2 : 0.f);
;     blast = (t0 + t1) + (t2 + t3);
; #pragma unroll
;     for (int c = 0; c < 16; ++c) bv[c] += off;
; __device__ __forceinline__ void gla_step3(const Params& P, int l, LAS unsigned char* lds, int item, int tid) {
;     ...
; #pragma unroll
;     for (int c = 0; c < 16; ++c) { const int row = rg * 16 + c;
;         const float q = bf2f(qraw[c]) * 0.08838834764831845f * __expf(bv[c]), k = bf2f(kraw[c]) * __expf(-bv[c]);
;         *(LAS bf16*)(QT + row * 272 + d * 2) = (bf16)f2bf(q); *(LAS bf16*)(KT + row * 272 + d * 2) = (bf16)f2bf(k); }
	ds_read2st64_b32 v[52:53], v37 offset1:2
	ds_read_b32 v37, v37 offset:1024
	s_waitcnt lgkmcnt(1)
	v_cndmask_b32_e32 v52, 0, v52, vcc
	v_cmp_lt_i32_e32 vcc, 1, v77
	s_nop 1
	v_cndmask_b32_e32 v53, 0, v53, vcc
	v_cmp_lt_i32_e32 vcc, 2, v77
	v_add_f32_e32 v52, v52, v53
	s_waitcnt lgkmcnt(0)
	v_cndmask_b32_e32 v37, 0, v37, vcc
	v_add_f32_e32 v52, v52, v37
	v_add_f32_e32 v53, v36, v52
	v_add_f32_e32 v38, v38, v52
	v_add_f32_e32 v39, v39, v52
	v_add_f32_e32 v40, v40, v52
	v_add_f32_e32 v41, v41, v52
	v_add_f32_e32 v42, v42, v52
	v_add_f32_e32 v43, v43, v52
	v_add_f32_e32 v44, v44, v52
	v_add_f32_e32 v45, v45, v52
	v_add_f32_e32 v46, v46, v52
	v_add_f32_e32 v47, v47, v52
	v_add_f32_e32 v48, v48, v52
	v_add_f32_e32 v49, v49, v52
	v_add_f32_e32 v50, v50, v52
	v_add_f32_e32 v37, v52, v51
	v_add_f32_e32 v36, v52, v96
	v_mul_f32_e32 v52, 0x3fb8aa3b, v53
	v_exp_f32_e32 v52, v52
	v_mul_f32_e32 v53, 0xbfb8aa3b, v53
	v_lshlrev_b32_e32 v51, 16, v95
	v_exp_f32_e32 v53, v53
	v_mul_f32_e32 v51, 0x3db504f3, v51
	v_mul_f32_e32 v51, v51, v52
	v_lshlrev_b32_e32 v52, 16, v94
	v_cvt_pk_bf16_f32 v51, v51, s0
	s_movk_i32 s0, 0x1100
	v_mul_f32_e32 v52, v53, v52
	v_mul_lo_u32 v53, v77, s0
	v_add3_u32 v0, 0, v0, v53
	ds_write_b16 v0, v51
	v_cvt_pk_bf16_f32 v51, v52, s0
	v_mul_f32_e32 v52, 0x3fb8aa3b, v38
	v_exp_f32_e32 v52, v52
	ds_write_b16 v0, v51 offset:17408
	v_lshlrev_b32_e32 v51, 16, v93
	v_mul_f32_e32 v38, 0xbfb8aa3b, v38
	v_mul_f32_e32 v51, 0x3db504f3, v51
	v_exp_f32_e32 v38, v38
	v_mul_f32_e32 v51, v51, v52
	v_cvt_pk_bf16_f32 v51, v51, s0
	v_lshlrev_b32_e32 v52, 16, v92
	ds_write_b16 v0, v51 offset:272
	v_mul_f32_e32 v51, 0x3fb8aa3b, v39
	v_mul_f32_e32 v38, v38, v52
	v_exp_f32_e32 v51, v51
	v_mul_f32_e32 v39, 0xbfb8aa3b, v39
	v_cvt_pk_bf16_f32 v38, v38, s0
	v_exp_f32_e32 v39, v39
	ds_write_b16 v0, v38 offset:17680
	v_lshlrev_b32_e32 v38, 16, v91
	v_mul_f32_e32 v38, 0x3db504f3, v38
	v_mul_f32_e32 v38, v38, v51
	v_lshlrev_b32_e32 v51, 16, v90
	v_mul_f32_e32 v39, v39, v51
	v_cvt_pk_bf16_f32 v38, v38, s0
	ds_write_b16 v0, v38 offset:544
	v_cvt_pk_bf16_f32 v38, v39, s0
	v_mul_f32_e32 v39, 0x3fb8aa3b, v40
	v_exp_f32_e32 v39, v39
	v_mul_f32_e32 v40, 0xbfb8aa3b, v40
	v_exp_f32_e32 v40, v40
	ds_write_b16 v0, v38 offset:17952
	v_lshlrev_b32_e32 v38, 16, v89
	v_mul_f32_e32 v38, 0x3db504f3, v38
	v_mul_f32_e32 v38, v38, v39
	v_lshlrev_b32_e32 v39, 16, v88
	v_mul_f32_e32 v39, v40, v39
	v_cvt_pk_bf16_f32 v38, v38, s0
	ds_write_b16 v0, v38 offset:816
	v_cvt_pk_bf16_f32 v38, v39, s0
	v_mul_f32_e32 v39, 0x3fb8aa3b, v41
	v_exp_f32_e32 v39, v39
	v_mul_f32_e32 v40, 0xbfb8aa3b, v41
	v_exp_f32_e32 v40, v40
	ds_write_b16 v0, v38 offset:18224
	v_lshlrev_b32_e32 v38, 16, v87
	v_mul_f32_e32 v38, 0x3db504f3, v38
	v_mul_f32_e32 v38, v38, v39
	v_lshlrev_b32_e32 v39, 16, v86
	v_mul_f32_e32 v39, v40, v39
	v_cvt_pk_bf16_f32 v38, v38, s0
	ds_write_b16 v0, v38 offset:1088
	v_cvt_pk_bf16_f32 v38, v39, s0
	v_mul_f32_e32 v39, 0x3fb8aa3b, v42
	v_exp_f32_e32 v39, v39
	v_mul_f32_e32 v40, 0xbfb8aa3b, v42
	v_exp_f32_e32 v40, v40
	ds_write_b16 v0, v38 offset:18496
	v_lshlrev_b32_e32 v38, 16, v85
	v_mul_f32_e32 v38, 0x3db504f3, v38
	v_mul_f32_e32 v38, v38, v39
	v_lshlrev_b32_e32 v39, 16, v84
	v_mul_f32_e32 v39, v40, v39
	v_cvt_pk_bf16_f32 v38, v38, s0
	ds_write_b16 v0, v38 offset:1360
	v_cvt_pk_bf16_f32 v38, v39, s0
	v_mul_f32_e32 v39, 0x3fb8aa3b, v43
	v_exp_f32_e32 v39, v39
	v_mul_f32_e32 v40, 0xbfb8aa3b, v43
	v_exp_f32_e32 v40, v40
	ds_write_b16 v0, v38 offset:18768
	v_lshlrev_b32_e32 v38, 16, v82
	v_mul_f32_e32 v38, 0x3db504f3, v38
	v_mul_f32_e32 v38, v38, v39
	v_lshlrev_b32_e32 v39, 16, v81
	v_mul_f32_e32 v39, v40, v39
	v_cvt_pk_bf16_f32 v38, v38, s0
	ds_write_b16 v0, v38 offset:1632
	v_cvt_pk_bf16_f32 v38, v39, s0
	v_mul_f32_e32 v39, 0x3fb8aa3b, v44
	v_exp_f32_e32 v39, v39
	v_mul_f32_e32 v40, 0xbfb8aa3b, v44
	v_exp_f32_e32 v40, v40
	ds_write_b16 v0, v38 offset:19040
	v_lshlrev_b32_e32 v38, 16, v80
	v_mul_f32_e32 v38, 0x3db504f3, v38
	v_mul_f32_e32 v38, v38, v39
	v_lshlrev_b32_e32 v39, 16, v79
	v_mul_f32_e32 v39, v40, v39
	v_cvt_pk_bf16_f32 v38, v38, s0
	ds_write_b16 v0, v38 offset:1904
	v_cvt_pk_bf16_f32 v38, v39, s0
	v_mul_f32_e32 v39, 0x3fb8aa3b, v45
	v_exp_f32_e32 v39, v39
	v_mul_f32_e32 v40, 0xbfb8aa3b, v45
	v_exp_f32_e32 v40, v40
	ds_write_b16 v0, v38 offset:19312
	v_lshlrev_b32_e32 v38, 16, v78
	v_mul_f32_e32 v38, 0x3db504f3, v38
	v_mul_f32_e32 v38, v38, v39
	v_lshlrev_b32_e32 v39, 16, v76
	v_mul_f32_e32 v39, v40, v39
	v_cvt_pk_bf16_f32 v38, v38, s0
	ds_write_b16 v0, v38 offset:2176
	v_cvt_pk_bf16_f32 v38, v39, s0
	v_mul_f32_e32 v39, 0x3fb8aa3b, v46
	v_exp_f32_e32 v39, v39
	v_mul_f32_e32 v40, 0xbfb8aa3b, v46
	v_exp_f32_e32 v40, v40
	ds_write_b16 v0, v38 offset:19584
	v_lshlrev_b32_e32 v38, 16, v75
	v_mul_f32_e32 v38, 0x3db504f3, v38
	v_mul_f32_e32 v38, v38, v39
	v_lshlrev_b32_e32 v39, 16, v74
	v_mul_f32_e32 v39, v40, v39
	v_cvt_pk_bf16_f32 v38, v38, s0
	ds_write_b16 v0, v38 offset:2448
	v_cvt_pk_bf16_f32 v38, v39, s0
	v_mul_f32_e32 v39, 0x3fb8aa3b, v47
	v_exp_f32_e32 v39, v39
	v_mul_f32_e32 v40, 0xbfb8aa3b, v47
	v_exp_f32_e32 v40, v40
	ds_write_b16 v0, v38 offset:19856
	v_lshlrev_b32_e32 v38, 16, v73
	v_mul_f32_e32 v38, 0x3db504f3, v38
	v_mul_f32_e32 v38, v38, v39
	v_lshlrev_b32_e32 v39, 16, v72
	v_mul_f32_e32 v39, v40, v39
	v_cvt_pk_bf16_f32 v38, v38, s0
	ds_write_b16 v0, v38 offset:2720
	v_cvt_pk_bf16_f32 v38, v39, s0
	v_mul_f32_e32 v39, 0x3fb8aa3b, v48
	v_exp_f32_e32 v39, v39
	v_mul_f32_e32 v40, 0xbfb8aa3b, v48
	v_exp_f32_e32 v40, v40
	ds_write_b16 v0, v38 offset:20128
	v_lshlrev_b32_e32 v38, 16, v71
	v_mul_f32_e32 v38, 0x3db504f3, v38
	v_mul_f32_e32 v38, v38, v39
	v_lshlrev_b32_e32 v39, 16, v70
; #define LAS __attribute__((address_space(3)))
; __device__ __forceinline__ unsigned pk2(float lo, float hi) { const f32x2c_t v = {lo, hi}; return __builtin_bit_cast(unsigned, __builtin_convertvector(v, bf16x2c_t)); }
; __device__ __forceinline__ unsigned f2bf(float f) { return pk2(f, 0.f) & 0xffffu; }
; __device__ __forceinline__ float bf2f(bf16 v) { return __uint_as_float(((unsigned)v) << 16); }
; #define MFMA16(a, b, c) __builtin_amdgcn_mfma_f32_16x16x32_bf16((a), (b), (c), 0, 0, 0)
; __device__ __forceinline__ void gla_step3(const Params& P, int l, LAS unsigned char* lds, int item, int tid) {
;     ...
;     for (int c = 0; c < 16; ++c) { const int row = rg * 16 + c;
;         const float q = bf2f(qraw[c]) * 0.08838834764831845f * __expf(bv[c]), k = bf2f(kraw[c]) * __expf(-bv[c]);
;         *(LAS bf16*)(QT + row * 272 + d * 2) = (bf16)f2bf(q); *(LAS bf16*)(KT + row * 272 + d * 2) = (bf16)f2bf(k); }
;     __syncthreads();
;     { const int cpt = w & 3;
; #pragma unroll
;       for (int hf = 0; hf < 2; ++hf) { const int ct = 2 * (w >> 2) + hf; f32x4 a4 = (f32x4){0.f, 0.f, 0.f, 0.f};
; #pragma unroll
;           for (int ks = 0; ks < 4; ++ks) { const bf16x8 ka = *(const LAS bf16x8*)(KT + (cpt * 16 + i) * 272 + (ks * 32 + quad * 8) * 2), qb = *(const LAS bf16x8*)(QT + (ct * 16 + i) * 272 + (ks * 32 + quad * 8) * 2);
;               a4 = MFMA16(ka, qb, a4); }
;           const int cq = ct * 16 + i, ck = cpt * 16 + quad * 4;
;           v2u o; o.x = pk2(ck <= cq ? a4[0] : 0.f, ck + 1 <= cq ? a4[1] : 0.f); o.y = pk2(ck + 2 <= cq ? a4[2] : 0.f, ck + 3 <= cq ? a4[3] : 0.f);
;           *(LAS v2u*)(PL + cq * 144 + ck * 2) = o; } }
;     __syncthreads();
	v_mul_f32_e32 v39, v40, v39
	v_cvt_pk_bf16_f32 v38, v38, s0
	ds_write_b16 v0, v38 offset:2992
	v_cvt_pk_bf16_f32 v38, v39, s0
	v_mul_f32_e32 v39, 0x3fb8aa3b, v49
	v_exp_f32_e32 v39, v39
	v_mul_f32_e32 v40, 0xbfb8aa3b, v49
	v_exp_f32_e32 v40, v40
	ds_write_b16 v0, v38 offset:20400
	v_lshlrev_b32_e32 v38, 16, v69
	v_mul_f32_e32 v38, 0x3db504f3, v38
	v_mul_f32_e32 v38, v38, v39
	v_lshlrev_b32_e32 v39, 16, v68
	v_mul_f32_e32 v39, v40, v39
	v_cvt_pk_bf16_f32 v38, v38, s0
	ds_write_b16 v0, v38 offset:3264
	v_cvt_pk_bf16_f32 v38, v39, s0
	v_mul_f32_e32 v39, 0x3fb8aa3b, v50
	v_exp_f32_e32 v39, v39
	v_mul_f32_e32 v40, 0xbfb8aa3b, v50
	v_exp_f32_e32 v40, v40
	ds_write_b16 v0, v38 offset:20672
	v_lshlrev_b32_e32 v38, 16, v67
	v_mul_f32_e32 v38, 0x3db504f3, v38
	v_mul_f32_e32 v38, v38, v39
	v_lshlrev_b32_e32 v39, 16, v66
	v_mul_f32_e32 v39, v40, v39
	v_cvt_pk_bf16_f32 v38, v38, s0
	ds_write_b16 v0, v38 offset:3536
	v_cvt_pk_bf16_f32 v38, v39, s0
	v_mul_f32_e32 v39, 0x3fb8aa3b, v37
	v_exp_f32_e32 v39, v39
	ds_write_b16 v0, v38 offset:20944
	v_lshlrev_b32_e32 v38, 16, v65
	v_mul_f32_e32 v37, 0xbfb8aa3b, v37
	v_mul_f32_e32 v38, 0x3db504f3, v38
	v_exp_f32_e32 v37, v37
	v_mul_f32_e32 v38, v38, v39
	v_cvt_pk_bf16_f32 v38, v38, s0
	v_lshlrev_b32_e32 v39, 16, v64
	ds_write_b16 v0, v38 offset:3808
	v_mul_f32_e32 v38, 0x3fb8aa3b, v36
	v_mul_f32_e32 v37, v37, v39
	v_exp_f32_e32 v38, v38
	v_mul_f32_e32 v36, 0xbfb8aa3b, v36
	v_cvt_pk_bf16_f32 v37, v37, s0
	v_exp_f32_e32 v36, v36
	ds_write_b16 v0, v37 offset:21216
	v_lshlrev_b32_e32 v37, 16, v63
	v_mul_f32_e32 v37, 0x3db504f3, v37
	v_mul_f32_e32 v37, v37, v38
	v_lshlrev_b32_e32 v38, 16, v62
	v_mul_f32_e32 v36, v36, v38
	v_cvt_pk_bf16_f32 v37, v37, s0
	v_cvt_pk_bf16_f32 v36, v36, s0
	ds_write_b16 v0, v37 offset:4080
	ds_write_b16 v0, v36 offset:21488
	v_lshlrev_b32_e32 v0, 4, v58
	v_and_b32_e32 v0, 48, v0
	v_lshlrev_b32_e32 v41, 4, v35
	v_or_b32_e32 v36, v0, v61
	v_add_u32_e32 v40, 0, v41
	v_mad_u32_u24 v62, v36, s16, v40
	s_waitcnt lgkmcnt(0)
	s_barrier
	ds_read_b128 v[36:39], v62 offset:17408
	s_movk_i32 s0, 0xffe0
	v_and_or_b32 v63, v60, s0, v61
	v_mad_u64_u32 v[50:51], s[0:1], v63, s16, v[40:41]
	ds_read_b128 v[42:45], v50
	s_waitcnt lgkmcnt(0)
	v_mfma_f32_16x16x32_bf16 v[36:39], v[36:39], v[42:45], 0
	ds_read_b128 v[42:45], v62 offset:17472
	ds_read_b128 v[46:49], v50 offset:64
	v_lshlrev_b32_e32 v35, 2, v35
	v_or_b32_e32 v52, v0, v35
	s_waitcnt lgkmcnt(0)
	v_mfma_f32_16x16x32_bf16 v[36:39], v[42:45], v[46:49], v[36:39]
	ds_read_b128 v[42:45], v62 offset:17536
	ds_read_b128 v[46:49], v50 offset:128
	v_cmp_le_i32_e32 vcc, v52, v63
	v_or_b32_e32 v53, 2, v52
	s_waitcnt lgkmcnt(0)
	v_mfma_f32_16x16x32_bf16 v[36:39], v[42:45], v[46:49], v[36:39]
	ds_read_b128 v[42:45], v62 offset:17600
	ds_read_b128 v[46:49], v50 offset:192
	v_or_b32_e32 v58, 3, v52
	v_lshl_add_u32 v0, v52, 1, s17
	s_waitcnt lgkmcnt(0)
	v_mfma_f32_16x16x32_bf16 v[36:39], v[42:45], v[46:49], v[36:39]
	v_or3_b32 v60, v61, v60, 16
	v_mad_u64_u32 v[50:51], s[0:1], v60, s16, v[40:41]
	s_nop 5
	v_cndmask_b32_e32 v36, 0, v36, vcc
	v_cmp_lt_i32_e32 vcc, v52, v63
	s_nop 1
	v_cndmask_b32_e32 v37, 0, v37, vcc
	v_cmp_le_i32_e32 vcc, v53, v63
	v_cvt_pk_bf16_f32 v36, v36, v37
	s_nop 0
	v_cndmask_b32_e32 v37, 0, v38, vcc
	v_cmp_le_i32_e32 vcc, v58, v63
	s_nop 1
	v_cndmask_b32_e32 v38, 0, v39, vcc
	v_cvt_pk_bf16_f32 v37, v37, v38
	v_mad_u64_u32 v[38:39], s[0:1], v63, s9, v[0:1]
	ds_write_b64 v38, v[36:37]
	ds_read_b128 v[36:39], v62 offset:17408
	ds_read_b128 v[42:45], v50
	s_waitcnt lgkmcnt(0)
	v_mfma_f32_16x16x32_bf16 v[36:39], v[36:39], v[42:45], 0
	ds_read_b128 v[42:45], v62 offset:17472
	ds_read_b128 v[46:49], v50 offset:64
	v_cmp_le_i32_e32 vcc, v52, v60
	s_waitcnt lgkmcnt(0)
	v_mfma_f32_16x16x32_bf16 v[36:39], v[42:45], v[46:49], v[36:39]
	ds_read_b128 v[42:45], v62 offset:17536
	ds_read_b128 v[46:49], v50 offset:128
	s_waitcnt lgkmcnt(0)
	v_mfma_f32_16x16x32_bf16 v[36:39], v[42:45], v[46:49], v[36:39]
	ds_read_b128 v[42:45], v62 offset:17600
	ds_read_b128 v[46:49], v50 offset:192
	s_waitcnt lgkmcnt(0)
	v_mfma_f32_16x16x32_bf16 v[36:39], v[42:45], v[46:49], v[36:39]
	s_nop 7
	v_cndmask_b32_e32 v36, 0, v36, vcc
	v_cmp_lt_i32_e32 vcc, v52, v60
	s_nop 1
	v_cndmask_b32_e32 v37, 0, v37, vcc
	v_cmp_le_i32_e32 vcc, v53, v60
	v_cvt_pk_bf16_f32 v36, v36, v37
	s_nop 0
	v_cndmask_b32_e32 v37, 0, v38, vcc
	v_cmp_le_i32_e32 vcc, v58, v60
	s_nop 1
	v_cndmask_b32_e32 v38, 0, v39, vcc
	v_cvt_pk_bf16_f32 v37, v37, v38
	v_mad_u64_u32 v[38:39], s[0:1], v60, s9, v[0:1]
	v_mad_u32_u24 v0, v61, s16, v40
	ds_write_b64 v38, v[36:37]
	s_waitcnt lgkmcnt(0)
	s_barrier
; #define LAS __attribute__((address_space(3)))
; #define MFMA16(a, b, c) __builtin_amdgcn_mfma_f32_16x16x32_bf16((a), (b), (c), 0, 0, 0)
; __device__ __forceinline__ s16x4 trread(const LAS unsigned char* p) { return __builtin_bit_cast(s16x4, __builtin_amdgcn_ds_read_tr16_b64_v4i16((LAS s16x4*)p)); }
; __device__ __forceinline__ bf16x8 cat8(s16x4 lo, s16x4 hi) { return (bf16x8){lo[0], lo[1], lo[2], lo[3], hi[0], hi[1], hi[2], hi[3]}; }
; __device__ __forceinline__ void gla_step3(const Params& P, int l, LAS unsigned char* lds, int item, int tid) {
;     ...
;     f32x4 acc[4][2];
; #pragma unroll
;     for (int ct = 0; ct < 4; ++ct) { acc[ct][0] = (f32x4){0.f, 0.f, 0.f, 0.f}; acc[ct][1] = (f32x4){0.f, 0.f, 0.f, 0.f}; }
; #pragma unroll
;     for (int ks = 0; ks < 4; ++ks) { const bf16x8 s0 = sfr[0][ks], s1 = sfr[1][ks];
; #pragma unroll
;         for (int ct = 0; ct < 4; ++ct) { const bf16x8 qa = *(const LAS bf16x8*)(QT + (ct * 16 + i) * 272 + (ks * 32 + quad * 8) * 2); acc[ct][0] = MFMA16(qa, s0, acc[ct][0]); acc[ct][1] = MFMA16(qa, s1, acc[ct][1]); } }
; #pragma unroll
;     for (int ks = 0; ks < 2; ++ks) { const LAS unsigned char* p0 = VT + (ks * 32 + quad * 8 + (i >> 2)) * 544 + (e0 + 4 * (i & 3)) * 2;
;         const bf16x8 v0 = cat8(trread(p0), trread(p0 + 4 * 544)), v1 = cat8(trread(p0 + 32), trread(p0 + 32 + 4 * 544));
; #pragma unroll
;         for (int ct = 0; ct < 4; ++ct) { const bf16x8 pa = *(const LAS bf16x8*)(PL + (ct * 16 + i) * 144 + (ks * 32 + quad * 8) * 2); acc[ct][0] = MFMA16(pa, v0, acc[ct][0]); acc[ct][1] = MFMA16(pa, v1, acc[ct][1]); } }
	ds_read_b128 v[36:39], v0
	ds_read_b128 v[46:49], v0 offset:4352
	ds_read_b128 v[62:65], v0 offset:8704
	ds_read_b128 v[70:73], v0 offset:13056
	s_waitcnt lgkmcnt(3)
	v_mfma_f32_16x16x32_bf16 v[42:45], v[36:39], v[26:29], 0
	v_mfma_f32_16x16x32_bf16 v[36:39], v[36:39], v[30:33], 0
	s_waitcnt lgkmcnt(2)
	v_mfma_f32_16x16x32_bf16 v[50:53], v[46:49], v[26:29], 0
	v_mfma_f32_16x16x32_bf16 v[46:49], v[46:49], v[30:33], 0
	s_waitcnt lgkmcnt(1)
	v_mfma_f32_16x16x32_bf16 v[66:69], v[62:65], v[26:29], 0
	v_mfma_f32_16x16x32_bf16 v[62:65], v[62:65], v[30:33], 0
	s_waitcnt lgkmcnt(0)
	v_mfma_f32_16x16x32_bf16 v[26:29], v[70:73], v[26:29], 0
	v_mfma_f32_16x16x32_bf16 v[30:33], v[70:73], v[30:33], 0
	ds_read_b128 v[70:73], v0 offset:64
	s_waitcnt lgkmcnt(0)
	v_mfma_f32_16x16x32_bf16 v[42:45], v[70:73], v[14:17], v[42:45]
	v_mfma_f32_16x16x32_bf16 v[36:39], v[70:73], v[22:25], v[36:39]
	ds_read_b128 v[70:73], v0 offset:4416
	s_waitcnt lgkmcnt(0)
	v_mfma_f32_16x16x32_bf16 v[50:53], v[70:73], v[14:17], v[50:53]
	v_mfma_f32_16x16x32_bf16 v[46:49], v[70:73], v[22:25], v[46:49]
	ds_read_b128 v[70:73], v0 offset:8768
	s_waitcnt lgkmcnt(0)
	v_mfma_f32_16x16x32_bf16 v[66:69], v[70:73], v[14:17], v[66:69]
	v_mfma_f32_16x16x32_bf16 v[62:65], v[70:73], v[22:25], v[62:65]
	ds_read_b128 v[70:73], v0 offset:13120
	s_waitcnt lgkmcnt(0)
	v_mfma_f32_16x16x32_bf16 v[14:17], v[70:73], v[14:17], v[26:29]
	s_nop 2
	ds_read_b128 v[26:29], v0 offset:128
	v_mfma_f32_16x16x32_bf16 v[22:25], v[70:73], v[22:25], v[30:33]
	s_waitcnt lgkmcnt(0)
	v_mfma_f32_16x16x32_bf16 v[30:33], v[26:29], v[10:13], v[42:45]
	v_mfma_f32_16x16x32_bf16 v[26:29], v[26:29], v[18:21], v[36:39]
	s_nop 2
	ds_read_b128 v[36:39], v0 offset:4480
	s_waitcnt lgkmcnt(0)
	v_mfma_f32_16x16x32_bf16 v[42:45], v[36:39], v[10:13], v[50:53]
	v_mfma_f32_16x16x32_bf16 v[36:39], v[36:39], v[18:21], v[46:49]
	s_nop 2
	ds_read_b128 v[46:49], v0 offset:8832
	s_waitcnt lgkmcnt(0)
	v_mfma_f32_16x16x32_bf16 v[50:53], v[46:49], v[10:13], v[66:69]
	v_mfma_f32_16x16x32_bf16 v[46:49], v[46:49], v[18:21], v[62:65]
	s_nop 2
	ds_read_b128 v[62:65], v0 offset:13184
	s_waitcnt lgkmcnt(0)
	v_mfma_f32_16x16x32_bf16 v[10:13], v[62:65], v[10:13], v[14:17]
	v_mfma_f32_16x16x32_bf16 v[14:17], v[62:65], v[18:21], v[22:25]
	ds_read_b128 v[18:21], v0 offset:192
	s_waitcnt lgkmcnt(0)
	v_mfma_f32_16x16x32_bf16 v[22:25], v[18:21], v[2:5], v[30:33]
	v_mfma_f32_16x16x32_bf16 v[18:21], v[18:21], v[6:9], v[26:29]
	s_nop 2
	ds_read_b128 v[26:29], v0 offset:4544
	s_waitcnt lgkmcnt(0)
	v_mfma_f32_16x16x32_bf16 v[30:33], v[26:29], v[2:5], v[42:45]
	v_mfma_f32_16x16x32_bf16 v[26:29], v[26:29], v[6:9], v[36:39]
	s_nop 2
	ds_read_b128 v[36:39], v0 offset:8896
	s_waitcnt lgkmcnt(0)
	v_mfma_f32_16x16x32_bf16 v[42:45], v[36:39], v[2:5], v[50:53]
	v_mfma_f32_16x16x32_bf16 v[36:39], v[36:39], v[6:9], v[46:49]
	s_nop 2
	ds_read_b128 v[46:49], v0 offset:13248
	s_waitcnt lgkmcnt(0)
	v_mfma_f32_16x16x32_bf16 v[2:5], v[46:49], v[2:5], v[10:13]
	v_lshrrev_b32_e32 v0, 2, v61
	s_nop 1
	v_or_b32_e32 v10, v55, v54
	v_lshl_add_u32 v40, v10, 1, 0
	v_or_b32_e32 v10, v34, v0
	v_add_u32_e32 v55, s17, v41
	v_mfma_f32_16x16x32_bf16 v[6:9], v[46:49], v[6:9], v[14:17]
	v_mad_u32_u24 v46, v61, s9, v55
	s_nop 1
	v_mad_u32_u24 v16, v10, s15, v40
	ds_read_b64_tr_b16 v[12:13], v16 offset:36992
	ds_read_b64_tr_b16 v[10:11], v16 offset:34816
	ds_read_b64_tr_b16 v[14:15], v16 offset:34848
	ds_read_b64_tr_b16 v[16:17], v16 offset:37024
	ds_read_b128 v[46:49], v46
	s_waitcnt lgkmcnt(0)
	v_mfma_f32_16x16x32_bf16 v[22:25], v[46:49], v[10:13], v[22:25]
	v_mfma_f32_16x16x32_bf16 v[18:21], v[46:49], v[14:17], v[18:21]
	v_mov_b32_e32 v46, 0x900
	v_mad_u32_u24 v58, v61, s9, v46
	v_add_u32_e32 v46, v55, v58
	ds_read_b128 v[46:49], v46
	s_waitcnt lgkmcnt(0)
	v_mfma_f32_16x16x32_bf16 v[50:53], v[46:49], v[10:13], v[30:33]
	v_mfma_f32_16x16x32_bf16 v[46:49], v[46:49], v[14:17], v[26:29]
	s_nop 2
	v_mov_b32_e32 v26, 0x1200
	v_mad_u32_u24 v60, v61, s9, v26
	v_add_u32_e32 v26, v55, v60
	ds_read_b128 v[26:29], v26
	s_waitcnt lgkmcnt(0)
	v_mfma_f32_16x16x32_bf16 v[42:45], v[26:29], v[10:13], v[42:45]
	v_mfma_f32_16x16x32_bf16 v[36:39], v[26:29], v[14:17], v[36:39]
	v_mov_b32_e32 v26, 0x1b00
	v_mad_u32_u24 v70, v61, s9, v26
	v_add_u32_e32 v26, v55, v70
	ds_read_b128 v[26:29], v26
	v_ashrrev_i32_e32 v55, 31, v54
	s_waitcnt lgkmcnt(0)
	v_mfma_f32_16x16x32_bf16 v[2:5], v[26:29], v[10:13], v[2:5]
	v_or_b32_e32 v10, 32, v34
	v_or_b32_e32 v0, v10, v0
	v_mad_u32_u24 v0, v0, s15, v40
	v_mfma_f32_16x16x32_bf16 v[62:65], v[26:29], v[14:17], v[6:9]
	s_nop 2
	ds_read_b64_tr_b16 v[8:9], v0 offset:36992
	ds_read_b64_tr_b16 v[6:7], v0 offset:34816
	ds_read_b64_tr_b16 v[66:67], v0 offset:34848
	ds_read_b64_tr_b16 v[68:69], v0 offset:37024
	v_lshl_add_u32 v0, v10, 1, s17
	v_mad_u32_u24 v10, v61, s9, v0
	ds_read_b128 v[10:13], v10
	s_lshl_b32 s9, s76, 1
	s_waitcnt lgkmcnt(0)
	v_mfma_f32_16x16x32_bf16 v[30:33], v[10:13], v[6:9], v[22:25]
	s_add_u32 s0, s92, s9
	s_addc_u32 s1, s93, 0
	v_mfma_f32_16x16x32_bf16 v[26:29], v[10:13], v[66:69], v[18:21]
	v_add_u32_e32 v10, v0, v58
	ds_read_b128 v[10:13], v10
	s_waitcnt lgkmcnt(0)
	v_mfma_f32_16x16x32_bf16 v[22:25], v[10:13], v[6:9], v[50:53]
	s_nop 2
	v_mov_b64_e32 v[52:53], s[0:1]
	v_mfma_f32_16x16x32_bf16 v[18:21], v[10:13], v[66:69], v[46:49]
	v_add_u32_e32 v10, v0, v60
	ds_read_b128 v[10:13], v10
	v_add_u32_e32 v0, v0, v70
	s_waitcnt lgkmcnt(0)
	v_mfma_f32_16x16x32_bf16 v[14:17], v[10:13], v[6:9], v[42:45]
	v_mfma_f32_16x16x32_bf16 v[10:13], v[10:13], v[66:69], v[36:39]
	s_nop 2
	ds_read_b128 v[36:39], v0
	s_waitcnt lgkmcnt(0)
; #define LAS __attribute__((address_space(3)))
; #define MFMA16(a, b, c) __builtin_amdgcn_mfma_f32_16x16x32_bf16((a), (b), (c), 0, 0, 0)
; __device__ __forceinline__ void gla_step3(const Params& P, int l, LAS unsigned char* lds, int item, int tid) {
;     ...
;         for (int ct = 0; ct < 4; ++ct) { const bf16x8 pa = *(const LAS bf16x8*)(PL + (ct * 16 + i) * 144 + (ks * 32 + quad * 8) * 2); acc[ct][0] = MFMA16(pa, v0, acc[ct][0]); acc[ct][1] = MFMA16(pa, v1, acc[ct][1]); } }
;     bf16 gra[4][4], grb[4][4];
; #pragma unroll
;     for (int ct = 0; ct < 4; ++ct)
; #pragma unroll
;         for (int j = 0; j < 4; ++j) { const size_t tt = (size_t)(t0 + ct * 16 + quad * 4 + j); gra[ct][j] = z[tt * ZP + ZC_GG + h * 256 + e0 + i]; grb[ct][j] = z[tt * ZP + ZC_GG + h * 256 + e0 + 16 + i]; }
	v_mfma_f32_16x16x32_bf16 v[6:9], v[36:39], v[6:9], v[2:5]
	v_lshlrev_b32_e32 v0, 1, v61
	v_mfma_f32_16x16x32_bf16 v[2:5], v[36:39], v[66:69], v[62:65]
	v_lshlrev_b64 v[66:67], 1, v[54:55]
	s_nop 1
	v_or_b32_e32 v64, s8, v35
	v_mad_i64_i32 v[36:37], s[0:1], v64, s80, v[52:53]
	v_lshl_add_u64 v[36:37], v[36:37], 0, v[66:67]
	v_lshl_add_u64 v[36:37], v[36:37], 0, v[0:1]
	v_lshl_add_u64 v[38:39], v[36:37], 0, s[96:97]
	v_add_co_u32_e32 v36, vcc, s68, v36
	v_or_b32_e32 v62, 1, v64
	s_nop 0
	v_addc_co_u32_e32 v37, vcc, 0, v37, vcc
	global_load_ushort v63, v[36:37], off
	global_load_ushort v89, v[38:39], off offset:32
	v_mad_i64_i32 v[36:37], s[0:1], v62, s80, v[52:53]
	v_lshl_add_u64 v[36:37], v[36:37], 0, v[66:67]
	v_lshl_add_u64 v[36:37], v[36:37], 0, v[0:1]
	v_lshl_add_u64 v[38:39], v[36:37], 0, s[96:97]
	v_add_co_u32_e32 v36, vcc, s68, v36
	v_or_b32_e32 v60, 2, v64
	s_nop 0
	v_addc_co_u32_e32 v37, vcc, 0, v37, vcc
	global_load_ushort v87, v[36:37], off
	global_load_ushort v88, v[38:39], off offset:32
	v_mad_i64_i32 v[36:37], s[0:1], v60, s80, v[52:53]
	v_lshl_add_u64 v[36:37], v[36:37], 0, v[66:67]
	v_lshl_add_u64 v[36:37], v[36:37], 0, v[0:1]
	v_lshl_add_u64 v[38:39], v[36:37], 0, s[96:97]
	v_add_co_u32_e32 v36, vcc, s68, v36
	v_or_b32_e32 v58, 3, v64
	s_nop 0
	v_addc_co_u32_e32 v37, vcc, 0, v37, vcc
	global_load_ushort v85, v[36:37], off
	global_load_ushort v86, v[38:39], off offset:32
	v_mad_i64_i32 v[36:37], s[0:1], v58, s80, v[52:53]
	v_lshl_add_u64 v[36:37], v[36:37], 0, v[66:67]
	v_lshl_add_u64 v[36:37], v[36:37], 0, v[0:1]
	v_lshl_add_u64 v[38:39], v[36:37], 0, s[96:97]
	v_add_co_u32_e32 v36, vcc, s68, v36
	v_or_b32_e32 v34, 16, v64
	s_nop 0
	v_addc_co_u32_e32 v37, vcc, 0, v37, vcc
	global_load_ushort v83, v[36:37], off
	global_load_ushort v84, v[38:39], off offset:32
	v_mad_i64_i32 v[36:37], s[0:1], v34, s80, v[52:53]
	v_lshl_add_u64 v[36:37], v[36:37], 0, v[66:67]
	v_lshl_add_u64 v[36:37], v[36:37], 0, v[0:1]
	v_lshl_add_u64 v[38:39], v[36:37], 0, s[96:97]
	v_add_co_u32_e32 v36, vcc, s68, v36
	v_or_b32_e32 v40, 17, v64
	s_nop 0
	v_addc_co_u32_e32 v37, vcc, 0, v37, vcc
	global_load_ushort v81, v[36:37], off
	global_load_ushort v82, v[38:39], off offset:32
	v_mad_i64_i32 v[36:37], s[0:1], v40, s80, v[52:53]
	v_lshl_add_u64 v[36:37], v[36:37], 0, v[66:67]
	v_lshl_add_u64 v[36:37], v[36:37], 0, v[0:1]
	v_lshl_add_u64 v[38:39], v[36:37], 0, s[96:97]
	v_add_co_u32_e32 v36, vcc, s68, v36
	v_or_b32_e32 v42, 18, v64
	s_nop 0
	v_addc_co_u32_e32 v37, vcc, 0, v37, vcc
	global_load_ushort v43, v[36:37], off
	global_load_ushort v45, v[38:39], off offset:32
	v_mad_i64_i32 v[36:37], s[0:1], v42, s80, v[52:53]
	v_lshl_add_u64 v[36:37], v[36:37], 0, v[66:67]
	v_lshl_add_u64 v[36:37], v[36:37], 0, v[0:1]
	v_lshl_add_u64 v[38:39], v[36:37], 0, s[96:97]
	v_add_co_u32_e32 v36, vcc, s68, v36
	v_or_b32_e32 v44, 19, v64
	s_nop 0
	v_addc_co_u32_e32 v37, vcc, 0, v37, vcc
	global_load_ushort v47, v[36:37], off
	global_load_ushort v49, v[38:39], off offset:32
	v_mad_i64_i32 v[36:37], s[0:1], v44, s80, v[52:53]
	v_lshl_add_u64 v[36:37], v[36:37], 0, v[66:67]
	v_lshl_add_u64 v[36:37], v[36:37], 0, v[0:1]
	v_lshl_add_u64 v[38:39], v[36:37], 0, s[96:97]
	v_add_co_u32_e32 v36, vcc, s68, v36
	v_or_b32_e32 v34, 32, v64
	s_nop 0
	v_addc_co_u32_e32 v37, vcc, 0, v37, vcc
	global_load_ushort v75, v[36:37], off
	global_load_ushort v76, v[38:39], off offset:32
	v_mad_i64_i32 v[36:37], s[0:1], v34, s80, v[52:53]
	v_lshl_add_u64 v[36:37], v[36:37], 0, v[66:67]
	v_lshl_add_u64 v[36:37], v[36:37], 0, v[0:1]
	v_lshl_add_u64 v[38:39], v[36:37], 0, s[96:97]
	v_add_co_u32_e32 v36, vcc, s68, v36
	v_or_b32_e32 v46, 33, v64
	s_nop 0
	v_addc_co_u32_e32 v37, vcc, 0, v37, vcc
	global_load_ushort v51, v[36:37], off
	global_load_ushort v72, v[38:39], off offset:32
	v_mad_i64_i32 v[36:37], s[0:1], v46, s80, v[52:53]
	v_lshl_add_u64 v[36:37], v[36:37], 0, v[66:67]
	v_lshl_add_u64 v[36:37], v[36:37], 0, v[0:1]
	v_lshl_add_u64 v[38:39], v[36:37], 0, s[96:97]
	v_add_co_u32_e32 v36, vcc, s68, v36
	v_or_b32_e32 v48, 34, v64
	s_nop 0
	v_addc_co_u32_e32 v37, vcc, 0, v37, vcc
	global_load_ushort v73, v[36:37], off
	global_load_ushort v74, v[38:39], off offset:32
	v_mad_i64_i32 v[36:37], s[0:1], v48, s80, v[52:53]
	v_lshl_add_u64 v[36:37], v[36:37], 0, v[66:67]
	v_lshl_add_u64 v[36:37], v[36:37], 0, v[0:1]
	v_lshl_add_u64 v[38:39], v[36:37], 0, s[96:97]
	v_add_co_u32_e32 v36, vcc, s68, v36
	v_or_b32_e32 v50, 35, v64
	s_nop 0
	v_addc_co_u32_e32 v37, vcc, 0, v37, vcc
	global_load_ushort v77, v[36:37], off
	global_load_ushort v78, v[38:39], off offset:32
	v_mad_i64_i32 v[36:37], s[0:1], v50, s80, v[52:53]
	v_lshl_add_u64 v[36:37], v[36:37], 0, v[66:67]
	v_lshl_add_u64 v[36:37], v[36:37], 0, v[0:1]
	v_lshl_add_u64 v[38:39], v[36:37], 0, s[96:97]
	v_add_co_u32_e32 v36, vcc, s68, v36
	v_or_b32_e32 v34, 48, v64
	s_nop 0
	v_addc_co_u32_e32 v37, vcc, 0, v37, vcc
	global_load_ushort v79, v[36:37], off
	global_load_ushort v80, v[38:39], off offset:32
	v_mad_i64_i32 v[36:37], s[0:1], v34, s80, v[52:53]
	v_lshl_add_u64 v[36:37], v[36:37], 0, v[66:67]
	v_or_b32_e32 v34, 49, v64
	v_lshl_add_u64 v[36:37], v[36:37], 0, v[0:1]
	v_mad_i64_i32 v[68:69], s[0:1], v34, s80, v[52:53]
	v_lshl_add_u64 v[38:39], v[36:37], 0, s[96:97]
	v_add_co_u32_e32 v36, vcc, s68, v36
	v_lshl_add_u64 v[68:69], v[68:69], 0, v[66:67]
	s_nop 0
	v_addc_co_u32_e32 v37, vcc, 0, v37, vcc
	v_lshl_add_u64 v[68:69], v[68:69], 0, v[0:1]
	v_lshl_add_u64 v[70:71], v[68:69], 0, s[96:97]
	v_add_co_u32_e32 v68, vcc, s68, v68
	global_load_ushort v37, v[36:37], off
	s_nop 0
	global_load_ushort v39, v[38:39], off offset:32
	v_addc_co_u32_e32 v69, vcc, 0, v69, vcc
; __device__ __forceinline__ float row16_sum(float v) { v = DPP_ADD(v, 0xB1); v = DPP_ADD(v, 0x4E); v = DPP_ADD(v, 0x141); v = DPP_ADD(v, 0x140); return v; }
; __device__ __forceinline__ void gla_step3(const Params& P, int l, LAS unsigned char* lds, int item, int tid) {
;     ...
;         for (int j = 0; j < 4; ++j) { const size_t tt = (size_t)(t0 + ct * 16 + quad * 4 + j); gra[ct][j] = z[tt * ZP + ZC_GG + h * 256 + e0 + i]; grb[ct][j] = z[tt * ZP + ZC_GG + h * 256 + e0 + 16 + i]; }
; #pragma unroll
;     for (int ct = 0; ct < 4; ++ct)
; #pragma unroll
;         for (int j = 0; j < 4; ++j) { float s = acc[ct][0][j] * acc[ct][0][j] + acc[ct][1][j] * acc[ct][1][j];
;             s = row16_sum(s);
;             if (i == 0) PART[w * 64 + ct * 16 + quad * 4 + j] = s; }
	v_or_b32_e32 v36, 50, v64
	global_load_ushort v68, v[68:69], off
	s_nop 0
	global_load_ushort v69, v[70:71], off offset:32
	v_mad_i64_i32 v[70:71], s[0:1], v36, s80, v[52:53]
	v_lshl_add_u64 v[70:71], v[70:71], 0, v[66:67]
	v_or_b32_e32 v38, 51, v64
	v_lshl_add_u64 v[70:71], v[70:71], 0, v[0:1]
	v_mad_i64_i32 v[52:53], s[0:1], v38, s80, v[52:53]
	v_lshl_add_u64 v[90:91], v[70:71], 0, s[96:97]
	v_add_co_u32_e32 v70, vcc, s68, v70
	v_lshl_add_u64 v[52:53], v[52:53], 0, v[66:67]
	s_nop 0
	v_addc_co_u32_e32 v71, vcc, 0, v71, vcc
	v_lshl_add_u64 v[52:53], v[52:53], 0, v[0:1]
	global_load_ushort v70, v[70:71], off
	s_nop 0
	global_load_ushort v71, v[90:91], off offset:32
	v_lshl_add_u64 v[90:91], v[52:53], 0, s[96:97]
	v_add_co_u32_e32 v52, vcc, s68, v52
	v_readlane_b32 s0, v255, 20
	s_nop 0
	v_addc_co_u32_e32 v53, vcc, 0, v53, vcc
	global_load_ushort v66, v[52:53], off
	global_load_ushort v67, v[90:91], off offset:32
	v_and_b32_e32 v52, 0x3fffffc0, v59
	v_cmp_eq_u32_e32 vcc, 0, v61
	v_lshl_add_u32 v61, v52, 2, s0
	v_mul_f32_e32 v52, v26, v26
	v_fmac_f32_e32 v52, v30, v30
	v_add_u32_e32 v41, v61, v41
	s_nop 0
	v_add_f32_dpp v52, v52, v52 quad_perm:[1,0,3,2] row_mask:0xf bank_mask:0xf bound_ctrl:1
	s_nop 1
	v_add_f32_dpp v52, v52, v52 quad_perm:[2,3,0,1] row_mask:0xf bank_mask:0xf bound_ctrl:1
	s_nop 1
	v_add_f32_dpp v52, v52, v52 row_half_mirror row_mask:0xf bank_mask:0xf bound_ctrl:1
	s_nop 1
	v_mov_b32_dpp v53, v52 row_mirror row_mask:0xf bank_mask:0xf bound_ctrl:1
	s_and_saveexec_b64 s[0:1], vcc
	v_add_f32_e32 v52, v52, v53
	ds_write_b32 v41, v52
	s_or_b64 exec, exec, s[0:1]
	v_mul_f32_e32 v52, v27, v27
	v_fmac_f32_e32 v52, v31, v31
	s_nop 1
	v_add_f32_dpp v52, v52, v52 quad_perm:[1,0,3,2] row_mask:0xf bank_mask:0xf bound_ctrl:1
	s_nop 1
	v_add_f32_dpp v52, v52, v52 quad_perm:[2,3,0,1] row_mask:0xf bank_mask:0xf bound_ctrl:1
	s_nop 1
	v_add_f32_dpp v52, v52, v52 row_half_mirror row_mask:0xf bank_mask:0xf bound_ctrl:1
	s_nop 1
	v_mov_b32_dpp v53, v52 row_mirror row_mask:0xf bank_mask:0xf bound_ctrl:1
	s_and_saveexec_b64 s[0:1], vcc
	v_add_f32_e32 v52, v52, v53
	ds_write_b32 v41, v52 offset:4
	s_or_b64 exec, exec, s[0:1]
	v_mul_f32_e32 v52, v28, v28
	v_fmac_f32_e32 v52, v32, v32
	s_nop 1
	v_add_f32_dpp v52, v52, v52 quad_perm:[1,0,3,2] row_mask:0xf bank_mask:0xf bound_ctrl:1
	s_nop 1
	v_add_f32_dpp v52, v52, v52 quad_perm:[2,3,0,1] row_mask:0xf bank_mask:0xf bound_ctrl:1
	s_nop 1
	v_add_f32_dpp v52, v52, v52 row_half_mirror row_mask:0xf bank_mask:0xf bound_ctrl:1
	s_nop 1
	v_mov_b32_dpp v53, v52 row_mirror row_mask:0xf bank_mask:0xf bound_ctrl:1
	s_and_saveexec_b64 s[0:1], vcc
	v_add_f32_e32 v52, v52, v53
	ds_write_b32 v41, v52 offset:8
	s_or_b64 exec, exec, s[0:1]
	v_mul_f32_e32 v52, v29, v29
	v_fmac_f32_e32 v52, v33, v33
	s_nop 1
	v_add_f32_dpp v52, v52, v52 quad_perm:[1,0,3,2] row_mask:0xf bank_mask:0xf bound_ctrl:1
	s_nop 1
	v_add_f32_dpp v52, v52, v52 quad_perm:[2,3,0,1] row_mask:0xf bank_mask:0xf bound_ctrl:1
	s_nop 1
	v_add_f32_dpp v52, v52, v52 row_half_mirror row_mask:0xf bank_mask:0xf bound_ctrl:1
	s_nop 1
	v_mov_b32_dpp v53, v52 row_mirror row_mask:0xf bank_mask:0xf bound_ctrl:1
	s_and_saveexec_b64 s[0:1], vcc
	v_add_f32_e32 v52, v52, v53
	ds_write_b32 v41, v52 offset:12
	s_or_b64 exec, exec, s[0:1]
	v_mul_f32_e32 v52, v18, v18
	v_fmac_f32_e32 v52, v22, v22
	s_nop 1
	v_add_f32_dpp v52, v52, v52 quad_perm:[1,0,3,2] row_mask:0xf bank_mask:0xf bound_ctrl:1
	s_nop 1
	v_add_f32_dpp v52, v52, v52 quad_perm:[2,3,0,1] row_mask:0xf bank_mask:0xf bound_ctrl:1
	s_nop 1
	v_add_f32_dpp v52, v52, v52 row_half_mirror row_mask:0xf bank_mask:0xf bound_ctrl:1
	s_nop 1
	v_mov_b32_dpp v53, v52 row_mirror row_mask:0xf bank_mask:0xf bound_ctrl:1
	s_and_saveexec_b64 s[0:1], vcc
	v_add_f32_e32 v52, v52, v53
	ds_write_b32 v41, v52 offset:64
	s_or_b64 exec, exec, s[0:1]
	v_mul_f32_e32 v52, v19, v19
	v_fmac_f32_e32 v52, v23, v23
	s_nop 1
	v_add_f32_dpp v52, v52, v52 quad_perm:[1,0,3,2] row_mask:0xf bank_mask:0xf bound_ctrl:1
	s_nop 1
	v_add_f32_dpp v52, v52, v52 quad_perm:[2,3,0,1] row_mask:0xf bank_mask:0xf bound_ctrl:1
	s_nop 1
	v_add_f32_dpp v52, v52, v52 row_half_mirror row_mask:0xf bank_mask:0xf bound_ctrl:1
	s_nop 1
	v_mov_b32_dpp v53, v52 row_mirror row_mask:0xf bank_mask:0xf bound_ctrl:1
	s_and_saveexec_b64 s[0:1], vcc
	v_add_f32_e32 v52, v52, v53
	ds_write_b32 v41, v52 offset:68
	s_or_b64 exec, exec, s[0:1]
	v_mul_f32_e32 v52, v20, v20
	v_fmac_f32_e32 v52, v24, v24
	s_nop 1
	v_add_f32_dpp v52, v52, v52 quad_perm:[1,0,3,2] row_mask:0xf bank_mask:0xf bound_ctrl:1
	s_nop 1
	v_add_f32_dpp v52, v52, v52 quad_perm:[2,3,0,1] row_mask:0xf bank_mask:0xf bound_ctrl:1
	s_nop 1
	v_add_f32_dpp v52, v52, v52 row_half_mirror row_mask:0xf bank_mask:0xf bound_ctrl:1
	s_nop 1
	v_mov_b32_dpp v53, v52 row_mirror row_mask:0xf bank_mask:0xf bound_ctrl:1
	s_and_saveexec_b64 s[0:1], vcc
	v_add_f32_e32 v52, v52, v53
	ds_write_b32 v41, v52 offset:72
	s_or_b64 exec, exec, s[0:1]
	v_mul_f32_e32 v52, v21, v21
	v_fmac_f32_e32 v52, v25, v25
	s_nop 1
	v_add_f32_dpp v52, v52, v52 quad_perm:[1,0,3,2] row_mask:0xf bank_mask:0xf bound_ctrl:1
	s_nop 1
	v_add_f32_dpp v52, v52, v52 quad_perm:[2,3,0,1] row_mask:0xf bank_mask:0xf bound_ctrl:1
	s_nop 1
	v_add_f32_dpp v52, v52, v52 row_half_mirror row_mask:0xf bank_mask:0xf bound_ctrl:1
	s_nop 1
	v_mov_b32_dpp v53, v52 row_mirror row_mask:0xf bank_mask:0xf bound_ctrl:1
	s_and_saveexec_b64 s[0:1], vcc
	v_add_f32_e32 v52, v52, v53
	ds_write_b32 v41, v52 offset:76
; __device__ __forceinline__ float row16_sum(float v) { v = DPP_ADD(v, 0xB1); v = DPP_ADD(v, 0x4E); v = DPP_ADD(v, 0x141); v = DPP_ADD(v, 0x140); return v; }
; __device__ __forceinline__ void gla_step3(const Params& P, int l, LAS unsigned char* lds, int item, int tid) {
;     ...
;         for (int j = 0; j < 4; ++j) { float s = acc[ct][0][j] * acc[ct][0][j] + acc[ct][1][j] * acc[ct][1][j];
;             s = row16_sum(s);
;             if (i == 0) PART[w * 64 + ct * 16 + quad * 4 + j] = s; }
;     __syncthreads();
;     if (tid < 64) { float s = 0.f;
; #pragma unroll
;         for (int ww = 0; ww < 8; ++ww) s += PART[ww * 64 + tid];
;         PART[512 + tid] = rsqrtf(s * (1.0f / 256.0f) + 1e-6f); }
;     __syncthreads();
	s_or_b64 exec, exec, s[0:1]
	v_mul_f32_e32 v52, v10, v10
	v_fmac_f32_e32 v52, v14, v14
	s_nop 1
	v_add_f32_dpp v52, v52, v52 quad_perm:[1,0,3,2] row_mask:0xf bank_mask:0xf bound_ctrl:1
	s_nop 1
	v_add_f32_dpp v52, v52, v52 quad_perm:[2,3,0,1] row_mask:0xf bank_mask:0xf bound_ctrl:1
	s_nop 1
	v_add_f32_dpp v52, v52, v52 row_half_mirror row_mask:0xf bank_mask:0xf bound_ctrl:1
	s_nop 1
	v_mov_b32_dpp v53, v52 row_mirror row_mask:0xf bank_mask:0xf bound_ctrl:1
	s_and_saveexec_b64 s[0:1], vcc
	v_add_f32_e32 v52, v52, v53
	ds_write_b32 v41, v52 offset:128
	s_or_b64 exec, exec, s[0:1]
	v_mul_f32_e32 v52, v11, v11
	v_fmac_f32_e32 v52, v15, v15
	s_nop 1
	v_add_f32_dpp v52, v52, v52 quad_perm:[1,0,3,2] row_mask:0xf bank_mask:0xf bound_ctrl:1
	s_nop 1
	v_add_f32_dpp v52, v52, v52 quad_perm:[2,3,0,1] row_mask:0xf bank_mask:0xf bound_ctrl:1
	s_nop 1
	v_add_f32_dpp v52, v52, v52 row_half_mirror row_mask:0xf bank_mask:0xf bound_ctrl:1
	s_nop 1
	v_mov_b32_dpp v53, v52 row_mirror row_mask:0xf bank_mask:0xf bound_ctrl:1
	s_and_saveexec_b64 s[0:1], vcc
	v_add_f32_e32 v52, v52, v53
	ds_write_b32 v41, v52 offset:132
	s_or_b64 exec, exec, s[0:1]
	v_mul_f32_e32 v52, v12, v12
	v_fmac_f32_e32 v52, v16, v16
	s_nop 1
	v_add_f32_dpp v52, v52, v52 quad_perm:[1,0,3,2] row_mask:0xf bank_mask:0xf bound_ctrl:1
	s_nop 1
	v_add_f32_dpp v52, v52, v52 quad_perm:[2,3,0,1] row_mask:0xf bank_mask:0xf bound_ctrl:1
	s_nop 1
	v_add_f32_dpp v52, v52, v52 row_half_mirror row_mask:0xf bank_mask:0xf bound_ctrl:1
	s_nop 1
	v_mov_b32_dpp v53, v52 row_mirror row_mask:0xf bank_mask:0xf bound_ctrl:1
	s_and_saveexec_b64 s[0:1], vcc
	v_add_f32_e32 v52, v52, v53
	ds_write_b32 v41, v52 offset:136
	s_or_b64 exec, exec, s[0:1]
	v_mul_f32_e32 v52, v13, v13
	v_fmac_f32_e32 v52, v17, v17
	s_nop 1
	v_add_f32_dpp v52, v52, v52 quad_perm:[1,0,3,2] row_mask:0xf bank_mask:0xf bound_ctrl:1
	s_nop 1
	v_add_f32_dpp v52, v52, v52 quad_perm:[2,3,0,1] row_mask:0xf bank_mask:0xf bound_ctrl:1
	s_nop 1
	v_add_f32_dpp v52, v52, v52 row_half_mirror row_mask:0xf bank_mask:0xf bound_ctrl:1
	s_nop 1
	v_mov_b32_dpp v53, v52 row_mirror row_mask:0xf bank_mask:0xf bound_ctrl:1
	s_and_saveexec_b64 s[0:1], vcc
	v_add_f32_e32 v52, v52, v53
	ds_write_b32 v41, v52 offset:140
	s_or_b64 exec, exec, s[0:1]
	v_mul_f32_e32 v52, v2, v2
	v_fmac_f32_e32 v52, v6, v6
	s_nop 1
	v_add_f32_dpp v52, v52, v52 quad_perm:[1,0,3,2] row_mask:0xf bank_mask:0xf bound_ctrl:1
	s_nop 1
	v_add_f32_dpp v52, v52, v52 quad_perm:[2,3,0,1] row_mask:0xf bank_mask:0xf bound_ctrl:1
	s_nop 1
	v_add_f32_dpp v52, v52, v52 row_half_mirror row_mask:0xf bank_mask:0xf bound_ctrl:1
	s_nop 1
	v_mov_b32_dpp v53, v52 row_mirror row_mask:0xf bank_mask:0xf bound_ctrl:1
	s_and_saveexec_b64 s[0:1], vcc
	v_add_f32_e32 v52, v52, v53
	ds_write_b32 v41, v52 offset:192
	s_or_b64 exec, exec, s[0:1]
	v_mul_f32_e32 v52, v3, v3
	v_fmac_f32_e32 v52, v7, v7
	s_nop 1
	v_add_f32_dpp v52, v52, v52 quad_perm:[1,0,3,2] row_mask:0xf bank_mask:0xf bound_ctrl:1
	s_nop 1
	v_add_f32_dpp v52, v52, v52 quad_perm:[2,3,0,1] row_mask:0xf bank_mask:0xf bound_ctrl:1
	s_nop 1
	v_add_f32_dpp v52, v52, v52 row_half_mirror row_mask:0xf bank_mask:0xf bound_ctrl:1
	s_nop 1
	v_mov_b32_dpp v53, v52 row_mirror row_mask:0xf bank_mask:0xf bound_ctrl:1
	s_and_saveexec_b64 s[0:1], vcc
	v_add_f32_e32 v52, v52, v53
	ds_write_b32 v41, v52 offset:196
	s_or_b64 exec, exec, s[0:1]
	v_mul_f32_e32 v52, v4, v4
	v_fmac_f32_e32 v52, v8, v8
	s_nop 1
	v_add_f32_dpp v52, v52, v52 quad_perm:[1,0,3,2] row_mask:0xf bank_mask:0xf bound_ctrl:1
	s_nop 1
	v_add_f32_dpp v52, v52, v52 quad_perm:[2,3,0,1] row_mask:0xf bank_mask:0xf bound_ctrl:1
	s_nop 1
	v_add_f32_dpp v52, v52, v52 row_half_mirror row_mask:0xf bank_mask:0xf bound_ctrl:1
	s_nop 1
	v_mov_b32_dpp v53, v52 row_mirror row_mask:0xf bank_mask:0xf bound_ctrl:1
	s_and_saveexec_b64 s[0:1], vcc
	v_add_f32_e32 v52, v52, v53
	ds_write_b32 v41, v52 offset:200
	s_or_b64 exec, exec, s[0:1]
	v_mul_f32_e32 v52, v5, v5
	v_fmac_f32_e32 v52, v9, v9
	s_nop 1
	v_add_f32_dpp v52, v52, v52 quad_perm:[1,0,3,2] row_mask:0xf bank_mask:0xf bound_ctrl:1
	s_nop 1
	v_add_f32_dpp v52, v52, v52 quad_perm:[2,3,0,1] row_mask:0xf bank_mask:0xf bound_ctrl:1
	s_nop 1
	v_add_f32_dpp v52, v52, v52 row_half_mirror row_mask:0xf bank_mask:0xf bound_ctrl:1
	s_nop 1
	v_mov_b32_dpp v53, v52 row_mirror row_mask:0xf bank_mask:0xf bound_ctrl:1
	s_and_saveexec_b64 s[0:1], vcc
	v_add_f32_e32 v52, v52, v53
	ds_write_b32 v41, v52 offset:204
	s_or_b64 exec, exec, s[0:1]
	v_cmp_gt_i32_e32 vcc, 64, v59
	s_waitcnt lgkmcnt(0)
	s_barrier
	s_and_saveexec_b64 s[0:1], vcc
	s_cbranch_execz .LBB0_633
	v_lshl_add_u32 v41, v59, 2, 0
	v_add_u32_e32 v41, 0x24400, v41
	ds_read2st64_b32 v[52:53], v41 offset1:1
	s_waitcnt lgkmcnt(0)
	v_add_f32_e32 v52, 0, v52
	v_add_f32_e32 v59, v52, v53
	ds_read2st64_b32 v[52:53], v41 offset0:2 offset1:3
	s_waitcnt lgkmcnt(0)
	v_add_f32_e32 v52, v59, v52
	v_add_f32_e32 v59, v52, v53
	ds_read2st64_b32 v[52:53], v41 offset0:4 offset1:5
	s_waitcnt lgkmcnt(0)
	v_add_f32_e32 v52, v59, v52
	v_add_f32_e32 v59, v52, v53
	ds_read2st64_b32 v[52:53], v41 offset0:6 offset1:7
	s_waitcnt lgkmcnt(0)
	v_add_f32_e32 v52, v59, v52
	v_add_f32_e32 v52, v52, v53
	v_fmamk_f32 v52, v52, 0x3b800000, v239
	v_cmp_gt_f32_e32 vcc, s74, v52
	v_mul_f32_e32 v53, 0x4b800000, v52
	s_nop 0
	v_cndmask_b32_e32 v52, v52, v53, vcc
	v_rsq_f32_e32 v52, v52
	s_nop 0
	v_mul_f32_e32 v53, 0x45800000, v52
	v_cndmask_b32_e32 v52, v52, v53, vcc
	ds_write_b32 v41, v52 offset:2048
	s_branch .LBB0_633
